# GEMM K-loops: the 112 per-segment s_setprio toggles removed; one static s_setprio 1 at kernel entry for waves 4-7 (the half that runs one phase behind in the 8-phase loop)
# speedup vs baseline: 1.0099x; 1.0078x over previous
; #define LAS3 __attribute__((address_space(3)))
; #define PG8_BAR __builtin_amdgcn_s_barrier()
; #define PG8_BAR __builtin_amdgcn_s_barrier()
; template <class Epi>
; DI void gemm_phase(char* smem, const bf16_t* A, int lda, const bf16_t* Bt, int ldb, int K, const Order& S_, const Epi& E) {
;     ...
;   if (wr == 1) PG8_BAR;
; __global__ void __launch_bounds__(NT, 2) fwd_megakernel(Params p) {
;   extern __shared__ __attribute__((aligned(16))) char smem[];
;   cg::grid_group grid = cg::this_grid();
;   volatile LAS3 unsigned* xst = (volatile LAS3 unsigned*)(LAS3 unsigned*)(smem + SMEM_BYTES - 16);
;   if (threadIdx.x == 0) { xst[0] = 0u; xst[1] = 0u; xst[2] = 0u; xst[3] = 0u; }
;   __syncthreads();
_Z14fwd_megakernel6Params:
	v_readfirstlane_b32 s100, v0
	s_nop 3
	s_bfe_u32 s100, s100, 0x10008
	s_cmp_eq_u32 s100, 0
	s_cbranch_scc1 .Lprio_skip
	s_setprio 1
.Lprio_skip:
	s_load_dwordx8 s[4:11], s[0:1], 0xc0
	s_load_dword s18, s[0:1], 0xf8
	s_load_dwordx4 s[92:95], s[0:1], 0xe0
	s_load_dwordx2 s[96:97], s[0:1], 0xf0
	s_add_u32 s24, s0, 0xf0
	s_addc_u32 s25, s1, 0
	v_and_b32_e32 v192, 0x3ff, v0
	s_waitcnt lgkmcnt(0)
	v_writelane_b32 v249, s4, 0
	s_nop 1
	v_writelane_b32 v249, s5, 1
	v_writelane_b32 v249, s6, 2
	v_writelane_b32 v249, s7, 3
	v_writelane_b32 v249, s8, 4
	v_writelane_b32 v249, s9, 5
	v_writelane_b32 v249, s10, 6
	v_writelane_b32 v249, s11, 7
	v_cmp_eq_u32_e64 s[6:7], 0, v192
	s_mov_b64 s[4:5], exec
	s_nop 0
	v_writelane_b32 v249, s6, 8
	s_nop 1
	v_writelane_b32 v249, s7, 9
	s_and_b64 s[6:7], s[4:5], s[6:7]
	s_mov_b64 exec, s[6:7]
	s_cbranch_execz .LBB0_2
	s_add_i32 s3, 0, 0x20ff0
	v_mov_b32_e32 v1, 0
	v_mov_b32_e32 v2, s3
	s_add_i32 s3, 0, 0x20ff4
	ds_write_b32 v2, v1
	v_mov_b32_e32 v2, s3
	s_add_i32 s3, 0, 0x20ff8
	ds_write_b32 v2, v1
	v_mov_b32_e32 v2, s3
	s_add_i32 s3, 0, 0x20ffc
	ds_write_b32 v2, v1
	v_mov_b32_e32 v2, s3
	ds_write_b32 v2, v1

; #define PG8_LDA(dst, b, h) do { _Pragma("unroll") for (int m = 0; m < 4; ++m) _Pragma("unroll") for (int k = 0; k < 2; ++k) dst[m][k] = *(const LAS bf16x8*)(lds + PG8_SA(b, h) + aoff + m * 2048 + k * 1024); } while (0)
; #define PG8_LDB(dst, b, h) do { _Pragma("unroll") for (int n = 0; n < 2; ++n) _Pragma("unroll") for (int k = 0; k < 2; ++k) dst[n][k] = *(const LAS bf16x8*)(lds + PG8_SB(b, h) + boff + n * 2048 + k * 1024); } while (0)
; #define PG8_MMA(ai, bj, At, Bt_) do { __builtin_amdgcn_s_setprio(1); _Pragma("unroll") for (int m = 0; m < 4; ++m) _Pragma("unroll") for (int n = 0; n < 2; ++n) _Pragma("unroll") for (int k = 0; k < 2; ++k) \
;     acc[ai][bj][m][n] = __builtin_amdgcn_mfma_f32_16x16x32_bf16(Bt_[n][k], At[m][k], acc[ai][bj][m][n], 0, 0, 0); __builtin_amdgcn_s_setprio(0); } while (0)
; #define PG8_WAIT_V(n) asm volatile("s_waitcnt vmcnt(" #n ")" ::: "memory")
; #define PG8_WAIT_L(n) asm volatile("s_waitcnt lgkmcnt(" #n ")" ::: "memory")
; #define PG8_BAR __builtin_amdgcn_s_barrier()
; #define PG8_SCHED __builtin_amdgcn_sched_barrier(0)
; #define PG8_STA(bufoff, gbase, ld2) PG8_STAGE3(bufoff, gbase, ld2, R0, R1)
; #define PG8_STB(bufoff, gbase, ld2) PG8_STAGE3(bufoff, gbase, ld2, Rb0, Rb1)
; #define PG8_LDA(dst, b, h) do { _Pragma("unroll") for (int m = 0; m < 4; ++m) _Pragma("unroll") for (int k = 0; k < 2; ++k) dst[m][k] = *(const LAS bf16x8*)(lds + PG8_SA(b, h) + aoff + m * 2048 + k * 1024); } while (0)
; #define PG8_LDB(dst, b, h) do { _Pragma("unroll") for (int n = 0; n < 2; ++n) _Pragma("unroll") for (int k = 0; k < 2; ++k) dst[n][k] = *(const LAS bf16x8*)(lds + PG8_SB(b, h) + boff + n * 2048 + k * 1024); } while (0)
; #define PG8_WAIT_V(n) asm volatile("s_waitcnt vmcnt(" #n ")" ::: "memory")
; template <class Sched, class Epi>
; DI void gemm_stream(char* smem, const Sched& S_, const Epi& E) {
;     ...
;       PG8_LDB(B0, 0, 0); PG8_SCHED; PG8_LDA(At, 0, 0); PG8_STA(PG8_SA(1, 1), a1 + hA, la2);
;       PG8_WAIT_L(8); PG8_BAR; PG8_WAIT_L(0); PG8_MMA(0, 0, At, B0); PG8_BAR; PG8_SCHED;
;       PG8_LDB(B1, 0, 1); PG8_STB(PG8_SB(0, 0), b2, xb2);
;       PG8_BAR; PG8_WAIT_L(0); PG8_MMA(0, 1, At, B1); PG8_BAR;
;       PG8_LDA(At, 0, 1); PG8_STA(PG8_SA(0, 0), a2, xa2);
;       PG8_BAR; PG8_WAIT_L(0); PG8_MMA(1, 0, At, B0); PG8_BAR; PG8_SCHED;
;       PG8_STB(PG8_SB(0, 1), b2 + xhB, xb2);
;       PG8_WAIT_V(6); PG8_BAR; PG8_MMA(1, 1, At, B1); PG8_BAR;
.LBB0_466:
	s_add_u32 s46, s44, 0xfffc0080
	s_addc_u32 s47, s45, -1
	s_add_i32 s52, 0, 0x10000
	v_add_u32_e32 v138, s52, v141
	ds_read_b128 v[144:147], v138
	ds_read_b128 v[148:151], v138 offset:1024
	ds_read_b128 v[152:155], v138 offset:2048
	ds_read_b128 v[156:159], v138 offset:3072
	s_cmp_eq_u32 s49, 12
	s_cselect_b32 s51, s37, s47
	s_cselect_b32 s50, s36, s46
	s_cselect_b32 s47, s41, s27
	s_cselect_b32 s46, s40, s1
	v_lshl_add_u64 v[138:139], s[44:45], 0, v[134:135]
	s_add_i32 m0, s5, 0xc000
	ds_read_b128 v[160:163], v143
	ds_read_b128 v[164:167], v143 offset:1024
	ds_read_b128 v[168:171], v143 offset:2048
	ds_read_b128 v[172:175], v143 offset:3072
	ds_read_b128 v[176:179], v143 offset:4096
	ds_read_b128 v[180:183], v143 offset:5120
	ds_read_b128 v[184:187], v143 offset:6144
	ds_read_b128 v[188:191], v143 offset:7168
	global_load_lds_dwordx4 v[138:139], off
	v_lshl_add_u64 v[138:139], s[44:45], 0, v[136:137]
	s_add_i32 m0, s5, 0xe000
	s_nop 0
	global_load_lds_dwordx4 v[138:139], off
	s_waitcnt lgkmcnt(8)
	s_barrier
	s_waitcnt lgkmcnt(0)
	s_waitcnt lgkmcnt(0)
	v_mfma_f32_16x16x32_bf16 v[124:127], v[144:147], v[160:163], v[124:127]
	v_mfma_f32_16x16x32_bf16 v[120:123], v[152:155], v[160:163], v[120:123]
	v_mfma_f32_16x16x32_bf16 v[116:119], v[144:147], v[168:171], v[116:119]
	v_mfma_f32_16x16x32_bf16 v[112:115], v[152:155], v[168:171], v[112:115]
	v_mfma_f32_16x16x32_bf16 v[108:111], v[144:147], v[176:179], v[108:111]
	v_mfma_f32_16x16x32_bf16 v[100:103], v[152:155], v[176:179], v[100:103]
	v_mfma_f32_16x16x32_bf16 v[92:95], v[144:147], v[184:187], v[92:95]
	v_mfma_f32_16x16x32_bf16 v[84:87], v[152:155], v[184:187], v[84:87]
	v_mfma_f32_16x16x32_bf16 v[124:127], v[148:151], v[164:167], v[124:127]
	v_mfma_f32_16x16x32_bf16 v[120:123], v[156:159], v[164:167], v[120:123]
	v_mfma_f32_16x16x32_bf16 v[116:119], v[148:151], v[172:175], v[116:119]
	v_mfma_f32_16x16x32_bf16 v[112:115], v[156:159], v[172:175], v[112:115]
	v_mfma_f32_16x16x32_bf16 v[108:111], v[148:151], v[180:183], v[108:111]
	v_mfma_f32_16x16x32_bf16 v[100:103], v[156:159], v[180:183], v[100:103]
	v_mfma_f32_16x16x32_bf16 v[92:95], v[148:151], v[188:191], v[92:95]
	v_mfma_f32_16x16x32_bf16 v[84:87], v[156:159], v[188:191], v[84:87]
	s_barrier
	s_add_i32 s56, 0, 0x14000
	v_add_u32_e32 v138, s56, v141
	s_add_i32 s52, s52, s4
	ds_read_b128 v[210:213], v138
	ds_read_b128 v[214:217], v138 offset:1024
	ds_read_b128 v[234:237], v138 offset:2048
	ds_read_b128 v[238:241], v138 offset:3072
	v_lshl_add_u64 v[138:139], s[46:47], 0, v[220:221]
	s_mov_b32 m0, s52
	v_lshl_add_u64 v[218:219], s[46:47], 0, v[128:129]
	global_load_lds_dwordx4 v[138:139], off
	s_add_i32 m0, s52, 0x2000
	s_nop 0
	global_load_lds_dwordx4 v[218:219], off
	s_barrier
	s_waitcnt lgkmcnt(0)
	s_waitcnt lgkmcnt(0)
	v_mfma_f32_16x16x32_bf16 v[104:107], v[210:213], v[160:163], v[104:107]
	v_mfma_f32_16x16x32_bf16 v[96:99], v[234:237], v[160:163], v[96:99]
	v_mfma_f32_16x16x32_bf16 v[88:91], v[210:213], v[168:171], v[88:91]
	v_mfma_f32_16x16x32_bf16 v[80:83], v[234:237], v[168:171], v[80:83]
	v_mfma_f32_16x16x32_bf16 v[76:79], v[210:213], v[176:179], v[76:79]
	v_mfma_f32_16x16x32_bf16 v[72:75], v[234:237], v[176:179], v[72:75]
	v_mfma_f32_16x16x32_bf16 v[68:71], v[210:213], v[184:187], v[68:71]
	v_mfma_f32_16x16x32_bf16 v[64:67], v[234:237], v[184:187], v[64:67]
	v_mfma_f32_16x16x32_bf16 v[104:107], v[214:217], v[164:167], v[104:107]
	v_mfma_f32_16x16x32_bf16 v[96:99], v[238:241], v[164:167], v[96:99]
	v_mfma_f32_16x16x32_bf16 v[88:91], v[214:217], v[172:175], v[88:91]
	v_mfma_f32_16x16x32_bf16 v[80:83], v[238:241], v[172:175], v[80:83]
	v_mfma_f32_16x16x32_bf16 v[76:79], v[214:217], v[180:183], v[76:79]
	v_mfma_f32_16x16x32_bf16 v[72:75], v[238:241], v[180:183], v[72:75]
	v_mfma_f32_16x16x32_bf16 v[68:71], v[214:217], v[188:191], v[68:71]
	v_mfma_f32_16x16x32_bf16 v[64:67], v[238:241], v[188:191], v[64:67]
	s_mov_b32 m0, s5
	v_lshl_add_u64 v[242:243], s[50:51], 0, v[130:131]
	s_barrier
	ds_read_b128 v[160:163], v143 offset:16384
	ds_read_b128 v[164:167], v143 offset:17408
	ds_read_b128 v[168:171], v143 offset:18432
	ds_read_b128 v[172:175], v143 offset:19456
	ds_read_b128 v[176:179], v143 offset:20480
	ds_read_b128 v[180:183], v143 offset:21504
	ds_read_b128 v[184:187], v143 offset:22528
	ds_read_b128 v[188:191], v143 offset:23552
	global_load_lds_dwordx4 v[242:243], off
	v_lshl_add_u64 v[244:245], s[50:51], 0, v[132:133]
	s_mov_b32 m0, s9
	s_nop 0
	global_load_lds_dwordx4 v[244:245], off
	s_barrier
	s_waitcnt lgkmcnt(0)
	s_waitcnt lgkmcnt(0)
	v_mfma_f32_16x16x32_bf16 v[60:63], v[144:147], v[160:163], v[60:63]
	v_mfma_f32_16x16x32_bf16 v[56:59], v[152:155], v[160:163], v[56:59]
	v_mfma_f32_16x16x32_bf16 v[52:55], v[144:147], v[168:171], v[52:55]
	v_mfma_f32_16x16x32_bf16 v[48:51], v[152:155], v[168:171], v[48:51]
	v_mfma_f32_16x16x32_bf16 v[44:47], v[144:147], v[176:179], v[44:47]
	v_mfma_f32_16x16x32_bf16 v[36:39], v[152:155], v[176:179], v[36:39]
	v_mfma_f32_16x16x32_bf16 v[28:31], v[144:147], v[184:187], v[28:31]
	v_mfma_f32_16x16x32_bf16 v[20:23], v[152:155], v[184:187], v[20:23]
	v_mfma_f32_16x16x32_bf16 v[60:63], v[148:151], v[164:167], v[60:63]
	v_mfma_f32_16x16x32_bf16 v[56:59], v[156:159], v[164:167], v[56:59]
	v_mfma_f32_16x16x32_bf16 v[52:55], v[148:151], v[172:175], v[52:55]
	v_mfma_f32_16x16x32_bf16 v[48:51], v[156:159], v[172:175], v[48:51]
	v_mfma_f32_16x16x32_bf16 v[44:47], v[148:151], v[180:183], v[44:47]
	v_mfma_f32_16x16x32_bf16 v[36:39], v[156:159], v[180:183], v[36:39]
	v_mfma_f32_16x16x32_bf16 v[28:31], v[148:151], v[188:191], v[28:31]
	v_mfma_f32_16x16x32_bf16 v[20:23], v[156:159], v[188:191], v[20:23]
	s_barrier
; #define PG8_LDA(dst, b, h) do { _Pragma("unroll") for (int m = 0; m < 4; ++m) _Pragma("unroll") for (int k = 0; k < 2; ++k) dst[m][k] = *(const LAS bf16x8*)(lds + PG8_SA(b, h) + aoff + m * 2048 + k * 1024); } while (0)
; #define PG8_LDB(dst, b, h) do { _Pragma("unroll") for (int n = 0; n < 2; ++n) _Pragma("unroll") for (int k = 0; k < 2; ++k) dst[n][k] = *(const LAS bf16x8*)(lds + PG8_SB(b, h) + boff + n * 2048 + k * 1024); } while (0)
; #define PG8_MMA(ai, bj, At, Bt_) do { __builtin_amdgcn_s_setprio(1); _Pragma("unroll") for (int m = 0; m < 4; ++m) _Pragma("unroll") for (int n = 0; n < 2; ++n) _Pragma("unroll") for (int k = 0; k < 2; ++k) \
;     acc[ai][bj][m][n] = __builtin_amdgcn_mfma_f32_16x16x32_bf16(Bt_[n][k], At[m][k], acc[ai][bj][m][n], 0, 0, 0); __builtin_amdgcn_s_setprio(0); } while (0)
; #define PG8_WAIT_V(n) asm volatile("s_waitcnt vmcnt(" #n ")" ::: "memory")
; #define PG8_WAIT_L(n) asm volatile("s_waitcnt lgkmcnt(" #n ")" ::: "memory")
; #define PG8_BAR __builtin_amdgcn_s_barrier()
; #define PG8_SCHED __builtin_amdgcn_sched_barrier(0)
; #define PG8_STA(bufoff, gbase, ld2) PG8_STAGE3(bufoff, gbase, ld2, R0, R1)
; #define PG8_STB(bufoff, gbase, ld2) PG8_STAGE3(bufoff, gbase, ld2, Rb0, Rb1)
; #define PG8_LDA(dst, b, h) do { _Pragma("unroll") for (int m = 0; m < 4; ++m) _Pragma("unroll") for (int k = 0; k < 2; ++k) dst[m][k] = *(const LAS bf16x8*)(lds + PG8_SA(b, h) + aoff + m * 2048 + k * 1024); } while (0)
; #define PG8_LDB(dst, b, h) do { _Pragma("unroll") for (int n = 0; n < 2; ++n) _Pragma("unroll") for (int k = 0; k < 2; ++k) dst[n][k] = *(const LAS bf16x8*)(lds + PG8_SB(b, h) + boff + n * 2048 + k * 1024); } while (0)
; #define PG8_WAIT_V(n) asm volatile("s_waitcnt vmcnt(" #n ")" ::: "memory")
; template <class Sched, class Epi>
; DI void gemm_stream(char* smem, const Sched& S_, const Epi& E) {
;     ...
;       PG8_STB(PG8_SB(0, 1), b2 + xhB, xb2);
;       PG8_WAIT_V(6); PG8_BAR; PG8_MMA(1, 1, At, B1); PG8_BAR;
;       PG8_LDB(B0, 1, 0); PG8_SCHED; PG8_LDA(At, 1, 0); PG8_STA(PG8_SA(0, 1), a2 + xhA, xa2);
;       PG8_WAIT_L(8); PG8_BAR; PG8_WAIT_L(0); PG8_MMA(0, 0, At, B0); PG8_BAR; PG8_SCHED;
;       PG8_LDB(B1, 1, 1); PG8_STB(PG8_SB(1, 0), b3, xb2);
;       PG8_BAR; PG8_WAIT_L(0); PG8_MMA(0, 1, At, B1); PG8_BAR;
;       PG8_LDA(At, 1, 1); PG8_STA(PG8_SA(1, 0), a3, xa2);
;       PG8_BAR; PG8_WAIT_L(0); PG8_MMA(1, 0, At, B0); PG8_BAR; PG8_SCHED;
	s_add_u32 s52, s46, 0x40000
	s_addc_u32 s53, s47, 0
	s_add_i32 s56, s56, s4
	v_lshl_add_u64 v[144:145], s[52:53], 0, v[220:221]
	s_mov_b32 m0, s56
	s_nop 0
	global_load_lds_dwordx4 v[144:145], off
	v_lshl_add_u64 v[144:145], s[52:53], 0, v[128:129]
	s_add_i32 m0, s56, 0x2000
	s_nop 0
	global_load_lds_dwordx4 v[144:145], off
	s_waitcnt vmcnt(6)
	s_barrier
	v_mfma_f32_16x16x32_bf16 v[40:43], v[210:213], v[160:163], v[40:43]
	v_mfma_f32_16x16x32_bf16 v[32:35], v[234:237], v[160:163], v[32:35]
	v_mfma_f32_16x16x32_bf16 v[24:27], v[210:213], v[168:171], v[24:27]
	v_mfma_f32_16x16x32_bf16 v[16:19], v[234:237], v[168:171], v[16:19]
	v_mfma_f32_16x16x32_bf16 v[12:15], v[210:213], v[176:179], v[12:15]
	v_mfma_f32_16x16x32_bf16 v[8:11], v[234:237], v[176:179], v[8:11]
	v_mfma_f32_16x16x32_bf16 v[4:7], v[210:213], v[184:187], v[4:7]
	v_mfma_f32_16x16x32_bf16 v[0:3], v[234:237], v[184:187], v[0:3]
	v_mfma_f32_16x16x32_bf16 v[40:43], v[214:217], v[164:167], v[40:43]
	v_mfma_f32_16x16x32_bf16 v[32:35], v[238:241], v[164:167], v[32:35]
	v_mfma_f32_16x16x32_bf16 v[24:27], v[214:217], v[172:175], v[24:27]
	v_mfma_f32_16x16x32_bf16 v[16:19], v[238:241], v[172:175], v[16:19]
	v_mfma_f32_16x16x32_bf16 v[12:15], v[214:217], v[180:183], v[12:15]
	v_mfma_f32_16x16x32_bf16 v[8:11], v[238:241], v[180:183], v[8:11]
	v_mfma_f32_16x16x32_bf16 v[4:7], v[214:217], v[188:191], v[4:7]
	v_mfma_f32_16x16x32_bf16 v[0:3], v[238:241], v[188:191], v[0:3]
	s_add_i32 s52, 0, 0x18000
	v_add_u32_e32 v156, s52, v141
	s_barrier
	ds_read_b128 v[144:147], v156
	ds_read_b128 v[148:151], v156 offset:1024
	ds_read_b128 v[152:155], v156 offset:2048
	ds_read_b128 v[156:159], v156 offset:3072
	s_add_u32 s50, s50, 0x40000
	s_addc_u32 s51, s51, 0
	s_mov_b32 m0, s13
	v_lshl_add_u64 v[210:211], s[50:51], 0, v[130:131]
	ds_read_b128 v[160:163], v143 offset:32768
	ds_read_b128 v[164:167], v143 offset:33792
	ds_read_b128 v[168:171], v143 offset:34816
	ds_read_b128 v[172:175], v143 offset:35840
	ds_read_b128 v[176:179], v143 offset:36864
	ds_read_b128 v[180:183], v143 offset:37888
	ds_read_b128 v[184:187], v143 offset:38912
	ds_read_b128 v[188:191], v143 offset:39936
	global_load_lds_dwordx4 v[210:211], off
	v_lshl_add_u64 v[210:211], s[50:51], 0, v[132:133]
	s_mov_b32 m0, s15
	s_nop 0
	global_load_lds_dwordx4 v[210:211], off
	s_waitcnt lgkmcnt(8)
	s_barrier
	s_waitcnt lgkmcnt(0)
	s_waitcnt lgkmcnt(0)
	v_mfma_f32_16x16x32_bf16 v[124:127], v[144:147], v[160:163], v[124:127]
	v_mfma_f32_16x16x32_bf16 v[120:123], v[152:155], v[160:163], v[120:123]
	v_mfma_f32_16x16x32_bf16 v[116:119], v[144:147], v[168:171], v[116:119]
	v_mfma_f32_16x16x32_bf16 v[112:115], v[152:155], v[168:171], v[112:115]
	v_mfma_f32_16x16x32_bf16 v[108:111], v[144:147], v[176:179], v[108:111]
	v_mfma_f32_16x16x32_bf16 v[100:103], v[152:155], v[176:179], v[100:103]
	v_mfma_f32_16x16x32_bf16 v[92:95], v[144:147], v[184:187], v[92:95]
	v_mfma_f32_16x16x32_bf16 v[84:87], v[152:155], v[184:187], v[84:87]
	v_mfma_f32_16x16x32_bf16 v[124:127], v[148:151], v[164:167], v[124:127]
	v_mfma_f32_16x16x32_bf16 v[120:123], v[156:159], v[164:167], v[120:123]
	v_mfma_f32_16x16x32_bf16 v[116:119], v[148:151], v[172:175], v[116:119]
	v_mfma_f32_16x16x32_bf16 v[112:115], v[156:159], v[172:175], v[112:115]
	v_mfma_f32_16x16x32_bf16 v[108:111], v[148:151], v[180:183], v[108:111]
	v_mfma_f32_16x16x32_bf16 v[100:103], v[156:159], v[180:183], v[100:103]
	v_mfma_f32_16x16x32_bf16 v[92:95], v[148:151], v[188:191], v[92:95]
	v_mfma_f32_16x16x32_bf16 v[84:87], v[156:159], v[188:191], v[84:87]
	s_barrier
	s_add_i32 s50, 0, 0x1c000
	s_add_i32 s51, s52, s4
	v_add_u32_e32 v194, s50, v141
	v_lshl_add_u64 v[138:139], v[138:139], 0, s[58:59]
	s_mov_b32 m0, s51
	ds_read_b128 v[210:213], v194
	ds_read_b128 v[214:217], v194 offset:1024
	ds_read_b128 v[234:237], v194 offset:2048
	ds_read_b128 v[238:241], v194 offset:3072
	global_load_lds_dwordx4 v[138:139], off
	v_lshl_add_u64 v[138:139], v[218:219], 0, s[58:59]
	s_add_i32 m0, s51, 0x2000
	s_nop 0
	global_load_lds_dwordx4 v[138:139], off
	s_barrier
	s_waitcnt lgkmcnt(0)
	s_waitcnt lgkmcnt(0)
	v_mfma_f32_16x16x32_bf16 v[104:107], v[210:213], v[160:163], v[104:107]
	v_mfma_f32_16x16x32_bf16 v[96:99], v[234:237], v[160:163], v[96:99]
	v_mfma_f32_16x16x32_bf16 v[88:91], v[210:213], v[168:171], v[88:91]
	v_mfma_f32_16x16x32_bf16 v[80:83], v[234:237], v[168:171], v[80:83]
	v_mfma_f32_16x16x32_bf16 v[76:79], v[210:213], v[176:179], v[76:79]
	v_mfma_f32_16x16x32_bf16 v[72:75], v[234:237], v[176:179], v[72:75]
	v_mfma_f32_16x16x32_bf16 v[68:71], v[210:213], v[184:187], v[68:71]
	v_mfma_f32_16x16x32_bf16 v[64:67], v[234:237], v[184:187], v[64:67]
	v_mfma_f32_16x16x32_bf16 v[104:107], v[214:217], v[164:167], v[104:107]
	v_mfma_f32_16x16x32_bf16 v[96:99], v[238:241], v[164:167], v[96:99]
	v_mfma_f32_16x16x32_bf16 v[88:91], v[214:217], v[172:175], v[88:91]
	v_mfma_f32_16x16x32_bf16 v[80:83], v[238:241], v[172:175], v[80:83]
	v_mfma_f32_16x16x32_bf16 v[76:79], v[214:217], v[180:183], v[76:79]
	v_mfma_f32_16x16x32_bf16 v[72:75], v[238:241], v[180:183], v[72:75]
	v_mfma_f32_16x16x32_bf16 v[68:71], v[214:217], v[188:191], v[68:71]
	v_mfma_f32_16x16x32_bf16 v[64:67], v[238:241], v[188:191], v[64:67]
	s_mov_b32 m0, s16
	v_lshl_add_u64 v[138:139], v[242:243], 0, s[58:59]
	s_barrier
	ds_read_b128 v[160:163], v143 offset:49152
	ds_read_b128 v[164:167], v143 offset:50176
	ds_read_b128 v[168:171], v143 offset:51200
	ds_read_b128 v[172:175], v143 offset:52224
	ds_read_b128 v[176:179], v143 offset:53248
	ds_read_b128 v[180:183], v143 offset:54272
	ds_read_b128 v[184:187], v143 offset:55296
	ds_read_b128 v[188:191], v143 offset:56320
	global_load_lds_dwordx4 v[138:139], off
	v_lshl_add_u64 v[138:139], v[244:245], 0, s[58:59]
	s_mov_b32 m0, s20
	s_nop 0
	global_load_lds_dwordx4 v[138:139], off
	s_barrier
; #define PG8_LDA(dst, b, h) do { _Pragma("unroll") for (int m = 0; m < 4; ++m) _Pragma("unroll") for (int k = 0; k < 2; ++k) dst[m][k] = *(const LAS bf16x8*)(lds + PG8_SA(b, h) + aoff + m * 2048 + k * 1024); } while (0)
; #define PG8_MMA(ai, bj, At, Bt_) do { __builtin_amdgcn_s_setprio(1); _Pragma("unroll") for (int m = 0; m < 4; ++m) _Pragma("unroll") for (int n = 0; n < 2; ++n) _Pragma("unroll") for (int k = 0; k < 2; ++k) \
;     acc[ai][bj][m][n] = __builtin_amdgcn_mfma_f32_16x16x32_bf16(Bt_[n][k], At[m][k], acc[ai][bj][m][n], 0, 0, 0); __builtin_amdgcn_s_setprio(0); } while (0)
; #define PG8_WAIT_V(n) asm volatile("s_waitcnt vmcnt(" #n ")" ::: "memory")
; #define PG8_WAIT_L(n) asm volatile("s_waitcnt lgkmcnt(" #n ")" ::: "memory")
; #define PG8_BAR __builtin_amdgcn_s_barrier()
; #define PG8_SCHED __builtin_amdgcn_sched_barrier(0)
; DI u32x4 pack8v(const f32x4& a, const f32x4& b) { u32x4 w; w.x = pk2(a[0], a[1]); w.y = pk2(a[2], a[3]); w.z = pk2(b[0], b[1]); w.w = pk2(b[2], b[3]); return w; }
; #define PG8_STA(bufoff, gbase, ld2) PG8_STAGE3(bufoff, gbase, ld2, R0, R1)
; #define PG8_STB(bufoff, gbase, ld2) PG8_STAGE3(bufoff, gbase, ld2, Rb0, Rb1)
; #define PG8_WAIT_V(n) asm volatile("s_waitcnt vmcnt(" #n ")" ::: "memory")
; #define PG8_WAIT_L(n) asm volatile("s_waitcnt lgkmcnt(" #n ")" ::: "memory")
; template <class Sched, class Epi>
; DI void gemm_stream(char* smem, const Sched& S_, const Epi& E) {
;     ...
;       PG8_LDA(At, 1, 1); PG8_STA(PG8_SA(1, 0), a3, xa2);
;       PG8_BAR; PG8_WAIT_L(0); PG8_MMA(1, 0, At, B0); PG8_BAR; PG8_SCHED;
;       PG8_STB(PG8_SB(1, 1), b3 + xhB, xb2);
;       PG8_WAIT_V(6); PG8_BAR; PG8_MMA(1, 1, At, B1); PG8_BAR;
;     }
;     E(acc, cur, wr, wc, fr, fq);
;   DI void operator()(const acc_t& acc, const Desc& u, int wr, int wc, int fr, int fq) const {
;     ...
;           for (int bj = 0; bj < 2; ++bj) *(u32x4*)(rowp + bj * HALF) = pack8v(acc[ai][bj][m][0], acc[ai][bj][m][1]); }
;     } else {
;       const int t0 = u.pn * BM, b = t0 / S, s0 = t0 - b * S + wc * 32 + 8 * fq;
; #pragma unroll
;       for (int ai = 0; ai < 2; ++ai)
; #pragma unroll
;         for (int m = 0; m < 4; ++m) { bf16_t* rowp = RVT + ((size_t)b * 512 + row0 + ai * HALF + m * 16) * S + s0;
; #pragma unroll
;           for (int bj = 0; bj < 2; ++bj) *(u32x4*)(rowp + bj * HALF) = pack8v(acc[ai][bj][m][0], acc[ai][bj][m][1]); }
	s_waitcnt lgkmcnt(0)
	s_waitcnt lgkmcnt(0)
	v_mfma_f32_16x16x32_bf16 v[60:63], v[144:147], v[160:163], v[60:63]
	v_mfma_f32_16x16x32_bf16 v[56:59], v[152:155], v[160:163], v[56:59]
	v_mfma_f32_16x16x32_bf16 v[52:55], v[144:147], v[168:171], v[52:55]
	v_mfma_f32_16x16x32_bf16 v[48:51], v[152:155], v[168:171], v[48:51]
	v_mfma_f32_16x16x32_bf16 v[44:47], v[144:147], v[176:179], v[44:47]
	v_mfma_f32_16x16x32_bf16 v[36:39], v[152:155], v[176:179], v[36:39]
	v_mfma_f32_16x16x32_bf16 v[28:31], v[144:147], v[184:187], v[28:31]
	v_mfma_f32_16x16x32_bf16 v[20:23], v[152:155], v[184:187], v[20:23]
	v_mfma_f32_16x16x32_bf16 v[60:63], v[148:151], v[164:167], v[60:63]
	v_mfma_f32_16x16x32_bf16 v[56:59], v[156:159], v[164:167], v[56:59]
	v_mfma_f32_16x16x32_bf16 v[52:55], v[148:151], v[172:175], v[52:55]
	v_mfma_f32_16x16x32_bf16 v[48:51], v[156:159], v[172:175], v[48:51]
	v_mfma_f32_16x16x32_bf16 v[44:47], v[148:151], v[180:183], v[44:47]
	v_mfma_f32_16x16x32_bf16 v[36:39], v[156:159], v[180:183], v[36:39]
	v_mfma_f32_16x16x32_bf16 v[28:31], v[148:151], v[188:191], v[28:31]
	v_mfma_f32_16x16x32_bf16 v[20:23], v[156:159], v[188:191], v[20:23]
	s_barrier
	s_add_u32 s46, s46, 0x40080
	s_addc_u32 s47, s47, 0
	s_add_i32 s50, s50, s4
	v_lshl_add_u64 v[138:139], s[46:47], 0, v[220:221]
	s_mov_b32 m0, s50
	s_nop 0
	global_load_lds_dwordx4 v[138:139], off
	v_lshl_add_u64 v[138:139], s[46:47], 0, v[128:129]
	s_add_i32 m0, s50, 0x2000
	s_nop 0
	global_load_lds_dwordx4 v[138:139], off
	s_waitcnt vmcnt(6)
	s_barrier
	v_mfma_f32_16x16x32_bf16 v[40:43], v[210:213], v[160:163], v[40:43]
	v_mfma_f32_16x16x32_bf16 v[32:35], v[234:237], v[160:163], v[32:35]
	v_mfma_f32_16x16x32_bf16 v[24:27], v[210:213], v[168:171], v[24:27]
	v_mfma_f32_16x16x32_bf16 v[16:19], v[234:237], v[168:171], v[16:19]
	v_mfma_f32_16x16x32_bf16 v[12:15], v[210:213], v[176:179], v[12:15]
	v_mfma_f32_16x16x32_bf16 v[8:11], v[234:237], v[176:179], v[8:11]
	v_mfma_f32_16x16x32_bf16 v[4:7], v[210:213], v[184:187], v[4:7]
	v_mfma_f32_16x16x32_bf16 v[0:3], v[234:237], v[184:187], v[0:3]
	v_mfma_f32_16x16x32_bf16 v[40:43], v[214:217], v[164:167], v[40:43]
	v_mfma_f32_16x16x32_bf16 v[32:35], v[238:241], v[164:167], v[32:35]
	v_mfma_f32_16x16x32_bf16 v[24:27], v[214:217], v[172:175], v[24:27]
	v_mfma_f32_16x16x32_bf16 v[16:19], v[238:241], v[172:175], v[16:19]
	v_mfma_f32_16x16x32_bf16 v[12:15], v[214:217], v[180:183], v[12:15]
	v_mfma_f32_16x16x32_bf16 v[8:11], v[238:241], v[180:183], v[8:11]
	v_mfma_f32_16x16x32_bf16 v[4:7], v[214:217], v[188:191], v[4:7]
	v_mfma_f32_16x16x32_bf16 v[0:3], v[238:241], v[188:191], v[0:3]
	s_add_i32 s49, s49, 2
	s_add_u32 s44, s44, 0x100
	s_addc_u32 s45, s45, 0
	s_add_u32 s1, s1, 0x100
	s_addc_u32 s27, s27, 0
	s_cmp_gt_u32 s49, 13
	s_barrier
	s_cbranch_scc0 .LBB0_466
	s_lshl_b32 s1, s33, 8
	v_lshl_add_u32 v138, s43, 8, v140
	s_cmp_lg_u32 s42, 0
	v_cvt_pk_bf16_f32 v124, v124, v125
	v_cvt_pk_bf16_f32 v125, v126, v127
	v_cvt_pk_bf16_f32 v126, v120, v121
	v_cvt_pk_bf16_f32 v127, v122, v123
	v_cvt_pk_bf16_f32 v104, v104, v105
	v_cvt_pk_bf16_f32 v105, v106, v107
	v_cvt_pk_bf16_f32 v106, v96, v97
	v_cvt_pk_bf16_f32 v107, v98, v99
	v_cvt_pk_bf16_f32 v96, v116, v117
	v_cvt_pk_bf16_f32 v97, v118, v119
	v_cvt_pk_bf16_f32 v98, v112, v113
	v_cvt_pk_bf16_f32 v99, v114, v115
	v_cvt_pk_bf16_f32 v88, v88, v89
	v_cvt_pk_bf16_f32 v89, v90, v91
	v_cvt_pk_bf16_f32 v90, v80, v81
	v_cvt_pk_bf16_f32 v91, v82, v83
	v_cvt_pk_bf16_f32 v80, v108, v109
	v_cvt_pk_bf16_f32 v81, v110, v111
	v_cvt_pk_bf16_f32 v82, v100, v101
	v_cvt_pk_bf16_f32 v83, v102, v103
	v_cvt_pk_bf16_f32 v76, v76, v77
	v_cvt_pk_bf16_f32 v77, v78, v79
	v_cvt_pk_bf16_f32 v78, v72, v73
	v_cvt_pk_bf16_f32 v79, v74, v75
	v_cvt_pk_bf16_f32 v72, v92, v93
	v_cvt_pk_bf16_f32 v73, v94, v95
	v_cvt_pk_bf16_f32 v74, v84, v85
	v_cvt_pk_bf16_f32 v75, v86, v87
	v_cvt_pk_bf16_f32 v68, v68, v69
	v_cvt_pk_bf16_f32 v69, v70, v71
	v_cvt_pk_bf16_f32 v70, v64, v65
	v_cvt_pk_bf16_f32 v71, v66, v67
	v_cvt_pk_bf16_f32 v60, v60, v61
	v_cvt_pk_bf16_f32 v61, v62, v63
	v_cvt_pk_bf16_f32 v62, v56, v57
	v_cvt_pk_bf16_f32 v63, v58, v59
	v_cvt_pk_bf16_f32 v40, v40, v41
	v_cvt_pk_bf16_f32 v41, v42, v43
	v_cvt_pk_bf16_f32 v42, v32, v33
	v_cvt_pk_bf16_f32 v43, v34, v35
	v_cvt_pk_bf16_f32 v32, v52, v53
	v_cvt_pk_bf16_f32 v33, v54, v55
	v_cvt_pk_bf16_f32 v34, v48, v49
	v_cvt_pk_bf16_f32 v35, v50, v51
	v_cvt_pk_bf16_f32 v24, v24, v25
	v_cvt_pk_bf16_f32 v25, v26, v27
	v_cvt_pk_bf16_f32 v26, v16, v17
	v_cvt_pk_bf16_f32 v27, v18, v19
	v_cvt_pk_bf16_f32 v16, v44, v45
	v_cvt_pk_bf16_f32 v17, v46, v47
	v_cvt_pk_bf16_f32 v18, v36, v37
	v_cvt_pk_bf16_f32 v19, v38, v39
	v_cvt_pk_bf16_f32 v12, v12, v13
	v_cvt_pk_bf16_f32 v13, v14, v15
	v_cvt_pk_bf16_f32 v14, v8, v9
	v_cvt_pk_bf16_f32 v15, v10, v11
	v_cvt_pk_bf16_f32 v8, v28, v29
	v_cvt_pk_bf16_f32 v9, v30, v31
	v_cvt_pk_bf16_f32 v10, v20, v21
	v_cvt_pk_bf16_f32 v11, v22, v23
	v_readlane_b32 s49, v254, 50
	s_cbranch_scc0 .LBB0_469
; DI u32x4 pack8v(const f32x4& a, const f32x4& b) { u32x4 w; w.x = pk2(a[0], a[1]); w.y = pk2(a[2], a[3]); w.z = pk2(b[0], b[1]); w.w = pk2(b[2], b[3]); return w; }
;   DI void operator()(const acc_t& acc, const Desc& u, int wr, int wc, int fr, int fq) const {
;     ...
;       const int t0 = u.pn * BM, b = t0 / S, s0 = t0 - b * S + wc * 32 + 8 * fq;
; #pragma unroll
;       for (int ai = 0; ai < 2; ++ai)
; #pragma unroll
;         for (int m = 0; m < 4; ++m) { bf16_t* rowp = RVT + ((size_t)b * 512 + row0 + ai * HALF + m * 16) * S + s0;
; #pragma unroll
;           for (int bj = 0; bj < 2; ++bj) *(u32x4*)(rowp + bj * HALF) = pack8v(acc[ai][bj][m][0], acc[ai][bj][m][1]); }
	s_mul_hi_i32 s27, s33, 0x78787879
	s_lshr_b32 s33, s27, 31
	s_ashr_i32 s27, s27, 3
	s_add_i32 s42, s27, s33
	s_ashr_i32 s43, s42, 31
	s_mul_i32 s27, s42, 0xffffef00
	s_lshl_b64 s[42:43], s[42:43], 9
	v_ashrrev_i32_e32 v139, 31, v138
	v_lshl_add_u64 v[22:23], s[42:43], 0, v[138:139]
	v_readlane_b32 s42, v251, 41
	s_add_i32 s27, s27, s1
	v_readlane_b32 s43, v251, 42
	v_or_b32_e32 v20, s27, v142
	s_movk_i32 s27, 0x2200
	v_mov_b64_e32 v[28:29], s[42:43]
	v_mad_u64_u32 v[28:29], s[42:43], v22, s27, v[28:29]
	v_ashrrev_i32_e32 v21, 31, v20
	v_mad_i32_i24 v29, v23, s27, v29
	v_lshl_add_u64 v[22:23], v[20:21], 1, v[28:29]
	s_mov_b32 s27, 0x22000
	v_add_co_u32_e32 v28, vcc, s27, v22
	s_mov_b64 s[42:43], 0x22000
	s_nop 0
	v_addc_co_u32_e32 v29, vcc, 0, v23, vcc
	s_mov_b32 s27, 0x44000
	global_store_dwordx4 v[22:23], v[124:127], off
	global_store_dwordx4 v[22:23], v[104:107], off offset:256
	v_lshl_add_u64 v[20:21], v[22:23], 0, s[42:43]
	global_store_dwordx4 v[28:29], v[96:99], off
	global_store_dwordx4 v[20:21], v[88:91], off offset:256
	v_add_co_u32_e32 v28, vcc, s27, v22
	s_mov_b64 s[42:43], 0x44000
	s_nop 0
	v_addc_co_u32_e32 v29, vcc, 0, v23, vcc
	s_mov_b32 s27, 0x66000
	v_lshl_add_u64 v[20:21], v[22:23], 0, s[42:43]
	global_store_dwordx4 v[28:29], v[80:83], off
	global_store_dwordx4 v[20:21], v[76:79], off offset:256
	v_add_co_u32_e32 v28, vcc, s27, v22
	s_mov_b64 s[42:43], 0x66000
	s_nop 0
	v_addc_co_u32_e32 v29, vcc, 0, v23, vcc
	s_mov_b32 s27, 0x110000
	v_lshl_add_u64 v[20:21], v[22:23], 0, s[42:43]
	global_store_dwordx4 v[28:29], v[72:75], off
	global_store_dwordx4 v[20:21], v[68:71], off offset:256
	v_add_co_u32_e32 v28, vcc, s27, v22
	s_mov_b64 s[42:43], 0x110000
	s_nop 0
	v_addc_co_u32_e32 v29, vcc, 0, v23, vcc
	s_mov_b32 s27, 0x132000
	v_lshl_add_u64 v[20:21], v[22:23], 0, s[42:43]
	global_store_dwordx4 v[28:29], v[60:63], off
	global_store_dwordx4 v[20:21], v[40:43], off offset:256
	v_add_co_u32_e32 v28, vcc, s27, v22
	s_mov_b64 s[42:43], 0x132000
	s_nop 0
	v_addc_co_u32_e32 v29, vcc, 0, v23, vcc
	s_mov_b32 s27, 0x154000
	v_lshl_add_u64 v[20:21], v[22:23], 0, s[42:43]
	global_store_dwordx4 v[28:29], v[32:35], off
	global_store_dwordx4 v[20:21], v[24:27], off offset:256
	s_mov_b64 s[42:43], 0x154000
	v_add_co_u32_e32 v28, vcc, s27, v22
	v_lshl_add_u64 v[20:21], v[22:23], 0, s[42:43]
	s_nop 0
	v_addc_co_u32_e32 v29, vcc, 0, v23, vcc
	s_mov_b64 s[42:43], 0x176000
	global_store_dwordx4 v[28:29], v[16:19], off
	global_store_dwordx4 v[20:21], v[12:15], off offset:256
	v_lshl_add_u64 v[20:21], v[22:23], 0, s[42:43]
	v_add_co_u32_e32 v22, vcc, 0x176000, v22
	s_nop 1
	v_addc_co_u32_e32 v23, vcc, 0, v23, vcc
	global_store_dwordx4 v[22:23], v[8:11], off
	s_movk_i32 s50, 0x100
	s_mov_b32 s51, 0x78787879
	s_cbranch_execnz .LBB0_456
	s_branch .LBB0_470

; #define PG8_LDA(dst, b, h) do { _Pragma("unroll") for (int m = 0; m < 4; ++m) _Pragma("unroll") for (int k = 0; k < 2; ++k) dst[m][k] = *(const LAS bf16x8*)(lds + PG8_SA(b, h) + aoff + m * 2048 + k * 1024); } while (0)
; #define PG8_LDB(dst, b, h) do { _Pragma("unroll") for (int n = 0; n < 2; ++n) _Pragma("unroll") for (int k = 0; k < 2; ++k) dst[n][k] = *(const LAS bf16x8*)(lds + PG8_SB(b, h) + boff + n * 2048 + k * 1024); } while (0)
; #define PG8_MMA(ai, bj, At, Bt_) do { __builtin_amdgcn_s_setprio(1); _Pragma("unroll") for (int m = 0; m < 4; ++m) _Pragma("unroll") for (int n = 0; n < 2; ++n) _Pragma("unroll") for (int k = 0; k < 2; ++k) \
;     acc[ai][bj][m][n] = __builtin_amdgcn_mfma_f32_16x16x32_bf16(Bt_[n][k], At[m][k], acc[ai][bj][m][n], 0, 0, 0); __builtin_amdgcn_s_setprio(0); } while (0)
; #define PG8_WAIT_L(n) asm volatile("s_waitcnt lgkmcnt(" #n ")" ::: "memory")
; #define PG8_BAR __builtin_amdgcn_s_barrier()
; #define PG8_SCHED __builtin_amdgcn_sched_barrier(0)
; #define PG8_STA(bufoff, gbase, ld2) PG8_STAGE3(bufoff, gbase, ld2, R0, R1)
; #define PG8_STB(bufoff, gbase, ld2) PG8_STAGE3(bufoff, gbase, ld2, Rb0, Rb1)
; #define PG8_LDA(dst, b, h) do { _Pragma("unroll") for (int m = 0; m < 4; ++m) _Pragma("unroll") for (int k = 0; k < 2; ++k) dst[m][k] = *(const LAS bf16x8*)(lds + PG8_SA(b, h) + aoff + m * 2048 + k * 1024); } while (0)
; template <class Sched, class Epi>
; DI void gemm_stream(char* smem, const Sched& S_, const Epi& E) {
;     ...
;       const bool last = (t == nt - 2);
;       const char* a1 = cA + (size_t)(t + 1) * kstep;
;       const char* a2 = last ? nA : cA + (size_t)(t + 2) * kstep; const char* b2 = last ? nB : cB + (size_t)(t + 2) * kstep;
;       const char* a3 = a2 + kstep; const char* b3 = b2 + kstep;
;       const int xa2 = (last ? nxt.lda : cur.lda) * 2, xb2 = (last ? nxt.ldb : cur.ldb) * 2;
;       const size_t xhA = (size_t)HALF * xa2, xhB = (size_t)HALF * xb2;
;       PG8_LDB(B0, 0, 0); PG8_SCHED; PG8_LDA(At, 0, 0); PG8_STA(PG8_SA(1, 1), a1 + hA, la2);
;       PG8_WAIT_L(8); PG8_BAR; PG8_WAIT_L(0); PG8_MMA(0, 0, At, B0); PG8_BAR; PG8_SCHED;
;       PG8_LDB(B1, 0, 1); PG8_STB(PG8_SB(0, 0), b2, xb2);
;       PG8_BAR; PG8_WAIT_L(0); PG8_MMA(0, 1, At, B1); PG8_BAR;
;       PG8_LDA(At, 0, 1); PG8_STA(PG8_SA(0, 0), a2, xa2);
;       PG8_BAR; PG8_WAIT_L(0); PG8_MMA(1, 0, At, B0); PG8_BAR; PG8_SCHED;
.LBB0_654:
	s_add_i32 s52, s40, 2
	s_add_u32 s44, s36, 0x80
	s_addc_u32 s41, s37, 0
	s_cmp_eq_u32 s63, s40
	s_cselect_b32 s41, s1, s41
	s_cselect_b32 s40, s0, s44
	s_cselect_b32 s44, s87, s62
	s_cselect_b32 s45, s86, s20
	s_cselect_b32 s47, s27, vcc_hi
	s_cselect_b32 s46, s26, vcc_lo
	s_add_i32 s53, 0, 0x10000
	v_add_u32_e32 v158, s53, v143
	ds_read_b128 v[146:149], v158
	ds_read_b128 v[150:153], v158 offset:1024
	ds_read_b128 v[154:157], v158 offset:2048
	ds_read_b128 v[158:161], v158 offset:3072
	s_lshl_b32 s88, s44, 1
	s_lshl_b32 s50, s45, 1
	s_ashr_i32 s89, s88, 31
	s_ashr_i32 s51, s50, 31
	s_lshl_b64 s[44:45], s[88:89], 7
	v_lshl_add_u64 v[190:191], s[36:37], 0, v[138:139]
	s_add_i32 m0, s33, 0xc000
	ds_read_b128 v[162:165], v145
	ds_read_b128 v[166:169], v145 offset:1024
	ds_read_b128 v[170:173], v145 offset:2048
	ds_read_b128 v[174:177], v145 offset:3072
	ds_read_b128 v[178:181], v145 offset:4096
	ds_read_b128 v[182:185], v145 offset:5120
	ds_read_b128 v[186:189], v145 offset:6144
	ds_read_b128 v[210:213], v145 offset:7168
	global_load_lds_dwordx4 v[190:191], off
	v_lshl_add_u64 v[190:191], s[36:37], 0, v[140:141]
	s_add_i32 m0, s33, 0xe000
	s_nop 0
	global_load_lds_dwordx4 v[190:191], off
	s_waitcnt lgkmcnt(8)
	s_barrier
	s_waitcnt lgkmcnt(0)
	s_waitcnt lgkmcnt(0)
	v_mfma_f32_16x16x32_bf16 v[124:127], v[146:149], v[162:165], v[124:127]
	v_mfma_f32_16x16x32_bf16 v[120:123], v[154:157], v[162:165], v[120:123]
	v_mfma_f32_16x16x32_bf16 v[116:119], v[146:149], v[170:173], v[116:119]
	v_mfma_f32_16x16x32_bf16 v[112:115], v[154:157], v[170:173], v[112:115]
	v_mfma_f32_16x16x32_bf16 v[108:111], v[146:149], v[178:181], v[108:111]
	v_mfma_f32_16x16x32_bf16 v[104:107], v[154:157], v[178:181], v[104:107]
	v_mfma_f32_16x16x32_bf16 v[100:103], v[146:149], v[186:189], v[100:103]
	v_mfma_f32_16x16x32_bf16 v[92:95], v[154:157], v[186:189], v[92:95]
	v_mfma_f32_16x16x32_bf16 v[124:127], v[150:153], v[166:169], v[124:127]
	v_mfma_f32_16x16x32_bf16 v[120:123], v[158:161], v[166:169], v[120:123]
	v_mfma_f32_16x16x32_bf16 v[116:119], v[150:153], v[174:177], v[116:119]
	v_mfma_f32_16x16x32_bf16 v[112:115], v[158:161], v[174:177], v[112:115]
	v_mfma_f32_16x16x32_bf16 v[108:111], v[150:153], v[182:185], v[108:111]
	v_mfma_f32_16x16x32_bf16 v[104:107], v[158:161], v[182:185], v[104:107]
	v_mfma_f32_16x16x32_bf16 v[100:103], v[150:153], v[210:213], v[100:103]
	v_mfma_f32_16x16x32_bf16 v[92:95], v[158:161], v[210:213], v[92:95]
	s_barrier
	s_add_i32 s64, 0, 0x14000
	v_add_u32_e32 v190, s64, v143
	s_add_i32 s53, s53, s13
	ds_read_b128 v[214:217], v190
	ds_read_b128 v[234:237], v190 offset:1024
	ds_read_b128 v[238:241], v190 offset:2048
	ds_read_b128 v[242:245], v190 offset:3072
	v_mad_u64_u32 v[190:191], s[56:57], s50, v135, v[128:129]
	s_mov_b32 m0, s53
	v_mad_u64_u32 v[218:219], s[56:57], s50, v137, v[130:131]
	global_load_lds_dwordx4 v190, s[46:47]
	s_add_i32 m0, s53, 0x2000
	v_mov_b32_e32 v191, v221
	global_load_lds_dwordx4 v218, s[46:47]
	s_barrier
	s_waitcnt lgkmcnt(0)
	v_mov_b32_e32 v219, v221
	v_lshl_add_u64 v[246:247], s[46:47], 0, v[190:191]
	v_lshl_add_u64 v[202:203], s[46:47], 0, v[218:219]
	s_waitcnt lgkmcnt(0)
	v_mfma_f32_16x16x32_bf16 v[96:99], v[214:217], v[162:165], v[96:99]
	v_mfma_f32_16x16x32_bf16 v[88:91], v[238:241], v[162:165], v[88:91]
	v_mfma_f32_16x16x32_bf16 v[84:87], v[214:217], v[170:173], v[84:87]
	v_mfma_f32_16x16x32_bf16 v[80:83], v[238:241], v[170:173], v[80:83]
	v_mfma_f32_16x16x32_bf16 v[76:79], v[214:217], v[178:181], v[76:79]
	v_mfma_f32_16x16x32_bf16 v[72:75], v[238:241], v[178:181], v[72:75]
	v_mfma_f32_16x16x32_bf16 v[68:71], v[214:217], v[186:189], v[68:71]
	v_mfma_f32_16x16x32_bf16 v[64:67], v[238:241], v[186:189], v[64:67]
	v_mfma_f32_16x16x32_bf16 v[96:99], v[234:237], v[166:169], v[96:99]
	v_mfma_f32_16x16x32_bf16 v[88:91], v[242:245], v[166:169], v[88:91]
	v_mfma_f32_16x16x32_bf16 v[84:87], v[234:237], v[174:177], v[84:87]
	v_mfma_f32_16x16x32_bf16 v[80:83], v[242:245], v[174:177], v[80:83]
	v_mfma_f32_16x16x32_bf16 v[76:79], v[234:237], v[182:185], v[76:79]
	v_mfma_f32_16x16x32_bf16 v[72:75], v[242:245], v[182:185], v[72:75]
	v_mfma_f32_16x16x32_bf16 v[68:71], v[234:237], v[210:213], v[68:71]
	v_mfma_f32_16x16x32_bf16 v[64:67], v[242:245], v[210:213], v[64:67]
	s_mov_b32 m0, s33
	v_mad_u64_u32 v[194:195], s[56:57], s88, v129, v[128:129]
	s_barrier
	ds_read_b128 v[162:165], v145 offset:16384
	ds_read_b128 v[166:169], v145 offset:17408
	ds_read_b128 v[170:173], v145 offset:18432
	ds_read_b128 v[174:177], v145 offset:19456
	ds_read_b128 v[178:181], v145 offset:20480
	ds_read_b128 v[182:185], v145 offset:21504
	ds_read_b128 v[186:189], v145 offset:22528
	ds_read_b128 v[210:213], v145 offset:23552
	global_load_lds_dwordx4 v194, s[40:41]
	v_mad_u64_u32 v[200:201], s[56:57], s88, v131, v[130:131]
	s_mov_b32 m0, s34
	v_mov_b32_e32 v195, v221
	global_load_lds_dwordx4 v200, s[40:41]
	s_barrier
	s_waitcnt lgkmcnt(0)
	v_mov_b32_e32 v201, v221
	v_lshl_add_u64 v[208:209], s[40:41], 0, v[194:195]
	v_lshl_add_u64 v[222:223], s[40:41], 0, v[200:201]
	s_waitcnt lgkmcnt(0)
	v_mfma_f32_16x16x32_bf16 v[60:63], v[146:149], v[162:165], v[60:63]
	s_lshl_b64 s[50:51], s[50:51], 7
	v_mfma_f32_16x16x32_bf16 v[56:59], v[154:157], v[162:165], v[56:59]
	v_mfma_f32_16x16x32_bf16 v[52:55], v[146:149], v[170:173], v[52:55]
	v_mfma_f32_16x16x32_bf16 v[48:51], v[154:157], v[170:173], v[48:51]
	v_mfma_f32_16x16x32_bf16 v[44:47], v[146:149], v[178:181], v[44:47]
	v_mfma_f32_16x16x32_bf16 v[40:43], v[154:157], v[178:181], v[40:43]
	v_mfma_f32_16x16x32_bf16 v[32:35], v[146:149], v[186:189], v[32:35]
	v_mfma_f32_16x16x32_bf16 v[24:27], v[154:157], v[186:189], v[24:27]
	v_mfma_f32_16x16x32_bf16 v[60:63], v[150:153], v[166:169], v[60:63]
	v_mfma_f32_16x16x32_bf16 v[56:59], v[158:161], v[166:169], v[56:59]
	v_mfma_f32_16x16x32_bf16 v[52:55], v[150:153], v[174:177], v[52:55]
	v_mfma_f32_16x16x32_bf16 v[48:51], v[158:161], v[174:177], v[48:51]
	v_mfma_f32_16x16x32_bf16 v[44:47], v[150:153], v[182:185], v[44:47]
	v_mfma_f32_16x16x32_bf16 v[40:43], v[158:161], v[182:185], v[40:43]
	v_mfma_f32_16x16x32_bf16 v[32:35], v[150:153], v[210:213], v[32:35]
	v_mfma_f32_16x16x32_bf16 v[24:27], v[158:161], v[210:213], v[24:27]
	s_barrier
; #define PG8_LDA(dst, b, h) do { _Pragma("unroll") for (int m = 0; m < 4; ++m) _Pragma("unroll") for (int k = 0; k < 2; ++k) dst[m][k] = *(const LAS bf16x8*)(lds + PG8_SA(b, h) + aoff + m * 2048 + k * 1024); } while (0)
; #define PG8_LDB(dst, b, h) do { _Pragma("unroll") for (int n = 0; n < 2; ++n) _Pragma("unroll") for (int k = 0; k < 2; ++k) dst[n][k] = *(const LAS bf16x8*)(lds + PG8_SB(b, h) + boff + n * 2048 + k * 1024); } while (0)
; #define PG8_MMA(ai, bj, At, Bt_) do { __builtin_amdgcn_s_setprio(1); _Pragma("unroll") for (int m = 0; m < 4; ++m) _Pragma("unroll") for (int n = 0; n < 2; ++n) _Pragma("unroll") for (int k = 0; k < 2; ++k) \
;     acc[ai][bj][m][n] = __builtin_amdgcn_mfma_f32_16x16x32_bf16(Bt_[n][k], At[m][k], acc[ai][bj][m][n], 0, 0, 0); __builtin_amdgcn_s_setprio(0); } while (0)
; #define PG8_WAIT_V(n) asm volatile("s_waitcnt vmcnt(" #n ")" ::: "memory")
; #define PG8_WAIT_L(n) asm volatile("s_waitcnt lgkmcnt(" #n ")" ::: "memory")
; #define PG8_BAR __builtin_amdgcn_s_barrier()
; #define PG8_SCHED __builtin_amdgcn_sched_barrier(0)
; #define PG8_STA(bufoff, gbase, ld2) PG8_STAGE3(bufoff, gbase, ld2, R0, R1)
; #define PG8_STB(bufoff, gbase, ld2) PG8_STAGE3(bufoff, gbase, ld2, Rb0, Rb1)
; #define PG8_LDA(dst, b, h) do { _Pragma("unroll") for (int m = 0; m < 4; ++m) _Pragma("unroll") for (int k = 0; k < 2; ++k) dst[m][k] = *(const LAS bf16x8*)(lds + PG8_SA(b, h) + aoff + m * 2048 + k * 1024); } while (0)
; #define PG8_LDB(dst, b, h) do { _Pragma("unroll") for (int n = 0; n < 2; ++n) _Pragma("unroll") for (int k = 0; k < 2; ++k) dst[n][k] = *(const LAS bf16x8*)(lds + PG8_SB(b, h) + boff + n * 2048 + k * 1024); } while (0)
; #define PG8_WAIT_V(n) asm volatile("s_waitcnt vmcnt(" #n ")" ::: "memory")
; template <class Sched, class Epi>
; DI void gemm_stream(char* smem, const Sched& S_, const Epi& E) {
;     ...
;       PG8_STB(PG8_SB(0, 1), b2 + xhB, xb2);
;       PG8_WAIT_V(6); PG8_BAR; PG8_MMA(1, 1, At, B1); PG8_BAR;
;       PG8_LDB(B0, 1, 0); PG8_SCHED; PG8_LDA(At, 1, 0); PG8_STA(PG8_SA(0, 1), a2 + xhA, xa2);
;       PG8_WAIT_L(8); PG8_BAR; PG8_WAIT_L(0); PG8_MMA(0, 0, At, B0); PG8_BAR; PG8_SCHED;
;       PG8_LDB(B1, 1, 1); PG8_STB(PG8_SB(1, 0), b3, xb2);
;       PG8_BAR; PG8_WAIT_L(0); PG8_MMA(0, 1, At, B1); PG8_BAR;
;       PG8_LDA(At, 1, 1); PG8_STA(PG8_SA(1, 0), a3, xa2);
;       PG8_BAR; PG8_WAIT_L(0); PG8_MMA(1, 0, At, B0); PG8_BAR; PG8_SCHED;
	s_add_u32 s46, s46, s50
	s_addc_u32 s47, s47, s51
	s_add_i32 s50, s64, s13
	s_mov_b32 m0, s50
	s_nop 0
	global_load_lds_dwordx4 v190, s[46:47]
	s_add_i32 m0, s50, 0x2000
	v_lshl_add_u64 v[190:191], s[46:47], 0, v[190:191]
	global_load_lds_dwordx4 v218, s[46:47]
	s_waitcnt vmcnt(6)
	v_lshl_add_u64 v[218:219], s[46:47], 0, v[218:219]
	s_barrier
	v_mfma_f32_16x16x32_bf16 v[36:39], v[214:217], v[162:165], v[36:39]
	v_mfma_f32_16x16x32_bf16 v[28:31], v[238:241], v[162:165], v[28:31]
	v_mfma_f32_16x16x32_bf16 v[20:23], v[214:217], v[170:173], v[20:23]
	v_mfma_f32_16x16x32_bf16 v[16:19], v[238:241], v[170:173], v[16:19]
	v_mfma_f32_16x16x32_bf16 v[12:15], v[214:217], v[178:181], v[12:15]
	v_mfma_f32_16x16x32_bf16 v[8:11], v[238:241], v[178:181], v[8:11]
	v_mfma_f32_16x16x32_bf16 v[4:7], v[214:217], v[186:189], v[4:7]
	v_mfma_f32_16x16x32_bf16 v[0:3], v[238:241], v[186:189], v[0:3]
	v_mfma_f32_16x16x32_bf16 v[36:39], v[234:237], v[166:169], v[36:39]
	v_mfma_f32_16x16x32_bf16 v[28:31], v[242:245], v[166:169], v[28:31]
	v_mfma_f32_16x16x32_bf16 v[20:23], v[234:237], v[174:177], v[20:23]
	v_mfma_f32_16x16x32_bf16 v[16:19], v[242:245], v[174:177], v[16:19]
	v_mfma_f32_16x16x32_bf16 v[12:15], v[234:237], v[182:185], v[12:15]
	v_mfma_f32_16x16x32_bf16 v[8:11], v[242:245], v[182:185], v[8:11]
	v_mfma_f32_16x16x32_bf16 v[4:7], v[234:237], v[210:213], v[4:7]
	v_mfma_f32_16x16x32_bf16 v[0:3], v[242:245], v[210:213], v[0:3]
	s_add_i32 s46, 0, 0x18000
	v_add_u32_e32 v158, s46, v143
	s_barrier
	ds_read_b128 v[146:149], v158
	ds_read_b128 v[150:153], v158 offset:1024
	ds_read_b128 v[154:157], v158 offset:2048
	ds_read_b128 v[158:161], v158 offset:3072
	s_add_u32 s40, s40, s44
	s_addc_u32 s41, s41, s45
	s_mov_b32 m0, s49
	ds_read_b128 v[162:165], v145 offset:32768
	ds_read_b128 v[166:169], v145 offset:33792
	ds_read_b128 v[170:173], v145 offset:34816
	ds_read_b128 v[174:177], v145 offset:35840
	ds_read_b128 v[178:181], v145 offset:36864
	ds_read_b128 v[182:185], v145 offset:37888
	ds_read_b128 v[186:189], v145 offset:38912
	ds_read_b128 v[210:213], v145 offset:39936
	global_load_lds_dwordx4 v194, s[40:41]
	s_mov_b32 m0, s60
	s_nop 0
	global_load_lds_dwordx4 v200, s[40:41]
	s_waitcnt lgkmcnt(8)
	s_barrier
	s_waitcnt lgkmcnt(0)
	s_waitcnt lgkmcnt(0)
	v_mfma_f32_16x16x32_bf16 v[124:127], v[146:149], v[162:165], v[124:127]
	v_mfma_f32_16x16x32_bf16 v[120:123], v[154:157], v[162:165], v[120:123]
	v_mfma_f32_16x16x32_bf16 v[116:119], v[146:149], v[170:173], v[116:119]
	v_mfma_f32_16x16x32_bf16 v[112:115], v[154:157], v[170:173], v[112:115]
	v_mfma_f32_16x16x32_bf16 v[108:111], v[146:149], v[178:181], v[108:111]
	v_mfma_f32_16x16x32_bf16 v[104:107], v[154:157], v[178:181], v[104:107]
	v_mfma_f32_16x16x32_bf16 v[100:103], v[146:149], v[186:189], v[100:103]
	v_mfma_f32_16x16x32_bf16 v[92:95], v[154:157], v[186:189], v[92:95]
	v_mfma_f32_16x16x32_bf16 v[124:127], v[150:153], v[166:169], v[124:127]
	v_mfma_f32_16x16x32_bf16 v[120:123], v[158:161], v[166:169], v[120:123]
	v_mfma_f32_16x16x32_bf16 v[116:119], v[150:153], v[174:177], v[116:119]
	v_mfma_f32_16x16x32_bf16 v[112:115], v[158:161], v[174:177], v[112:115]
	v_mfma_f32_16x16x32_bf16 v[108:111], v[150:153], v[182:185], v[108:111]
	v_mfma_f32_16x16x32_bf16 v[104:107], v[158:161], v[182:185], v[104:107]
	v_mfma_f32_16x16x32_bf16 v[100:103], v[150:153], v[210:213], v[100:103]
	v_mfma_f32_16x16x32_bf16 v[92:95], v[158:161], v[210:213], v[92:95]
	s_barrier
	s_add_i32 s40, 0, 0x1c000
	v_add_u32_e32 v194, s40, v143
	s_add_i32 s41, s46, s13
	ds_read_b128 v[214:217], v194
	ds_read_b128 v[234:237], v194 offset:1024
	ds_read_b128 v[238:241], v194 offset:2048
	ds_read_b128 v[242:245], v194 offset:3072
	v_lshl_add_u64 v[194:195], v[246:247], 0, s[58:59]
	s_mov_b32 m0, s41
	s_nop 0
	global_load_lds_dwordx4 v[194:195], off
	v_lshl_add_u64 v[194:195], v[202:203], 0, s[58:59]
	s_add_i32 m0, s41, 0x2000
	s_nop 0
	global_load_lds_dwordx4 v[194:195], off
	s_barrier
	s_waitcnt lgkmcnt(0)
	s_waitcnt lgkmcnt(0)
	v_mfma_f32_16x16x32_bf16 v[96:99], v[214:217], v[162:165], v[96:99]
	v_mfma_f32_16x16x32_bf16 v[88:91], v[238:241], v[162:165], v[88:91]
	v_mfma_f32_16x16x32_bf16 v[84:87], v[214:217], v[170:173], v[84:87]
	v_mfma_f32_16x16x32_bf16 v[80:83], v[238:241], v[170:173], v[80:83]
	v_mfma_f32_16x16x32_bf16 v[76:79], v[214:217], v[178:181], v[76:79]
	v_mfma_f32_16x16x32_bf16 v[72:75], v[238:241], v[178:181], v[72:75]
	v_mfma_f32_16x16x32_bf16 v[68:71], v[214:217], v[186:189], v[68:71]
	v_mfma_f32_16x16x32_bf16 v[64:67], v[238:241], v[186:189], v[64:67]
	v_mfma_f32_16x16x32_bf16 v[96:99], v[234:237], v[166:169], v[96:99]
	v_mfma_f32_16x16x32_bf16 v[88:91], v[242:245], v[166:169], v[88:91]
	v_mfma_f32_16x16x32_bf16 v[84:87], v[234:237], v[174:177], v[84:87]
	v_mfma_f32_16x16x32_bf16 v[80:83], v[242:245], v[174:177], v[80:83]
	v_mfma_f32_16x16x32_bf16 v[76:79], v[234:237], v[182:185], v[76:79]
	v_mfma_f32_16x16x32_bf16 v[72:75], v[242:245], v[182:185], v[72:75]
	v_mfma_f32_16x16x32_bf16 v[68:71], v[234:237], v[210:213], v[68:71]
	v_mfma_f32_16x16x32_bf16 v[64:67], v[242:245], v[210:213], v[64:67]
	s_mov_b32 m0, s97
	v_lshl_add_u64 v[194:195], v[208:209], 0, s[58:59]
	s_barrier
	ds_read_b128 v[162:165], v145 offset:49152
	ds_read_b128 v[166:169], v145 offset:50176
	ds_read_b128 v[170:173], v145 offset:51200
	ds_read_b128 v[174:177], v145 offset:52224
	ds_read_b128 v[178:181], v145 offset:53248
	ds_read_b128 v[182:185], v145 offset:54272
	ds_read_b128 v[186:189], v145 offset:55296
	ds_read_b128 v[210:213], v145 offset:56320
	global_load_lds_dwordx4 v[194:195], off
	v_lshl_add_u64 v[194:195], v[222:223], 0, s[58:59]
	s_mov_b32 m0, s42
	s_nop 0
	global_load_lds_dwordx4 v[194:195], off
	s_barrier
; #define PG8_LDA(dst, b, h) do { _Pragma("unroll") for (int m = 0; m < 4; ++m) _Pragma("unroll") for (int k = 0; k < 2; ++k) dst[m][k] = *(const LAS bf16x8*)(lds + PG8_SA(b, h) + aoff + m * 2048 + k * 1024); } while (0)
; #define PG8_MMA(ai, bj, At, Bt_) do { __builtin_amdgcn_s_setprio(1); _Pragma("unroll") for (int m = 0; m < 4; ++m) _Pragma("unroll") for (int n = 0; n < 2; ++n) _Pragma("unroll") for (int k = 0; k < 2; ++k) \
;     acc[ai][bj][m][n] = __builtin_amdgcn_mfma_f32_16x16x32_bf16(Bt_[n][k], At[m][k], acc[ai][bj][m][n], 0, 0, 0); __builtin_amdgcn_s_setprio(0); } while (0)
; #define PG8_WAIT_V(n) asm volatile("s_waitcnt vmcnt(" #n ")" ::: "memory")
; #define PG8_WAIT_L(n) asm volatile("s_waitcnt lgkmcnt(" #n ")" ::: "memory")
; #define PG8_BAR __builtin_amdgcn_s_barrier()
; #define PG8_SCHED __builtin_amdgcn_sched_barrier(0)
; DI u32x4 pack8v(const f32x4& a, const f32x4& b) { u32x4 w; w.x = pk2(a[0], a[1]); w.y = pk2(a[2], a[3]); w.z = pk2(b[0], b[1]); w.w = pk2(b[2], b[3]); return w; }
; #define PG8_STA(bufoff, gbase, ld2) PG8_STAGE3(bufoff, gbase, ld2, R0, R1)
; #define PG8_STB(bufoff, gbase, ld2) PG8_STAGE3(bufoff, gbase, ld2, Rb0, Rb1)
; #define PG8_LDA(dst, b, h) do { _Pragma("unroll") for (int m = 0; m < 4; ++m) _Pragma("unroll") for (int k = 0; k < 2; ++k) dst[m][k] = *(const LAS bf16x8*)(lds + PG8_SA(b, h) + aoff + m * 2048 + k * 1024); } while (0)
; template <class Sched, class Epi>
; DI void gemm_stream(char* smem, const Sched& S_, const Epi& E) {
;     ...
;       PG8_LDA(At, 1, 1); PG8_STA(PG8_SA(1, 0), a3, xa2);
;       PG8_BAR; PG8_WAIT_L(0); PG8_MMA(1, 0, At, B0); PG8_BAR; PG8_SCHED;
;       PG8_STB(PG8_SB(1, 1), b3 + xhB, xb2);
;       PG8_WAIT_V(6); PG8_BAR; PG8_MMA(1, 1, At, B1); PG8_BAR;
;     }
;     E(acc, cur, wr, wc, fr, fq);
;   DI void operator()(const acc_t& acc, const Desc& u, int wr, int wc, int fr, int fq) const {
;     ...
;     } else if (u.kind == 1) {
; #pragma unroll
;       for (int ai = 0; ai < 2; ++ai)
; #pragma unroll
;         for (int m = 0; m < 4; ++m) { const int tl = row0 + ai * HALF + m * 16, bl = tl / S, s = tl - bl * S;
; #pragma unroll
;           for (int bj = 0; bj < 2; ++bj) { const int c = u.pn * BM + bj * HALF + wc * 32 + 8 * fq, head = c >> 6, j = c & 63;
;             *(u32x4*)(Kb + ((size_t)(bl * 8 + head) * S + s) * 96 + j) = pack8v(acc[ai][bj][m][0], acc[ai][bj][m][1]); } }
	s_waitcnt lgkmcnt(0)
	s_waitcnt lgkmcnt(0)
	v_mfma_f32_16x16x32_bf16 v[60:63], v[146:149], v[162:165], v[60:63]
	v_mfma_f32_16x16x32_bf16 v[56:59], v[154:157], v[162:165], v[56:59]
	v_mfma_f32_16x16x32_bf16 v[52:55], v[146:149], v[170:173], v[52:55]
	v_mfma_f32_16x16x32_bf16 v[48:51], v[154:157], v[170:173], v[48:51]
	v_mfma_f32_16x16x32_bf16 v[44:47], v[146:149], v[178:181], v[44:47]
	v_mfma_f32_16x16x32_bf16 v[40:43], v[154:157], v[178:181], v[40:43]
	v_mfma_f32_16x16x32_bf16 v[32:35], v[146:149], v[186:189], v[32:35]
	v_mfma_f32_16x16x32_bf16 v[24:27], v[154:157], v[186:189], v[24:27]
	v_mfma_f32_16x16x32_bf16 v[60:63], v[150:153], v[166:169], v[60:63]
	v_mfma_f32_16x16x32_bf16 v[56:59], v[158:161], v[166:169], v[56:59]
	v_mfma_f32_16x16x32_bf16 v[52:55], v[150:153], v[174:177], v[52:55]
	v_mfma_f32_16x16x32_bf16 v[48:51], v[158:161], v[174:177], v[48:51]
	v_mfma_f32_16x16x32_bf16 v[44:47], v[150:153], v[182:185], v[44:47]
	v_mfma_f32_16x16x32_bf16 v[40:43], v[158:161], v[182:185], v[40:43]
	v_mfma_f32_16x16x32_bf16 v[32:35], v[150:153], v[210:213], v[32:35]
	v_mfma_f32_16x16x32_bf16 v[24:27], v[158:161], v[210:213], v[24:27]
	s_barrier
	s_add_i32 s40, s40, s13
	v_lshl_add_u64 v[146:147], v[190:191], 0, s[58:59]
	s_mov_b32 m0, s40
	s_nop 0
	global_load_lds_dwordx4 v[146:147], off
	v_lshl_add_u64 v[146:147], v[218:219], 0, s[58:59]
	s_add_i32 m0, s40, 0x2000
	s_nop 0
	global_load_lds_dwordx4 v[146:147], off
	s_waitcnt vmcnt(6)
	s_barrier
	v_mfma_f32_16x16x32_bf16 v[36:39], v[214:217], v[162:165], v[36:39]
	v_mfma_f32_16x16x32_bf16 v[28:31], v[238:241], v[162:165], v[28:31]
	v_mfma_f32_16x16x32_bf16 v[20:23], v[214:217], v[170:173], v[20:23]
	v_mfma_f32_16x16x32_bf16 v[16:19], v[238:241], v[170:173], v[16:19]
	v_mfma_f32_16x16x32_bf16 v[12:15], v[214:217], v[178:181], v[12:15]
	v_mfma_f32_16x16x32_bf16 v[8:11], v[238:241], v[178:181], v[8:11]
	v_mfma_f32_16x16x32_bf16 v[4:7], v[214:217], v[186:189], v[4:7]
	v_mfma_f32_16x16x32_bf16 v[0:3], v[238:241], v[186:189], v[0:3]
	v_mfma_f32_16x16x32_bf16 v[36:39], v[234:237], v[166:169], v[36:39]
	v_mfma_f32_16x16x32_bf16 v[28:31], v[242:245], v[166:169], v[28:31]
	v_mfma_f32_16x16x32_bf16 v[20:23], v[234:237], v[174:177], v[20:23]
	v_mfma_f32_16x16x32_bf16 v[16:19], v[242:245], v[174:177], v[16:19]
	v_mfma_f32_16x16x32_bf16 v[12:15], v[234:237], v[182:185], v[12:15]
	v_mfma_f32_16x16x32_bf16 v[8:11], v[242:245], v[182:185], v[8:11]
	v_mfma_f32_16x16x32_bf16 v[4:7], v[234:237], v[210:213], v[4:7]
	v_mfma_f32_16x16x32_bf16 v[0:3], v[242:245], v[210:213], v[0:3]
	s_add_u32 s36, s36, 0x100
	s_addc_u32 s37, s37, 0
	s_add_u32 vcc_lo, vcc_lo, 0x100
	s_addc_u32 vcc_hi, vcc_hi, 0
	s_cmp_ge_i32 s52, s5
	s_mov_b32 s40, s52
	s_barrier
	s_cbranch_scc0 .LBB0_654
	v_readlane_b32 s46, v254, 46
	v_lshl_add_u32 v138, s4, 8, v142
	s_mov_b64 s[44:45], -1
	s_mov_b64 s[36:37], 0
	s_cmp_lt_i32 s91, 1
	s_mov_b64 s[40:41], 0
	v_readlane_b32 s47, v254, 47
	s_movk_i32 s50, 0x100
	s_mov_b32 s51, 0x78787879
	s_cbranch_scc1 .LBB0_659
	s_cmp_eq_u32 s91, 1
	s_mov_b64 s[40:41], -1
	s_cbranch_scc0 .LBB0_658
	v_mul_hi_i32 v139, v138, s51
	v_lshrrev_b32_e32 v140, 31, v139
	v_ashrrev_i32_e32 v139, 11, v139
	s_lshl_b32 s4, s9, 8
	v_add_u32_e32 v139, v139, v140
	s_movk_i32 s20, 0xef00
	s_or_b32 s4, s4, s90
	v_mad_i32_i24 v140, v139, s20, v138
	v_lshlrev_b32_e32 v139, 3, v139
	s_ashr_i32 s4, s4, 6
	v_ashrrev_i32_e32 v141, 31, v140
	v_add_u32_e32 v150, s4, v139
	s_movk_i32 s44, 0x1100
	s_or_b32 s5, s4, 2
	v_mad_i64_i32 v[150:151], s[40:41], v150, s44, v[140:141]
	v_add_u32_e32 v139, s5, v139
	v_mad_u64_u32 v[152:153], s[40:41], v150, s17, v[132:133]
	v_mad_i64_i32 v[140:141], s[40:41], v139, s44, v[140:141]
	v_or_b32_e32 v139, 16, v138
	v_mad_i32_i24 v153, v151, s17, v153
	v_mad_u64_u32 v[150:151], s[40:41], v140, s17, v[132:133]
	v_mul_hi_i32 v140, v139, s51
	v_mad_i32_i24 v151, v141, s17, v151
	v_lshrrev_b32_e32 v141, 31, v140
	v_ashrrev_i32_e32 v140, 11, v140
	v_cvt_pk_bf16_f32 v146, v124, v125
	v_cvt_pk_bf16_f32 v147, v126, v127
	v_cvt_pk_bf16_f32 v148, v120, v121
	v_cvt_pk_bf16_f32 v149, v122, v123
	v_add_u32_e32 v141, v140, v141
	global_store_dwordx4 v[152:153], v[146:149], off
	v_mad_i32_i24 v140, v141, s20, v139
	v_lshlrev_b32_e32 v139, 3, v141
	v_cvt_pk_bf16_f32 v146, v96, v97
	v_cvt_pk_bf16_f32 v147, v98, v99
	v_cvt_pk_bf16_f32 v148, v88, v89
	v_cvt_pk_bf16_f32 v149, v90, v91
	global_store_dwordx4 v[150:151], v[146:149], off
	v_ashrrev_i32_e32 v141, 31, v140
	v_add_u32_e32 v150, s4, v139
	v_mad_i64_i32 v[150:151], s[40:41], v150, s44, v[140:141]
	v_add_u32_e32 v139, s5, v139
	v_mad_u64_u32 v[152:153], s[40:41], v150, s17, v[132:133]
	v_mad_i64_i32 v[140:141], s[40:41], v139, s44, v[140:141]
	v_or_b32_e32 v139, 32, v138
	v_mad_i32_i24 v153, v151, s17, v153
	v_mad_u64_u32 v[150:151], s[40:41], v140, s17, v[132:133]
	v_mul_hi_i32 v140, v139, s51
	v_mad_i32_i24 v151, v141, s17, v151
	v_lshrrev_b32_e32 v141, 31, v140
	v_ashrrev_i32_e32 v140, 11, v140
	v_cvt_pk_bf16_f32 v146, v116, v117
	v_cvt_pk_bf16_f32 v147, v118, v119
	v_cvt_pk_bf16_f32 v148, v112, v113
	v_cvt_pk_bf16_f32 v149, v114, v115
	v_add_u32_e32 v141, v140, v141
	global_store_dwordx4 v[152:153], v[146:149], off
	v_mad_i32_i24 v140, v141, s20, v139
	v_lshlrev_b32_e32 v139, 3, v141
	v_cvt_pk_bf16_f32 v146, v84, v85
	v_cvt_pk_bf16_f32 v147, v86, v87
	v_cvt_pk_bf16_f32 v148, v80, v81
	v_cvt_pk_bf16_f32 v149, v82, v83
	global_store_dwordx4 v[150:151], v[146:149], off
	v_ashrrev_i32_e32 v141, 31, v140
	v_add_u32_e32 v150, s4, v139
	v_mad_i64_i32 v[150:151], s[40:41], v150, s44, v[140:141]
	v_add_u32_e32 v139, s5, v139
	v_mad_u64_u32 v[152:153], s[40:41], v150, s17, v[132:133]
; DI u32x4 pack8v(const f32x4& a, const f32x4& b) { u32x4 w; w.x = pk2(a[0], a[1]); w.y = pk2(a[2], a[3]); w.z = pk2(b[0], b[1]); w.w = pk2(b[2], b[3]); return w; }
;   DI void operator()(const acc_t& acc, const Desc& u, int wr, int wc, int fr, int fq) const {
;     ...
;     } else if (u.kind == 1) {
; #pragma unroll
;       for (int ai = 0; ai < 2; ++ai)
; #pragma unroll
;         for (int m = 0; m < 4; ++m) { const int tl = row0 + ai * HALF + m * 16, bl = tl / S, s = tl - bl * S;
; #pragma unroll
;           for (int bj = 0; bj < 2; ++bj) { const int c = u.pn * BM + bj * HALF + wc * 32 + 8 * fq, head = c >> 6, j = c & 63;
;             *(u32x4*)(Kb + ((size_t)(bl * 8 + head) * S + s) * 96 + j) = pack8v(acc[ai][bj][m][0], acc[ai][bj][m][1]); } }
	v_mad_i64_i32 v[140:141], s[40:41], v139, s44, v[140:141]
	v_or_b32_e32 v139, 48, v138
	v_mad_i32_i24 v153, v151, s17, v153
	v_mad_u64_u32 v[150:151], s[40:41], v140, s17, v[132:133]
	v_mul_hi_i32 v140, v139, s51
	v_mad_i32_i24 v151, v141, s17, v151
	v_lshrrev_b32_e32 v141, 31, v140
	v_ashrrev_i32_e32 v140, 11, v140
	v_cvt_pk_bf16_f32 v146, v108, v109
	v_cvt_pk_bf16_f32 v147, v110, v111
	v_cvt_pk_bf16_f32 v148, v104, v105
	v_cvt_pk_bf16_f32 v149, v106, v107
	v_add_u32_e32 v141, v140, v141
	global_store_dwordx4 v[152:153], v[146:149], off
	v_mad_i32_i24 v140, v141, s20, v139
	v_lshlrev_b32_e32 v139, 3, v141
	v_cvt_pk_bf16_f32 v146, v76, v77
	v_cvt_pk_bf16_f32 v147, v78, v79
	v_cvt_pk_bf16_f32 v148, v72, v73
	v_cvt_pk_bf16_f32 v149, v74, v75
	global_store_dwordx4 v[150:151], v[146:149], off
	v_ashrrev_i32_e32 v141, 31, v140
	v_add_u32_e32 v150, s4, v139
	v_mad_i64_i32 v[150:151], s[40:41], v150, s44, v[140:141]
	v_add_u32_e32 v139, s5, v139
	v_mad_u64_u32 v[152:153], s[40:41], v150, s17, v[132:133]
	v_mad_i64_i32 v[140:141], s[40:41], v139, s44, v[140:141]
	v_add_u32_e32 v139, 0x80, v138
	v_mad_i32_i24 v153, v151, s17, v153
	v_mad_u64_u32 v[150:151], s[40:41], v140, s17, v[132:133]
	v_mul_hi_i32 v140, v139, s51
	v_mad_i32_i24 v151, v141, s17, v151
	v_lshrrev_b32_e32 v141, 31, v140
	v_ashrrev_i32_e32 v140, 11, v140
	v_cvt_pk_bf16_f32 v146, v100, v101
	v_cvt_pk_bf16_f32 v147, v102, v103
	v_cvt_pk_bf16_f32 v148, v92, v93
	v_cvt_pk_bf16_f32 v149, v94, v95
	v_add_u32_e32 v141, v140, v141
	global_store_dwordx4 v[152:153], v[146:149], off
	v_mad_i32_i24 v140, v141, s20, v139
	v_lshlrev_b32_e32 v139, 3, v141
	v_cvt_pk_bf16_f32 v146, v68, v69
	v_cvt_pk_bf16_f32 v147, v70, v71
	v_cvt_pk_bf16_f32 v148, v64, v65
	v_cvt_pk_bf16_f32 v149, v66, v67
	global_store_dwordx4 v[150:151], v[146:149], off
	v_ashrrev_i32_e32 v141, 31, v140
	v_add_u32_e32 v150, s4, v139
	v_mad_i64_i32 v[150:151], s[40:41], v150, s44, v[140:141]
	v_add_u32_e32 v139, s5, v139
	v_mad_u64_u32 v[152:153], s[40:41], v150, s17, v[132:133]
	v_mad_i64_i32 v[140:141], s[40:41], v139, s44, v[140:141]
	v_add_u32_e32 v139, 0x90, v138
	v_mad_i32_i24 v153, v151, s17, v153
	v_mad_u64_u32 v[150:151], s[40:41], v140, s17, v[132:133]
	v_mul_hi_i32 v140, v139, s51
	v_mad_i32_i24 v151, v141, s17, v151
	v_lshrrev_b32_e32 v141, 31, v140
	v_ashrrev_i32_e32 v140, 11, v140
	v_cvt_pk_bf16_f32 v146, v60, v61
	v_cvt_pk_bf16_f32 v147, v62, v63
	v_cvt_pk_bf16_f32 v148, v56, v57
	v_cvt_pk_bf16_f32 v149, v58, v59
	v_add_u32_e32 v141, v140, v141
	global_store_dwordx4 v[152:153], v[146:149], off
	v_mad_i32_i24 v140, v141, s20, v139
	v_lshlrev_b32_e32 v139, 3, v141
	v_cvt_pk_bf16_f32 v146, v36, v37
	v_cvt_pk_bf16_f32 v147, v38, v39
	v_cvt_pk_bf16_f32 v148, v28, v29
	v_cvt_pk_bf16_f32 v149, v30, v31
	global_store_dwordx4 v[150:151], v[146:149], off
	v_ashrrev_i32_e32 v141, 31, v140
	v_add_u32_e32 v150, s4, v139
	v_mad_i64_i32 v[150:151], s[40:41], v150, s44, v[140:141]
	v_add_u32_e32 v139, s5, v139
	v_mad_u64_u32 v[152:153], s[40:41], v150, s17, v[132:133]
	v_mad_i64_i32 v[140:141], s[40:41], v139, s44, v[140:141]
	v_add_u32_e32 v139, 0xa0, v138
	v_mad_i32_i24 v153, v151, s17, v153
	v_mad_u64_u32 v[150:151], s[40:41], v140, s17, v[132:133]
	v_mul_hi_i32 v140, v139, s51
	v_mad_i32_i24 v151, v141, s17, v151
	v_lshrrev_b32_e32 v141, 31, v140
	v_ashrrev_i32_e32 v140, 11, v140
	v_cvt_pk_bf16_f32 v146, v52, v53
	v_cvt_pk_bf16_f32 v147, v54, v55
	v_cvt_pk_bf16_f32 v148, v48, v49
	v_cvt_pk_bf16_f32 v149, v50, v51
	v_add_u32_e32 v141, v140, v141
	global_store_dwordx4 v[152:153], v[146:149], off
	v_mad_i32_i24 v140, v141, s20, v139
	v_lshlrev_b32_e32 v139, 3, v141
	v_cvt_pk_bf16_f32 v146, v20, v21
	v_cvt_pk_bf16_f32 v147, v22, v23
	v_cvt_pk_bf16_f32 v148, v16, v17
	v_cvt_pk_bf16_f32 v149, v18, v19
	global_store_dwordx4 v[150:151], v[146:149], off
	v_ashrrev_i32_e32 v141, 31, v140
	v_add_u32_e32 v150, s4, v139
	v_mad_i64_i32 v[150:151], s[40:41], v150, s44, v[140:141]
	v_add_u32_e32 v139, s5, v139
	v_mad_u64_u32 v[152:153], s[40:41], v150, s17, v[132:133]
	v_mad_i64_i32 v[140:141], s[40:41], v139, s44, v[140:141]
	v_add_u32_e32 v139, 0xb0, v138
	v_mad_i32_i24 v153, v151, s17, v153
	v_mad_u64_u32 v[150:151], s[40:41], v140, s17, v[132:133]
	v_mul_hi_i32 v140, v139, s51
	v_mad_i32_i24 v151, v141, s17, v151
	v_lshrrev_b32_e32 v141, 31, v140
	v_ashrrev_i32_e32 v140, 11, v140
	v_cvt_pk_bf16_f32 v146, v44, v45
	v_cvt_pk_bf16_f32 v147, v46, v47
	v_cvt_pk_bf16_f32 v148, v40, v41
	v_cvt_pk_bf16_f32 v149, v42, v43
	v_add_u32_e32 v141, v140, v141
	global_store_dwordx4 v[152:153], v[146:149], off
	v_mad_i32_i24 v140, v141, s20, v139
	v_lshlrev_b32_e32 v139, 3, v141
	v_cvt_pk_bf16_f32 v146, v12, v13
	v_cvt_pk_bf16_f32 v147, v14, v15
	v_cvt_pk_bf16_f32 v148, v8, v9
	v_cvt_pk_bf16_f32 v149, v10, v11
	global_store_dwordx4 v[150:151], v[146:149], off
	v_ashrrev_i32_e32 v141, 31, v140
	v_add_u32_e32 v150, s4, v139
	v_mad_i64_i32 v[150:151], s[40:41], v150, s44, v[140:141]
	v_add_u32_e32 v139, s5, v139
	v_mad_u64_u32 v[152:153], s[40:41], v150, s17, v[132:133]
	v_mad_i64_i32 v[140:141], s[4:5], v139, s44, v[140:141]
	v_cvt_pk_bf16_f32 v146, v32, v33
	v_cvt_pk_bf16_f32 v147, v34, v35
	v_cvt_pk_bf16_f32 v148, v24, v25
	v_cvt_pk_bf16_f32 v149, v26, v27
	v_mad_i32_i24 v153, v151, s17, v153
	v_mad_u64_u32 v[150:151], s[4:5], v140, s17, v[132:133]
	global_store_dwordx4 v[152:153], v[146:149], off
	v_mad_i32_i24 v151, v141, s17, v151
	s_movk_i32 s80, 0xef00
	v_cvt_pk_bf16_f32 v146, v4, v5
	v_cvt_pk_bf16_f32 v147, v6, v7
	v_cvt_pk_bf16_f32 v148, v0, v1
	v_cvt_pk_bf16_f32 v149, v2, v3
	global_store_dwordx4 v[150:151], v[146:149], off
	s_mov_b64 s[40:41], 0

; #define PG8_LDA(dst, b, h) do { _Pragma("unroll") for (int m = 0; m < 4; ++m) _Pragma("unroll") for (int k = 0; k < 2; ++k) dst[m][k] = *(const LAS bf16x8*)(lds + PG8_SA(b, h) + aoff + m * 2048 + k * 1024); } while (0)
; #define PG8_LDB(dst, b, h) do { _Pragma("unroll") for (int n = 0; n < 2; ++n) _Pragma("unroll") for (int k = 0; k < 2; ++k) dst[n][k] = *(const LAS bf16x8*)(lds + PG8_SB(b, h) + boff + n * 2048 + k * 1024); } while (0)
; #define PG8_MMA(ai, bj, At, Bt_) do { __builtin_amdgcn_s_setprio(1); _Pragma("unroll") for (int m = 0; m < 4; ++m) _Pragma("unroll") for (int n = 0; n < 2; ++n) _Pragma("unroll") for (int k = 0; k < 2; ++k) \
;     acc[ai][bj][m][n] = __builtin_amdgcn_mfma_f32_16x16x32_bf16(Bt_[n][k], At[m][k], acc[ai][bj][m][n], 0, 0, 0); __builtin_amdgcn_s_setprio(0); } while (0)
; #define PG8_WAIT_L(n) asm volatile("s_waitcnt lgkmcnt(" #n ")" ::: "memory")
; #define PG8_BAR __builtin_amdgcn_s_barrier()
; #define PG8_SCHED __builtin_amdgcn_sched_barrier(0)
; #define PG8_STA(bufoff, gbase, ld2) PG8_STAGE3(bufoff, gbase, ld2, R0, R1)
; #define PG8_STB(bufoff, gbase, ld2) PG8_STAGE3(bufoff, gbase, ld2, Rb0, Rb1)
; #define PG8_WAIT_L(n) asm volatile("s_waitcnt lgkmcnt(" #n ")" ::: "memory")
; #define PG8_BAR __builtin_amdgcn_s_barrier()
; #define PG8_SCHED __builtin_amdgcn_sched_barrier(0)
; template <class Sched, class Epi>
; DI void gemm_stream(char* smem, const Sched& S_, const Epi& E) {
;     ...
;     for (int t = 0; t < nt; t += 2) {
;       const bool last = (t == nt - 2);
;       const char* a1 = cA + (size_t)(t + 1) * kstep;
;       const char* a2 = last ? nA : cA + (size_t)(t + 2) * kstep; const char* b2 = last ? nB : cB + (size_t)(t + 2) * kstep;
;       const char* a3 = a2 + kstep; const char* b3 = b2 + kstep;
;       const int xa2 = (last ? nxt.lda : cur.lda) * 2, xb2 = (last ? nxt.ldb : cur.ldb) * 2;
;       const size_t xhA = (size_t)HALF * xa2, xhB = (size_t)HALF * xb2;
;       PG8_LDB(B0, 0, 0); PG8_SCHED; PG8_LDA(At, 0, 0); PG8_STA(PG8_SA(1, 1), a1 + hA, la2);
;       PG8_WAIT_L(8); PG8_BAR; PG8_WAIT_L(0); PG8_MMA(0, 0, At, B0); PG8_BAR; PG8_SCHED;
;       PG8_LDB(B1, 0, 1); PG8_STB(PG8_SB(0, 0), b2, xb2);
;       PG8_BAR; PG8_WAIT_L(0); PG8_MMA(0, 1, At, B1); PG8_BAR;
;       PG8_LDA(At, 0, 1); PG8_STA(PG8_SA(0, 0), a2, xa2);
;       PG8_BAR; PG8_WAIT_L(0); PG8_MMA(1, 0, At, B0); PG8_BAR; PG8_SCHED;
.LBB0_933:
	s_add_i32 s53, s40, 2
	s_add_u32 s42, s36, 0x80
	s_addc_u32 s41, s37, 0
	s_cmp_eq_u32 vcc_lo, s40
	s_cselect_b32 s41, s1, s41
	s_cselect_b32 s40, s0, s42
	s_cselect_b32 s42, s4, s20
	s_cselect_b32 s43, s87, s63
	s_cselect_b32 s45, s27, s52
	s_cselect_b32 s44, s26, vcc_hi
	s_add_i32 s64, 0, 0x10000
	v_add_u32_e32 v158, s64, v143
	ds_read_b128 v[146:149], v158
	ds_read_b128 v[150:153], v158 offset:1024
	ds_read_b128 v[154:157], v158 offset:2048
	ds_read_b128 v[158:161], v158 offset:3072
	s_lshl_b32 s50, s42, 1
	s_lshl_b32 s46, s43, 1
	s_ashr_i32 s51, s50, 31
	s_ashr_i32 s47, s46, 31
	s_lshl_b64 s[42:43], s[50:51], 7
	v_lshl_add_u64 v[190:191], s[36:37], 0, v[138:139]
	s_add_i32 m0, s49, 0xc000
	ds_read_b128 v[162:165], v145
	ds_read_b128 v[166:169], v145 offset:1024
	ds_read_b128 v[170:173], v145 offset:2048
	ds_read_b128 v[174:177], v145 offset:3072
	ds_read_b128 v[178:181], v145 offset:4096
	ds_read_b128 v[182:185], v145 offset:5120
	ds_read_b128 v[186:189], v145 offset:6144
	ds_read_b128 v[210:213], v145 offset:7168
	global_load_lds_dwordx4 v[190:191], off
	v_lshl_add_u64 v[190:191], s[36:37], 0, v[140:141]
	s_add_i32 m0, s49, 0xe000
	s_nop 0
	global_load_lds_dwordx4 v[190:191], off
	s_waitcnt lgkmcnt(8)
	s_barrier
	s_waitcnt lgkmcnt(0)
	s_waitcnt lgkmcnt(0)
	v_mfma_f32_16x16x32_bf16 v[124:127], v[146:149], v[162:165], v[124:127]
	v_mfma_f32_16x16x32_bf16 v[120:123], v[154:157], v[162:165], v[120:123]
	v_mfma_f32_16x16x32_bf16 v[116:119], v[146:149], v[170:173], v[116:119]
	v_mfma_f32_16x16x32_bf16 v[112:115], v[154:157], v[170:173], v[112:115]
	v_mfma_f32_16x16x32_bf16 v[108:111], v[146:149], v[178:181], v[108:111]
	v_mfma_f32_16x16x32_bf16 v[104:107], v[154:157], v[178:181], v[104:107]
	v_mfma_f32_16x16x32_bf16 v[100:103], v[146:149], v[186:189], v[100:103]
	v_mfma_f32_16x16x32_bf16 v[92:95], v[154:157], v[186:189], v[92:95]
	v_mfma_f32_16x16x32_bf16 v[124:127], v[150:153], v[166:169], v[124:127]
	v_mfma_f32_16x16x32_bf16 v[120:123], v[158:161], v[166:169], v[120:123]
	v_mfma_f32_16x16x32_bf16 v[116:119], v[150:153], v[174:177], v[116:119]
	v_mfma_f32_16x16x32_bf16 v[112:115], v[158:161], v[174:177], v[112:115]
	v_mfma_f32_16x16x32_bf16 v[108:111], v[150:153], v[182:185], v[108:111]
	v_mfma_f32_16x16x32_bf16 v[104:107], v[158:161], v[182:185], v[104:107]
	v_mfma_f32_16x16x32_bf16 v[100:103], v[150:153], v[210:213], v[100:103]
	v_mfma_f32_16x16x32_bf16 v[92:95], v[158:161], v[210:213], v[92:95]
	s_barrier
	s_add_i32 s65, 0, 0x14000
	v_add_u32_e32 v190, s65, v143
	s_add_i32 s51, s64, s34
	ds_read_b128 v[214:217], v190
	ds_read_b128 v[234:237], v190 offset:1024
	ds_read_b128 v[238:241], v190 offset:2048
	ds_read_b128 v[242:245], v190 offset:3072
	v_mad_u64_u32 v[190:191], s[56:57], s46, v135, v[128:129]
	s_mov_b32 m0, s51
	v_mad_u64_u32 v[194:195], s[56:57], s46, v137, v[130:131]
	global_load_lds_dwordx4 v190, s[44:45]
	s_add_i32 m0, s51, 0x2000
	v_mov_b32_e32 v191, v221
	global_load_lds_dwordx4 v194, s[44:45]
	s_barrier
	s_waitcnt lgkmcnt(0)
	v_mov_b32_e32 v195, v221
	v_lshl_add_u64 v[200:201], s[44:45], 0, v[190:191]
	v_lshl_add_u64 v[202:203], s[44:45], 0, v[194:195]
	s_waitcnt lgkmcnt(0)
	v_mfma_f32_16x16x32_bf16 v[96:99], v[214:217], v[162:165], v[96:99]
	v_mfma_f32_16x16x32_bf16 v[88:91], v[238:241], v[162:165], v[88:91]
	v_mfma_f32_16x16x32_bf16 v[84:87], v[214:217], v[170:173], v[84:87]
	v_mfma_f32_16x16x32_bf16 v[80:83], v[238:241], v[170:173], v[80:83]
	v_mfma_f32_16x16x32_bf16 v[76:79], v[214:217], v[178:181], v[76:79]
	v_mfma_f32_16x16x32_bf16 v[72:75], v[238:241], v[178:181], v[72:75]
	v_mfma_f32_16x16x32_bf16 v[68:71], v[214:217], v[186:189], v[68:71]
	v_mfma_f32_16x16x32_bf16 v[64:67], v[238:241], v[186:189], v[64:67]
	v_mfma_f32_16x16x32_bf16 v[96:99], v[234:237], v[166:169], v[96:99]
	v_mfma_f32_16x16x32_bf16 v[88:91], v[242:245], v[166:169], v[88:91]
	v_mfma_f32_16x16x32_bf16 v[84:87], v[234:237], v[174:177], v[84:87]
	v_mfma_f32_16x16x32_bf16 v[80:83], v[242:245], v[174:177], v[80:83]
	v_mfma_f32_16x16x32_bf16 v[76:79], v[234:237], v[182:185], v[76:79]
	v_mfma_f32_16x16x32_bf16 v[72:75], v[242:245], v[182:185], v[72:75]
	v_mfma_f32_16x16x32_bf16 v[68:71], v[234:237], v[210:213], v[68:71]
	v_mfma_f32_16x16x32_bf16 v[64:67], v[242:245], v[210:213], v[64:67]
	s_mov_b32 m0, s49
	v_mad_u64_u32 v[208:209], s[56:57], s50, v129, v[128:129]
	s_barrier
	ds_read_b128 v[162:165], v145 offset:16384
	ds_read_b128 v[166:169], v145 offset:17408
	ds_read_b128 v[170:173], v145 offset:18432
	ds_read_b128 v[174:177], v145 offset:19456
	ds_read_b128 v[178:181], v145 offset:20480
	ds_read_b128 v[182:185], v145 offset:21504
	ds_read_b128 v[186:189], v145 offset:22528
	ds_read_b128 v[210:213], v145 offset:23552
	global_load_lds_dwordx4 v208, s[40:41]
	v_mad_u64_u32 v[218:219], s[50:51], s50, v131, v[130:131]
	s_mov_b32 m0, s60
	v_mov_b32_e32 v209, v221
	global_load_lds_dwordx4 v218, s[40:41]
	s_barrier
	s_waitcnt lgkmcnt(0)
	v_mov_b32_e32 v219, v221
	v_lshl_add_u64 v[222:223], s[40:41], 0, v[208:209]
	v_lshl_add_u64 v[246:247], s[40:41], 0, v[218:219]
	s_waitcnt lgkmcnt(0)
	v_mfma_f32_16x16x32_bf16 v[60:63], v[146:149], v[162:165], v[60:63]
	s_lshl_b64 s[46:47], s[46:47], 7
	v_mfma_f32_16x16x32_bf16 v[56:59], v[154:157], v[162:165], v[56:59]
	v_mfma_f32_16x16x32_bf16 v[52:55], v[146:149], v[170:173], v[52:55]
	v_mfma_f32_16x16x32_bf16 v[48:51], v[154:157], v[170:173], v[48:51]
	v_mfma_f32_16x16x32_bf16 v[44:47], v[146:149], v[178:181], v[44:47]
	v_mfma_f32_16x16x32_bf16 v[40:43], v[154:157], v[178:181], v[40:43]
	v_mfma_f32_16x16x32_bf16 v[32:35], v[146:149], v[186:189], v[32:35]
	v_mfma_f32_16x16x32_bf16 v[24:27], v[154:157], v[186:189], v[24:27]
	v_mfma_f32_16x16x32_bf16 v[60:63], v[150:153], v[166:169], v[60:63]
	v_mfma_f32_16x16x32_bf16 v[56:59], v[158:161], v[166:169], v[56:59]
	v_mfma_f32_16x16x32_bf16 v[52:55], v[150:153], v[174:177], v[52:55]
	v_mfma_f32_16x16x32_bf16 v[48:51], v[158:161], v[174:177], v[48:51]
	v_mfma_f32_16x16x32_bf16 v[44:47], v[150:153], v[182:185], v[44:47]
	v_mfma_f32_16x16x32_bf16 v[40:43], v[158:161], v[182:185], v[40:43]
	v_mfma_f32_16x16x32_bf16 v[32:35], v[150:153], v[210:213], v[32:35]
	v_mfma_f32_16x16x32_bf16 v[24:27], v[158:161], v[210:213], v[24:27]
	s_barrier
; #define PG8_LDA(dst, b, h) do { _Pragma("unroll") for (int m = 0; m < 4; ++m) _Pragma("unroll") for (int k = 0; k < 2; ++k) dst[m][k] = *(const LAS bf16x8*)(lds + PG8_SA(b, h) + aoff + m * 2048 + k * 1024); } while (0)
; #define PG8_LDB(dst, b, h) do { _Pragma("unroll") for (int n = 0; n < 2; ++n) _Pragma("unroll") for (int k = 0; k < 2; ++k) dst[n][k] = *(const LAS bf16x8*)(lds + PG8_SB(b, h) + boff + n * 2048 + k * 1024); } while (0)
; #define PG8_MMA(ai, bj, At, Bt_) do { __builtin_amdgcn_s_setprio(1); _Pragma("unroll") for (int m = 0; m < 4; ++m) _Pragma("unroll") for (int n = 0; n < 2; ++n) _Pragma("unroll") for (int k = 0; k < 2; ++k) \
;     acc[ai][bj][m][n] = __builtin_amdgcn_mfma_f32_16x16x32_bf16(Bt_[n][k], At[m][k], acc[ai][bj][m][n], 0, 0, 0); __builtin_amdgcn_s_setprio(0); } while (0)
; #define PG8_WAIT_V(n) asm volatile("s_waitcnt vmcnt(" #n ")" ::: "memory")
; #define PG8_WAIT_L(n) asm volatile("s_waitcnt lgkmcnt(" #n ")" ::: "memory")
; #define PG8_BAR __builtin_amdgcn_s_barrier()
; #define PG8_SCHED __builtin_amdgcn_sched_barrier(0)
; #define PG8_STA(bufoff, gbase, ld2) PG8_STAGE3(bufoff, gbase, ld2, R0, R1)
; #define PG8_STB(bufoff, gbase, ld2) PG8_STAGE3(bufoff, gbase, ld2, Rb0, Rb1)
; #define PG8_LDA(dst, b, h) do { _Pragma("unroll") for (int m = 0; m < 4; ++m) _Pragma("unroll") for (int k = 0; k < 2; ++k) dst[m][k] = *(const LAS bf16x8*)(lds + PG8_SA(b, h) + aoff + m * 2048 + k * 1024); } while (0)
; #define PG8_LDB(dst, b, h) do { _Pragma("unroll") for (int n = 0; n < 2; ++n) _Pragma("unroll") for (int k = 0; k < 2; ++k) dst[n][k] = *(const LAS bf16x8*)(lds + PG8_SB(b, h) + boff + n * 2048 + k * 1024); } while (0)
; #define PG8_WAIT_V(n) asm volatile("s_waitcnt vmcnt(" #n ")" ::: "memory")
; template <class Sched, class Epi>
; DI void gemm_stream(char* smem, const Sched& S_, const Epi& E) {
;     ...
;       PG8_STB(PG8_SB(0, 1), b2 + xhB, xb2);
;       PG8_WAIT_V(6); PG8_BAR; PG8_MMA(1, 1, At, B1); PG8_BAR;
;       PG8_LDB(B0, 1, 0); PG8_SCHED; PG8_LDA(At, 1, 0); PG8_STA(PG8_SA(0, 1), a2 + xhA, xa2);
;       PG8_WAIT_L(8); PG8_BAR; PG8_WAIT_L(0); PG8_MMA(0, 0, At, B0); PG8_BAR; PG8_SCHED;
;       PG8_LDB(B1, 1, 1); PG8_STB(PG8_SB(1, 0), b3, xb2);
;       PG8_BAR; PG8_WAIT_L(0); PG8_MMA(0, 1, At, B1); PG8_BAR;
;       PG8_LDA(At, 1, 1); PG8_STA(PG8_SA(1, 0), a3, xa2);
;       PG8_BAR; PG8_WAIT_L(0); PG8_MMA(1, 0, At, B0); PG8_BAR; PG8_SCHED;
	s_add_u32 s44, s44, s46
	s_addc_u32 s45, s45, s47
	s_add_i32 s46, s65, s34
	s_mov_b32 m0, s46
	s_nop 0
	global_load_lds_dwordx4 v190, s[44:45]
	s_add_i32 m0, s46, 0x2000
	v_lshl_add_u64 v[190:191], s[44:45], 0, v[190:191]
	global_load_lds_dwordx4 v194, s[44:45]
	s_waitcnt vmcnt(6)
	v_lshl_add_u64 v[194:195], s[44:45], 0, v[194:195]
	s_barrier
	v_mfma_f32_16x16x32_bf16 v[36:39], v[214:217], v[162:165], v[36:39]
	v_mfma_f32_16x16x32_bf16 v[28:31], v[238:241], v[162:165], v[28:31]
	v_mfma_f32_16x16x32_bf16 v[20:23], v[214:217], v[170:173], v[20:23]
	v_mfma_f32_16x16x32_bf16 v[16:19], v[238:241], v[170:173], v[16:19]
	v_mfma_f32_16x16x32_bf16 v[12:15], v[214:217], v[178:181], v[12:15]
	v_mfma_f32_16x16x32_bf16 v[8:11], v[238:241], v[178:181], v[8:11]
	v_mfma_f32_16x16x32_bf16 v[4:7], v[214:217], v[186:189], v[4:7]
	v_mfma_f32_16x16x32_bf16 v[0:3], v[238:241], v[186:189], v[0:3]
	v_mfma_f32_16x16x32_bf16 v[36:39], v[234:237], v[166:169], v[36:39]
	v_mfma_f32_16x16x32_bf16 v[28:31], v[242:245], v[166:169], v[28:31]
	v_mfma_f32_16x16x32_bf16 v[20:23], v[234:237], v[174:177], v[20:23]
	v_mfma_f32_16x16x32_bf16 v[16:19], v[242:245], v[174:177], v[16:19]
	v_mfma_f32_16x16x32_bf16 v[12:15], v[234:237], v[182:185], v[12:15]
	v_mfma_f32_16x16x32_bf16 v[8:11], v[242:245], v[182:185], v[8:11]
	v_mfma_f32_16x16x32_bf16 v[4:7], v[234:237], v[210:213], v[4:7]
	v_mfma_f32_16x16x32_bf16 v[0:3], v[242:245], v[210:213], v[0:3]
	s_add_i32 s44, 0, 0x18000
	v_add_u32_e32 v158, s44, v143
	s_barrier
	ds_read_b128 v[146:149], v158
	ds_read_b128 v[150:153], v158 offset:1024
	ds_read_b128 v[154:157], v158 offset:2048
	ds_read_b128 v[158:161], v158 offset:3072
	s_add_u32 s40, s40, s42
	s_addc_u32 s41, s41, s43
	s_mov_b32 m0, s89
	ds_read_b128 v[162:165], v145 offset:32768
	ds_read_b128 v[166:169], v145 offset:33792
	ds_read_b128 v[170:173], v145 offset:34816
	ds_read_b128 v[174:177], v145 offset:35840
	ds_read_b128 v[178:181], v145 offset:36864
	ds_read_b128 v[182:185], v145 offset:37888
	ds_read_b128 v[186:189], v145 offset:38912
	ds_read_b128 v[210:213], v145 offset:39936
	global_load_lds_dwordx4 v208, s[40:41]
	s_mov_b32 m0, s90
	s_nop 0
	global_load_lds_dwordx4 v218, s[40:41]
	s_waitcnt lgkmcnt(8)
	s_barrier
	s_waitcnt lgkmcnt(0)
	s_waitcnt lgkmcnt(0)
	v_mfma_f32_16x16x32_bf16 v[124:127], v[146:149], v[162:165], v[124:127]
	v_mfma_f32_16x16x32_bf16 v[120:123], v[154:157], v[162:165], v[120:123]
	v_mfma_f32_16x16x32_bf16 v[116:119], v[146:149], v[170:173], v[116:119]
	v_mfma_f32_16x16x32_bf16 v[112:115], v[154:157], v[170:173], v[112:115]
	v_mfma_f32_16x16x32_bf16 v[108:111], v[146:149], v[178:181], v[108:111]
	v_mfma_f32_16x16x32_bf16 v[104:107], v[154:157], v[178:181], v[104:107]
	v_mfma_f32_16x16x32_bf16 v[100:103], v[146:149], v[186:189], v[100:103]
	v_mfma_f32_16x16x32_bf16 v[92:95], v[154:157], v[186:189], v[92:95]
	v_mfma_f32_16x16x32_bf16 v[124:127], v[150:153], v[166:169], v[124:127]
	v_mfma_f32_16x16x32_bf16 v[120:123], v[158:161], v[166:169], v[120:123]
	v_mfma_f32_16x16x32_bf16 v[116:119], v[150:153], v[174:177], v[116:119]
	v_mfma_f32_16x16x32_bf16 v[112:115], v[158:161], v[174:177], v[112:115]
	v_mfma_f32_16x16x32_bf16 v[108:111], v[150:153], v[182:185], v[108:111]
	v_mfma_f32_16x16x32_bf16 v[104:107], v[158:161], v[182:185], v[104:107]
	v_mfma_f32_16x16x32_bf16 v[100:103], v[150:153], v[210:213], v[100:103]
	v_mfma_f32_16x16x32_bf16 v[92:95], v[158:161], v[210:213], v[92:95]
	s_barrier
	s_add_i32 s40, 0, 0x1c000
	s_add_i32 s41, s44, s34
	v_add_u32_e32 v204, s40, v143
	v_lshl_add_u64 v[200:201], v[200:201], 0, s[58:59]
	s_mov_b32 m0, s41
	ds_read_b128 v[214:217], v204
	ds_read_b128 v[234:237], v204 offset:1024
	ds_read_b128 v[238:241], v204 offset:2048
	ds_read_b128 v[242:245], v204 offset:3072
	global_load_lds_dwordx4 v[200:201], off
	v_lshl_add_u64 v[200:201], v[202:203], 0, s[58:59]
	s_add_i32 m0, s41, 0x2000
	s_nop 0
	global_load_lds_dwordx4 v[200:201], off
	s_barrier
	s_waitcnt lgkmcnt(0)
	s_waitcnt lgkmcnt(0)
	v_mfma_f32_16x16x32_bf16 v[96:99], v[214:217], v[162:165], v[96:99]
	v_mfma_f32_16x16x32_bf16 v[88:91], v[238:241], v[162:165], v[88:91]
	v_mfma_f32_16x16x32_bf16 v[84:87], v[214:217], v[170:173], v[84:87]
	v_mfma_f32_16x16x32_bf16 v[80:83], v[238:241], v[170:173], v[80:83]
	v_mfma_f32_16x16x32_bf16 v[76:79], v[214:217], v[178:181], v[76:79]
	v_mfma_f32_16x16x32_bf16 v[72:75], v[238:241], v[178:181], v[72:75]
	v_mfma_f32_16x16x32_bf16 v[68:71], v[214:217], v[186:189], v[68:71]
	v_mfma_f32_16x16x32_bf16 v[64:67], v[238:241], v[186:189], v[64:67]
	v_mfma_f32_16x16x32_bf16 v[96:99], v[234:237], v[166:169], v[96:99]
	v_mfma_f32_16x16x32_bf16 v[88:91], v[242:245], v[166:169], v[88:91]
	v_mfma_f32_16x16x32_bf16 v[84:87], v[234:237], v[174:177], v[84:87]
	v_mfma_f32_16x16x32_bf16 v[80:83], v[242:245], v[174:177], v[80:83]
	v_mfma_f32_16x16x32_bf16 v[76:79], v[234:237], v[182:185], v[76:79]
	v_mfma_f32_16x16x32_bf16 v[72:75], v[242:245], v[182:185], v[72:75]
	v_mfma_f32_16x16x32_bf16 v[68:71], v[234:237], v[210:213], v[68:71]
	v_mfma_f32_16x16x32_bf16 v[64:67], v[242:245], v[210:213], v[64:67]
	s_mov_b32 m0, s9
	v_lshl_add_u64 v[200:201], v[222:223], 0, s[58:59]
	s_barrier
	ds_read_b128 v[162:165], v145 offset:49152
	ds_read_b128 v[166:169], v145 offset:50176
	ds_read_b128 v[170:173], v145 offset:51200
	ds_read_b128 v[174:177], v145 offset:52224
	ds_read_b128 v[178:181], v145 offset:53248
	ds_read_b128 v[182:185], v145 offset:54272
	ds_read_b128 v[186:189], v145 offset:55296
	ds_read_b128 v[210:213], v145 offset:56320
	global_load_lds_dwordx4 v[200:201], off
	v_lshl_add_u64 v[200:201], v[246:247], 0, s[58:59]
	s_mov_b32 m0, s88
	s_nop 0
	global_load_lds_dwordx4 v[200:201], off
	s_barrier
; #define PG8_MMA(ai, bj, At, Bt_) do { __builtin_amdgcn_s_setprio(1); _Pragma("unroll") for (int m = 0; m < 4; ++m) _Pragma("unroll") for (int n = 0; n < 2; ++n) _Pragma("unroll") for (int k = 0; k < 2; ++k) \
;     acc[ai][bj][m][n] = __builtin_amdgcn_mfma_f32_16x16x32_bf16(Bt_[n][k], At[m][k], acc[ai][bj][m][n], 0, 0, 0); __builtin_amdgcn_s_setprio(0); } while (0)
; #define PG8_WAIT_V(n) asm volatile("s_waitcnt vmcnt(" #n ")" ::: "memory")
; #define PG8_WAIT_L(n) asm volatile("s_waitcnt lgkmcnt(" #n ")" ::: "memory")
; #define PG8_BAR __builtin_amdgcn_s_barrier()
; #define PG8_SCHED __builtin_amdgcn_sched_barrier(0)
; DI u32x4 pack8v(const f32x4& a, const f32x4& b) { u32x4 w; w.x = pk2(a[0], a[1]); w.y = pk2(a[2], a[3]); w.z = pk2(b[0], b[1]); w.w = pk2(b[2], b[3]); return w; }
; #define PG8_STB(bufoff, gbase, ld2) PG8_STAGE3(bufoff, gbase, ld2, Rb0, Rb1)
; #define PG8_MMA(ai, bj, At, Bt_) do { __builtin_amdgcn_s_setprio(1); _Pragma("unroll") for (int m = 0; m < 4; ++m) _Pragma("unroll") for (int n = 0; n < 2; ++n) _Pragma("unroll") for (int k = 0; k < 2; ++k) \
;     acc[ai][bj][m][n] = __builtin_amdgcn_mfma_f32_16x16x32_bf16(Bt_[n][k], At[m][k], acc[ai][bj][m][n], 0, 0, 0); __builtin_amdgcn_s_setprio(0); } while (0)
; #define PG8_WAIT_V(n) asm volatile("s_waitcnt vmcnt(" #n ")" ::: "memory")
; #define PG8_WAIT_L(n) asm volatile("s_waitcnt lgkmcnt(" #n ")" ::: "memory")
; #define PG8_BAR __builtin_amdgcn_s_barrier()
; #define PG8_SCHED __builtin_amdgcn_sched_barrier(0)
; template <class Sched, class Epi>
; DI void gemm_stream(char* smem, const Sched& S_, const Epi& E) {
;     ...
;       PG8_BAR; PG8_WAIT_L(0); PG8_MMA(1, 0, At, B0); PG8_BAR; PG8_SCHED;
;       PG8_STB(PG8_SB(1, 1), b3 + xhB, xb2);
;       PG8_WAIT_V(6); PG8_BAR; PG8_MMA(1, 1, At, B1); PG8_BAR;
;     }
;   DI void operator()(const acc_t& acc, const Desc& u, int wr, int wc, int fr, int fq) const {
;     ...
;     } else if (u.kind == 1) {
; #pragma unroll
;       for (int ai = 0; ai < 2; ++ai)
; #pragma unroll
;         for (int m = 0; m < 4; ++m) { const int tl = row0 + ai * HALF + m * 16, bl = tl / S, s = tl - bl * S;
; #pragma unroll
;           for (int bj = 0; bj < 2; ++bj) { const int c = u.pn * BM + bj * HALF + wc * 32 + 8 * fq, head = c >> 6, j = c & 63;
;             *(u32x4*)(Kb + ((size_t)(bl * 8 + head) * S + s) * 96 + j) = pack8v(acc[ai][bj][m][0], acc[ai][bj][m][1]); } }
	s_waitcnt lgkmcnt(0)
	s_waitcnt lgkmcnt(0)
	v_mfma_f32_16x16x32_bf16 v[60:63], v[146:149], v[162:165], v[60:63]
	v_mfma_f32_16x16x32_bf16 v[56:59], v[154:157], v[162:165], v[56:59]
	v_mfma_f32_16x16x32_bf16 v[52:55], v[146:149], v[170:173], v[52:55]
	v_mfma_f32_16x16x32_bf16 v[48:51], v[154:157], v[170:173], v[48:51]
	v_mfma_f32_16x16x32_bf16 v[44:47], v[146:149], v[178:181], v[44:47]
	v_mfma_f32_16x16x32_bf16 v[40:43], v[154:157], v[178:181], v[40:43]
	v_mfma_f32_16x16x32_bf16 v[32:35], v[146:149], v[186:189], v[32:35]
	v_mfma_f32_16x16x32_bf16 v[24:27], v[154:157], v[186:189], v[24:27]
	v_mfma_f32_16x16x32_bf16 v[60:63], v[150:153], v[166:169], v[60:63]
	v_mfma_f32_16x16x32_bf16 v[56:59], v[158:161], v[166:169], v[56:59]
	v_mfma_f32_16x16x32_bf16 v[52:55], v[150:153], v[174:177], v[52:55]
	v_mfma_f32_16x16x32_bf16 v[48:51], v[158:161], v[174:177], v[48:51]
	v_mfma_f32_16x16x32_bf16 v[44:47], v[150:153], v[182:185], v[44:47]
	v_mfma_f32_16x16x32_bf16 v[40:43], v[158:161], v[182:185], v[40:43]
	v_mfma_f32_16x16x32_bf16 v[32:35], v[150:153], v[210:213], v[32:35]
	v_mfma_f32_16x16x32_bf16 v[24:27], v[158:161], v[210:213], v[24:27]
	s_barrier
	s_add_i32 s40, s40, s34
	v_lshl_add_u64 v[146:147], v[190:191], 0, s[58:59]
	s_mov_b32 m0, s40
	s_nop 0
	global_load_lds_dwordx4 v[146:147], off
	v_lshl_add_u64 v[146:147], v[194:195], 0, s[58:59]
	s_add_i32 m0, s40, 0x2000
	s_nop 0
	global_load_lds_dwordx4 v[146:147], off
	s_waitcnt vmcnt(6)
	s_barrier
	v_mfma_f32_16x16x32_bf16 v[36:39], v[214:217], v[162:165], v[36:39]
	v_mfma_f32_16x16x32_bf16 v[28:31], v[238:241], v[162:165], v[28:31]
	v_mfma_f32_16x16x32_bf16 v[20:23], v[214:217], v[170:173], v[20:23]
	v_mfma_f32_16x16x32_bf16 v[16:19], v[238:241], v[170:173], v[16:19]
	v_mfma_f32_16x16x32_bf16 v[12:15], v[214:217], v[178:181], v[12:15]
	v_mfma_f32_16x16x32_bf16 v[8:11], v[238:241], v[178:181], v[8:11]
	v_mfma_f32_16x16x32_bf16 v[4:7], v[214:217], v[186:189], v[4:7]
	v_mfma_f32_16x16x32_bf16 v[0:3], v[238:241], v[186:189], v[0:3]
	v_mfma_f32_16x16x32_bf16 v[36:39], v[234:237], v[166:169], v[36:39]
	v_mfma_f32_16x16x32_bf16 v[28:31], v[242:245], v[166:169], v[28:31]
	v_mfma_f32_16x16x32_bf16 v[20:23], v[234:237], v[174:177], v[20:23]
	v_mfma_f32_16x16x32_bf16 v[16:19], v[242:245], v[174:177], v[16:19]
	v_mfma_f32_16x16x32_bf16 v[12:15], v[234:237], v[182:185], v[12:15]
	v_mfma_f32_16x16x32_bf16 v[8:11], v[242:245], v[182:185], v[8:11]
	v_mfma_f32_16x16x32_bf16 v[4:7], v[234:237], v[210:213], v[4:7]
	v_mfma_f32_16x16x32_bf16 v[0:3], v[242:245], v[210:213], v[0:3]
	s_add_u32 s36, s36, 0x100
	s_addc_u32 s37, s37, 0
	s_add_u32 vcc_hi, vcc_hi, 0x100
	s_addc_u32 s52, s52, 0
	s_cmp_ge_i32 s53, s5
	s_mov_b32 s40, s53
	s_barrier
	s_cbranch_scc0 .LBB0_933
	v_readlane_b32 s44, v252, 27
	v_lshl_add_u32 v138, s29, 8, v142
	s_mov_b64 s[42:43], -1
	s_mov_b64 s[36:37], 0
	s_cmp_lt_i32 s97, 1
	s_mov_b64 s[40:41], 0
	v_readlane_b32 s45, v252, 28
	s_movk_i32 s50, 0x100
	s_mov_b32 s51, 0x78787879
	s_cbranch_scc1 .LBB0_938
	s_cmp_eq_u32 s97, 1
	s_mov_b64 s[40:41], -1
	s_cbranch_scc0 .LBB0_937
	v_mul_hi_i32 v139, v138, s51
	v_lshrrev_b32_e32 v140, 31, v139
	v_ashrrev_i32_e32 v139, 11, v139
	s_lshl_b32 s5, s33, 8
	v_add_u32_e32 v139, v139, v140
	s_movk_i32 s29, 0xef00
	s_or_b32 s5, s5, s67
	v_mad_i32_i24 v140, v139, s29, v138
	v_lshlrev_b32_e32 v139, 3, v139
	s_ashr_i32 s5, s5, 6
	v_ashrrev_i32_e32 v141, 31, v140
	v_add_u32_e32 v150, s5, v139
	s_movk_i32 s42, 0x1100
	s_or_b32 s20, s5, 2
	v_mad_i64_i32 v[150:151], s[40:41], v150, s42, v[140:141]
	v_add_u32_e32 v139, s20, v139
	v_mad_u64_u32 v[152:153], s[40:41], v150, s17, v[132:133]
	v_mad_i64_i32 v[140:141], s[40:41], v139, s42, v[140:141]
	v_or_b32_e32 v139, 16, v138
	v_mad_i32_i24 v153, v151, s17, v153
	v_mad_u64_u32 v[150:151], s[40:41], v140, s17, v[132:133]
	v_mul_hi_i32 v140, v139, s51
	v_mad_i32_i24 v151, v141, s17, v151
	v_lshrrev_b32_e32 v141, 31, v140
	v_ashrrev_i32_e32 v140, 11, v140
	v_cvt_pk_bf16_f32 v146, v124, v125
	v_cvt_pk_bf16_f32 v147, v126, v127
	v_cvt_pk_bf16_f32 v148, v120, v121
	v_cvt_pk_bf16_f32 v149, v122, v123
	v_add_u32_e32 v141, v140, v141
	global_store_dwordx4 v[152:153], v[146:149], off
	v_mad_i32_i24 v140, v141, s29, v139
	v_lshlrev_b32_e32 v139, 3, v141
	v_cvt_pk_bf16_f32 v146, v96, v97
	v_cvt_pk_bf16_f32 v147, v98, v99
	v_cvt_pk_bf16_f32 v148, v88, v89
	v_cvt_pk_bf16_f32 v149, v90, v91
	global_store_dwordx4 v[150:151], v[146:149], off
	v_ashrrev_i32_e32 v141, 31, v140
	v_add_u32_e32 v150, s5, v139
	v_mad_i64_i32 v[150:151], s[40:41], v150, s42, v[140:141]
	v_add_u32_e32 v139, s20, v139
	v_mad_u64_u32 v[152:153], s[40:41], v150, s17, v[132:133]
	v_mad_i64_i32 v[140:141], s[40:41], v139, s42, v[140:141]
	v_or_b32_e32 v139, 32, v138
	v_mad_i32_i24 v153, v151, s17, v153
	v_mad_u64_u32 v[150:151], s[40:41], v140, s17, v[132:133]
	v_mul_hi_i32 v140, v139, s51
	v_mad_i32_i24 v151, v141, s17, v151
	v_lshrrev_b32_e32 v141, 31, v140
	v_ashrrev_i32_e32 v140, 11, v140
	v_cvt_pk_bf16_f32 v146, v116, v117
	v_cvt_pk_bf16_f32 v147, v118, v119
	v_cvt_pk_bf16_f32 v148, v112, v113
	v_cvt_pk_bf16_f32 v149, v114, v115
	v_add_u32_e32 v141, v140, v141
	global_store_dwordx4 v[152:153], v[146:149], off
	v_mad_i32_i24 v140, v141, s29, v139
	v_lshlrev_b32_e32 v139, 3, v141
	v_cvt_pk_bf16_f32 v146, v84, v85
	v_cvt_pk_bf16_f32 v147, v86, v87
	v_cvt_pk_bf16_f32 v148, v80, v81
	v_cvt_pk_bf16_f32 v149, v82, v83
	global_store_dwordx4 v[150:151], v[146:149], off
	v_ashrrev_i32_e32 v141, 31, v140
	v_add_u32_e32 v150, s5, v139
	v_mad_i64_i32 v[150:151], s[40:41], v150, s42, v[140:141]
	v_add_u32_e32 v139, s20, v139
	v_mad_u64_u32 v[152:153], s[40:41], v150, s17, v[132:133]
; DI u32x4 pack8v(const f32x4& a, const f32x4& b) { u32x4 w; w.x = pk2(a[0], a[1]); w.y = pk2(a[2], a[3]); w.z = pk2(b[0], b[1]); w.w = pk2(b[2], b[3]); return w; }
;   DI void operator()(const acc_t& acc, const Desc& u, int wr, int wc, int fr, int fq) const {
;     ...
;     } else if (u.kind == 1) {
; #pragma unroll
;       for (int ai = 0; ai < 2; ++ai)
; #pragma unroll
;         for (int m = 0; m < 4; ++m) { const int tl = row0 + ai * HALF + m * 16, bl = tl / S, s = tl - bl * S;
; #pragma unroll
;           for (int bj = 0; bj < 2; ++bj) { const int c = u.pn * BM + bj * HALF + wc * 32 + 8 * fq, head = c >> 6, j = c & 63;
;             *(u32x4*)(Kb + ((size_t)(bl * 8 + head) * S + s) * 96 + j) = pack8v(acc[ai][bj][m][0], acc[ai][bj][m][1]); } }
	v_mad_i64_i32 v[140:141], s[40:41], v139, s42, v[140:141]
	v_or_b32_e32 v139, 48, v138
	v_mad_i32_i24 v153, v151, s17, v153
	v_mad_u64_u32 v[150:151], s[40:41], v140, s17, v[132:133]
	v_mul_hi_i32 v140, v139, s51
	v_mad_i32_i24 v151, v141, s17, v151
	v_lshrrev_b32_e32 v141, 31, v140
	v_ashrrev_i32_e32 v140, 11, v140
	v_cvt_pk_bf16_f32 v146, v108, v109
	v_cvt_pk_bf16_f32 v147, v110, v111
	v_cvt_pk_bf16_f32 v148, v104, v105
	v_cvt_pk_bf16_f32 v149, v106, v107
	v_add_u32_e32 v141, v140, v141
	global_store_dwordx4 v[152:153], v[146:149], off
	v_mad_i32_i24 v140, v141, s29, v139
	v_lshlrev_b32_e32 v139, 3, v141
	v_cvt_pk_bf16_f32 v146, v76, v77
	v_cvt_pk_bf16_f32 v147, v78, v79
	v_cvt_pk_bf16_f32 v148, v72, v73
	v_cvt_pk_bf16_f32 v149, v74, v75
	global_store_dwordx4 v[150:151], v[146:149], off
	v_ashrrev_i32_e32 v141, 31, v140
	v_add_u32_e32 v150, s5, v139
	v_mad_i64_i32 v[150:151], s[40:41], v150, s42, v[140:141]
	v_add_u32_e32 v139, s20, v139
	v_mad_u64_u32 v[152:153], s[40:41], v150, s17, v[132:133]
	v_mad_i64_i32 v[140:141], s[40:41], v139, s42, v[140:141]
	v_add_u32_e32 v139, 0x80, v138
	v_mad_i32_i24 v153, v151, s17, v153
	v_mad_u64_u32 v[150:151], s[40:41], v140, s17, v[132:133]
	v_mul_hi_i32 v140, v139, s51
	v_mad_i32_i24 v151, v141, s17, v151
	v_lshrrev_b32_e32 v141, 31, v140
	v_ashrrev_i32_e32 v140, 11, v140
	v_cvt_pk_bf16_f32 v146, v100, v101
	v_cvt_pk_bf16_f32 v147, v102, v103
	v_cvt_pk_bf16_f32 v148, v92, v93
	v_cvt_pk_bf16_f32 v149, v94, v95
	v_add_u32_e32 v141, v140, v141
	global_store_dwordx4 v[152:153], v[146:149], off
	v_mad_i32_i24 v140, v141, s29, v139
	v_lshlrev_b32_e32 v139, 3, v141
	v_cvt_pk_bf16_f32 v146, v68, v69
	v_cvt_pk_bf16_f32 v147, v70, v71
	v_cvt_pk_bf16_f32 v148, v64, v65
	v_cvt_pk_bf16_f32 v149, v66, v67
	global_store_dwordx4 v[150:151], v[146:149], off
	v_ashrrev_i32_e32 v141, 31, v140
	v_add_u32_e32 v150, s5, v139
	v_mad_i64_i32 v[150:151], s[40:41], v150, s42, v[140:141]
	v_add_u32_e32 v139, s20, v139
	v_mad_u64_u32 v[152:153], s[40:41], v150, s17, v[132:133]
	v_mad_i64_i32 v[140:141], s[40:41], v139, s42, v[140:141]
	v_add_u32_e32 v139, 0x90, v138
	v_mad_i32_i24 v153, v151, s17, v153
	v_mad_u64_u32 v[150:151], s[40:41], v140, s17, v[132:133]
	v_mul_hi_i32 v140, v139, s51
	v_mad_i32_i24 v151, v141, s17, v151
	v_lshrrev_b32_e32 v141, 31, v140
	v_ashrrev_i32_e32 v140, 11, v140
	v_cvt_pk_bf16_f32 v146, v60, v61
	v_cvt_pk_bf16_f32 v147, v62, v63
	v_cvt_pk_bf16_f32 v148, v56, v57
	v_cvt_pk_bf16_f32 v149, v58, v59
	v_add_u32_e32 v141, v140, v141
	global_store_dwordx4 v[152:153], v[146:149], off
	v_mad_i32_i24 v140, v141, s29, v139
	v_lshlrev_b32_e32 v139, 3, v141
	v_cvt_pk_bf16_f32 v146, v36, v37
	v_cvt_pk_bf16_f32 v147, v38, v39
	v_cvt_pk_bf16_f32 v148, v28, v29
	v_cvt_pk_bf16_f32 v149, v30, v31
	global_store_dwordx4 v[150:151], v[146:149], off
	v_ashrrev_i32_e32 v141, 31, v140
	v_add_u32_e32 v150, s5, v139
	v_mad_i64_i32 v[150:151], s[40:41], v150, s42, v[140:141]
	v_add_u32_e32 v139, s20, v139
	v_mad_u64_u32 v[152:153], s[40:41], v150, s17, v[132:133]
	v_mad_i64_i32 v[140:141], s[40:41], v139, s42, v[140:141]
	v_add_u32_e32 v139, 0xa0, v138
	v_mad_i32_i24 v153, v151, s17, v153
	v_mad_u64_u32 v[150:151], s[40:41], v140, s17, v[132:133]
	v_mul_hi_i32 v140, v139, s51
	v_mad_i32_i24 v151, v141, s17, v151
	v_lshrrev_b32_e32 v141, 31, v140
	v_ashrrev_i32_e32 v140, 11, v140
	v_cvt_pk_bf16_f32 v146, v52, v53
	v_cvt_pk_bf16_f32 v147, v54, v55
	v_cvt_pk_bf16_f32 v148, v48, v49
	v_cvt_pk_bf16_f32 v149, v50, v51
	v_add_u32_e32 v141, v140, v141
	global_store_dwordx4 v[152:153], v[146:149], off
	v_mad_i32_i24 v140, v141, s29, v139
	v_lshlrev_b32_e32 v139, 3, v141
	v_cvt_pk_bf16_f32 v146, v20, v21
	v_cvt_pk_bf16_f32 v147, v22, v23
	v_cvt_pk_bf16_f32 v148, v16, v17
	v_cvt_pk_bf16_f32 v149, v18, v19
	global_store_dwordx4 v[150:151], v[146:149], off
	v_ashrrev_i32_e32 v141, 31, v140
	v_add_u32_e32 v150, s5, v139
	v_mad_i64_i32 v[150:151], s[40:41], v150, s42, v[140:141]
	v_add_u32_e32 v139, s20, v139
	v_mad_u64_u32 v[152:153], s[40:41], v150, s17, v[132:133]
	v_mad_i64_i32 v[140:141], s[40:41], v139, s42, v[140:141]
	v_add_u32_e32 v139, 0xb0, v138
	v_mad_i32_i24 v153, v151, s17, v153
	v_mad_u64_u32 v[150:151], s[40:41], v140, s17, v[132:133]
	v_mul_hi_i32 v140, v139, s51
	v_mad_i32_i24 v151, v141, s17, v151
	v_lshrrev_b32_e32 v141, 31, v140
	v_ashrrev_i32_e32 v140, 11, v140
	v_cvt_pk_bf16_f32 v146, v44, v45
	v_cvt_pk_bf16_f32 v147, v46, v47
	v_cvt_pk_bf16_f32 v148, v40, v41
	v_cvt_pk_bf16_f32 v149, v42, v43
	v_add_u32_e32 v141, v140, v141
	global_store_dwordx4 v[152:153], v[146:149], off
	v_mad_i32_i24 v140, v141, s29, v139
	v_lshlrev_b32_e32 v139, 3, v141
	v_cvt_pk_bf16_f32 v146, v12, v13
	v_cvt_pk_bf16_f32 v147, v14, v15
	v_cvt_pk_bf16_f32 v148, v8, v9
	v_cvt_pk_bf16_f32 v149, v10, v11
	global_store_dwordx4 v[150:151], v[146:149], off
	v_ashrrev_i32_e32 v141, 31, v140
	v_add_u32_e32 v150, s5, v139
	v_mad_i64_i32 v[150:151], s[40:41], v150, s42, v[140:141]
	v_add_u32_e32 v139, s20, v139
	v_mad_u64_u32 v[152:153], s[40:41], v150, s17, v[132:133]
	v_mad_i64_i32 v[140:141], s[40:41], v139, s42, v[140:141]
	v_cvt_pk_bf16_f32 v146, v32, v33
	v_cvt_pk_bf16_f32 v147, v34, v35
	v_cvt_pk_bf16_f32 v148, v24, v25
	v_cvt_pk_bf16_f32 v149, v26, v27
	v_mad_i32_i24 v153, v151, s17, v153
	v_mad_u64_u32 v[150:151], s[40:41], v140, s17, v[132:133]
	global_store_dwordx4 v[152:153], v[146:149], off
	v_mad_i32_i24 v151, v141, s17, v151
	s_movk_i32 s80, 0xef00
	v_cvt_pk_bf16_f32 v146, v4, v5
	v_cvt_pk_bf16_f32 v147, v6, v7
	v_cvt_pk_bf16_f32 v148, v0, v1
	v_cvt_pk_bf16_f32 v149, v2, v3
	global_store_dwordx4 v[150:151], v[146:149], off
	s_mov_b64 s[40:41], 0

; #define PG8_LDA(dst, b, h) do { _Pragma("unroll") for (int m = 0; m < 4; ++m) _Pragma("unroll") for (int k = 0; k < 2; ++k) dst[m][k] = *(const LAS bf16x8*)(lds + PG8_SA(b, h) + aoff + m * 2048 + k * 1024); } while (0)
; #define PG8_LDB(dst, b, h) do { _Pragma("unroll") for (int n = 0; n < 2; ++n) _Pragma("unroll") for (int k = 0; k < 2; ++k) dst[n][k] = *(const LAS bf16x8*)(lds + PG8_SB(b, h) + boff + n * 2048 + k * 1024); } while (0)
; #define PG8_MMA(ai, bj, At, Bt_) do { __builtin_amdgcn_s_setprio(1); _Pragma("unroll") for (int m = 0; m < 4; ++m) _Pragma("unroll") for (int n = 0; n < 2; ++n) _Pragma("unroll") for (int k = 0; k < 2; ++k) \
;     acc[ai][bj][m][n] = __builtin_amdgcn_mfma_f32_16x16x32_bf16(Bt_[n][k], At[m][k], acc[ai][bj][m][n], 0, 0, 0); __builtin_amdgcn_s_setprio(0); } while (0)
; #define PG8_WAIT_L(n) asm volatile("s_waitcnt lgkmcnt(" #n ")" ::: "memory")
; #define PG8_BAR __builtin_amdgcn_s_barrier()
; #define PG8_SCHED __builtin_amdgcn_sched_barrier(0)
; #define PG8_STA(bufoff, gbase, ld2) PG8_STAGE3(bufoff, gbase, ld2, R0, R1)
; #define PG8_STB(bufoff, gbase, ld2) PG8_STAGE3(bufoff, gbase, ld2, Rb0, Rb1)
; #define PG8_WAIT_L(n) asm volatile("s_waitcnt lgkmcnt(" #n ")" ::: "memory")
; #define PG8_BAR __builtin_amdgcn_s_barrier()
; #define PG8_SCHED __builtin_amdgcn_sched_barrier(0)
; template <class Sched, class Epi>
; DI void gemm_stream(char* smem, const Sched& S_, const Epi& E) {
;     ...
;     for (int t = 0; t < nt; t += 2) {
;       const bool last = (t == nt - 2);
;       const char* a1 = cA + (size_t)(t + 1) * kstep;
;       const char* a2 = last ? nA : cA + (size_t)(t + 2) * kstep; const char* b2 = last ? nB : cB + (size_t)(t + 2) * kstep;
;       const char* a3 = a2 + kstep; const char* b3 = b2 + kstep;
;       const int xa2 = (last ? nxt.lda : cur.lda) * 2, xb2 = (last ? nxt.ldb : cur.ldb) * 2;
;       const size_t xhA = (size_t)HALF * xa2, xhB = (size_t)HALF * xb2;
;       PG8_LDB(B0, 0, 0); PG8_SCHED; PG8_LDA(At, 0, 0); PG8_STA(PG8_SA(1, 1), a1 + hA, la2);
;       PG8_WAIT_L(8); PG8_BAR; PG8_WAIT_L(0); PG8_MMA(0, 0, At, B0); PG8_BAR; PG8_SCHED;
;       PG8_LDB(B1, 0, 1); PG8_STB(PG8_SB(0, 0), b2, xb2);
;       PG8_BAR; PG8_WAIT_L(0); PG8_MMA(0, 1, At, B1); PG8_BAR;
;       PG8_LDA(At, 0, 1); PG8_STA(PG8_SA(0, 0), a2, xa2);
;       PG8_BAR; PG8_WAIT_L(0); PG8_MMA(1, 0, At, B0); PG8_BAR; PG8_SCHED;
.LBB0_1166:
	s_add_i32 s53, s46, 2
	s_add_u32 s50, s44, 0x80
	s_addc_u32 s47, s45, 0
	s_cmp_eq_u32 s62, s46
	s_cselect_b32 s47, s41, s47
	s_cselect_b32 s46, s40, s50
	s_cselect_b32 s50, s13, s20
	s_cselect_b32 s51, s3, s16
	s_cselect_b32 s89, s1, s52
	s_cselect_b32 s88, s0, s63
	s_add_i32 s64, 0, 0x10000
	v_add_u32_e32 v144, s64, v239
	ds_read_b128 v[132:135], v144
	ds_read_b128 v[136:139], v144 offset:1024
	ds_read_b128 v[140:143], v144 offset:2048
	ds_read_b128 v[144:147], v144 offset:3072
	s_lshl_b32 vcc_lo, s50, 1
	s_lshl_b32 s90, s51, 1
	s_ashr_i32 vcc_hi, vcc_lo, 31
	s_ashr_i32 s91, s90, 31
	s_lshl_b64 s[50:51], vcc, 7
	v_lshl_add_u64 v[180:181], s[44:45], 0, v[128:129]
	s_add_i32 m0, s39, 0xc000
	ds_read_b128 v[148:151], v241
	ds_read_b128 v[152:155], v241 offset:1024
	ds_read_b128 v[156:159], v241 offset:2048
	ds_read_b128 v[160:163], v241 offset:3072
	ds_read_b128 v[164:167], v241 offset:4096
	ds_read_b128 v[168:171], v241 offset:5120
	ds_read_b128 v[172:175], v241 offset:6144
	ds_read_b128 v[176:179], v241 offset:7168
	global_load_lds_dwordx4 v[180:181], off
	v_lshl_add_u64 v[180:181], s[44:45], 0, v[130:131]
	s_add_i32 m0, s39, 0xe000
	s_nop 0
	global_load_lds_dwordx4 v[180:181], off
	s_waitcnt lgkmcnt(8)
	s_barrier
	s_waitcnt lgkmcnt(0)
	s_waitcnt lgkmcnt(0)
	v_mfma_f32_16x16x32_bf16 v[124:127], v[132:135], v[148:151], v[124:127]
	v_mfma_f32_16x16x32_bf16 v[120:123], v[140:143], v[148:151], v[120:123]
	v_mfma_f32_16x16x32_bf16 v[116:119], v[132:135], v[156:159], v[116:119]
	v_mfma_f32_16x16x32_bf16 v[112:115], v[140:143], v[156:159], v[112:115]
	v_mfma_f32_16x16x32_bf16 v[100:103], v[132:135], v[164:167], v[100:103]
	v_mfma_f32_16x16x32_bf16 v[96:99], v[140:143], v[164:167], v[96:99]
	v_mfma_f32_16x16x32_bf16 v[84:87], v[132:135], v[172:175], v[84:87]
	v_mfma_f32_16x16x32_bf16 v[80:83], v[140:143], v[172:175], v[80:83]
	v_mfma_f32_16x16x32_bf16 v[124:127], v[136:139], v[152:155], v[124:127]
	v_mfma_f32_16x16x32_bf16 v[120:123], v[144:147], v[152:155], v[120:123]
	v_mfma_f32_16x16x32_bf16 v[116:119], v[136:139], v[160:163], v[116:119]
	v_mfma_f32_16x16x32_bf16 v[112:115], v[144:147], v[160:163], v[112:115]
	v_mfma_f32_16x16x32_bf16 v[100:103], v[136:139], v[168:171], v[100:103]
	v_mfma_f32_16x16x32_bf16 v[96:99], v[144:147], v[168:171], v[96:99]
	v_mfma_f32_16x16x32_bf16 v[84:87], v[136:139], v[176:179], v[84:87]
	v_mfma_f32_16x16x32_bf16 v[80:83], v[144:147], v[176:179], v[80:83]
	s_barrier
	s_add_i32 s65, 0, 0x14000
	s_add_i32 s64, s64, s60
	v_add_u32_e32 v195, s65, v239
	v_mad_u64_u32 v[200:201], s[56:57], s90, v236, v[204:205]
	s_mov_b32 m0, s64
	ds_read_b128 v[180:183], v195
	ds_read_b128 v[184:187], v195 offset:1024
	ds_read_b128 v[188:191], v195 offset:2048
	ds_read_b128 v[210:213], v195 offset:3072
	global_load_lds_dwordx4 v200, s[88:89]
	v_mad_u64_u32 v[202:203], s[56:57], s90, v237, v[206:207]
	s_add_i32 m0, s64, 0x2000
	v_mov_b32_e32 v201, v221
	global_load_lds_dwordx4 v202, s[88:89]
	s_barrier
	s_waitcnt lgkmcnt(0)
	v_mov_b32_e32 v203, v221
	v_lshl_add_u64 v[214:215], s[88:89], 0, v[200:201]
	v_lshl_add_u64 v[216:217], s[88:89], 0, v[202:203]
	s_waitcnt lgkmcnt(0)
	v_mfma_f32_16x16x32_bf16 v[108:111], v[180:183], v[148:151], v[108:111]
	v_mfma_f32_16x16x32_bf16 v[104:107], v[188:191], v[148:151], v[104:107]
	v_mfma_f32_16x16x32_bf16 v[92:95], v[180:183], v[156:159], v[92:95]
	v_mfma_f32_16x16x32_bf16 v[88:91], v[188:191], v[156:159], v[88:91]
	v_mfma_f32_16x16x32_bf16 v[76:79], v[180:183], v[164:167], v[76:79]
	v_mfma_f32_16x16x32_bf16 v[72:75], v[188:191], v[164:167], v[72:75]
	v_mfma_f32_16x16x32_bf16 v[68:71], v[180:183], v[172:175], v[68:71]
	v_mfma_f32_16x16x32_bf16 v[64:67], v[188:191], v[172:175], v[64:67]
	v_mfma_f32_16x16x32_bf16 v[108:111], v[184:187], v[152:155], v[108:111]
	v_mfma_f32_16x16x32_bf16 v[104:107], v[210:213], v[152:155], v[104:107]
	v_mfma_f32_16x16x32_bf16 v[92:95], v[184:187], v[160:163], v[92:95]
	v_mfma_f32_16x16x32_bf16 v[88:91], v[210:213], v[160:163], v[88:91]
	v_mfma_f32_16x16x32_bf16 v[76:79], v[184:187], v[168:171], v[76:79]
	v_mfma_f32_16x16x32_bf16 v[72:75], v[210:213], v[168:171], v[72:75]
	v_mfma_f32_16x16x32_bf16 v[68:71], v[184:187], v[176:179], v[68:71]
	v_mfma_f32_16x16x32_bf16 v[64:67], v[210:213], v[176:179], v[64:67]
	s_mov_b32 m0, s39
	v_mad_u64_u32 v[218:219], s[56:57], vcc_lo, v234, v[204:205]
	s_barrier
	ds_read_b128 v[148:151], v241 offset:16384
	ds_read_b128 v[152:155], v241 offset:17408
	ds_read_b128 v[156:159], v241 offset:18432
	ds_read_b128 v[160:163], v241 offset:19456
	ds_read_b128 v[164:167], v241 offset:20480
	ds_read_b128 v[168:171], v241 offset:21504
	ds_read_b128 v[172:175], v241 offset:22528
	ds_read_b128 v[176:179], v241 offset:23552
	global_load_lds_dwordx4 v218, s[46:47]
	v_mad_u64_u32 v[222:223], s[56:57], vcc_lo, v235, v[206:207]
	s_mov_b32 m0, s38
	v_mov_b32_e32 v219, v221
	global_load_lds_dwordx4 v222, s[46:47]
	s_barrier
	s_waitcnt lgkmcnt(0)
	v_mov_b32_e32 v223, v221
	v_lshl_add_u64 v[242:243], s[46:47], 0, v[218:219]
	v_lshl_add_u64 v[244:245], s[46:47], 0, v[222:223]
	s_waitcnt lgkmcnt(0)
	v_mfma_f32_16x16x32_bf16 v[60:63], v[132:135], v[148:151], v[60:63]
	s_lshl_b64 s[56:57], s[90:91], 7
	v_mfma_f32_16x16x32_bf16 v[56:59], v[140:143], v[148:151], v[56:59]
	v_mfma_f32_16x16x32_bf16 v[52:55], v[132:135], v[156:159], v[52:55]
	v_mfma_f32_16x16x32_bf16 v[48:51], v[140:143], v[156:159], v[48:51]
	v_mfma_f32_16x16x32_bf16 v[36:39], v[132:135], v[164:167], v[36:39]
	v_mfma_f32_16x16x32_bf16 v[32:35], v[140:143], v[164:167], v[32:35]
	v_mfma_f32_16x16x32_bf16 v[20:23], v[132:135], v[172:175], v[20:23]
	v_mfma_f32_16x16x32_bf16 v[16:19], v[140:143], v[172:175], v[16:19]
	v_mfma_f32_16x16x32_bf16 v[60:63], v[136:139], v[152:155], v[60:63]
	v_mfma_f32_16x16x32_bf16 v[56:59], v[144:147], v[152:155], v[56:59]
	v_mfma_f32_16x16x32_bf16 v[52:55], v[136:139], v[160:163], v[52:55]
	v_mfma_f32_16x16x32_bf16 v[48:51], v[144:147], v[160:163], v[48:51]
	v_mfma_f32_16x16x32_bf16 v[36:39], v[136:139], v[168:171], v[36:39]
	v_mfma_f32_16x16x32_bf16 v[32:35], v[144:147], v[168:171], v[32:35]
	v_mfma_f32_16x16x32_bf16 v[20:23], v[136:139], v[176:179], v[20:23]
	v_mfma_f32_16x16x32_bf16 v[16:19], v[144:147], v[176:179], v[16:19]
	s_barrier
; #define PG8_LDA(dst, b, h) do { _Pragma("unroll") for (int m = 0; m < 4; ++m) _Pragma("unroll") for (int k = 0; k < 2; ++k) dst[m][k] = *(const LAS bf16x8*)(lds + PG8_SA(b, h) + aoff + m * 2048 + k * 1024); } while (0)
; #define PG8_LDB(dst, b, h) do { _Pragma("unroll") for (int n = 0; n < 2; ++n) _Pragma("unroll") for (int k = 0; k < 2; ++k) dst[n][k] = *(const LAS bf16x8*)(lds + PG8_SB(b, h) + boff + n * 2048 + k * 1024); } while (0)
; #define PG8_MMA(ai, bj, At, Bt_) do { __builtin_amdgcn_s_setprio(1); _Pragma("unroll") for (int m = 0; m < 4; ++m) _Pragma("unroll") for (int n = 0; n < 2; ++n) _Pragma("unroll") for (int k = 0; k < 2; ++k) \
;     acc[ai][bj][m][n] = __builtin_amdgcn_mfma_f32_16x16x32_bf16(Bt_[n][k], At[m][k], acc[ai][bj][m][n], 0, 0, 0); __builtin_amdgcn_s_setprio(0); } while (0)
; #define PG8_WAIT_V(n) asm volatile("s_waitcnt vmcnt(" #n ")" ::: "memory")
; #define PG8_WAIT_L(n) asm volatile("s_waitcnt lgkmcnt(" #n ")" ::: "memory")
; #define PG8_BAR __builtin_amdgcn_s_barrier()
; #define PG8_SCHED __builtin_amdgcn_sched_barrier(0)
; #define PG8_STA(bufoff, gbase, ld2) PG8_STAGE3(bufoff, gbase, ld2, R0, R1)
; #define PG8_STB(bufoff, gbase, ld2) PG8_STAGE3(bufoff, gbase, ld2, Rb0, Rb1)
; #define PG8_LDA(dst, b, h) do { _Pragma("unroll") for (int m = 0; m < 4; ++m) _Pragma("unroll") for (int k = 0; k < 2; ++k) dst[m][k] = *(const LAS bf16x8*)(lds + PG8_SA(b, h) + aoff + m * 2048 + k * 1024); } while (0)
; #define PG8_LDB(dst, b, h) do { _Pragma("unroll") for (int n = 0; n < 2; ++n) _Pragma("unroll") for (int k = 0; k < 2; ++k) dst[n][k] = *(const LAS bf16x8*)(lds + PG8_SB(b, h) + boff + n * 2048 + k * 1024); } while (0)
; #define PG8_WAIT_V(n) asm volatile("s_waitcnt vmcnt(" #n ")" ::: "memory")
; #define PG8_WAIT_L(n) asm volatile("s_waitcnt lgkmcnt(" #n ")" ::: "memory")
; #define PG8_BAR __builtin_amdgcn_s_barrier()
; template <class Sched, class Epi>
; DI void gemm_stream(char* smem, const Sched& S_, const Epi& E) {
;     ...
;       PG8_STB(PG8_SB(0, 1), b2 + xhB, xb2);
;       PG8_WAIT_V(6); PG8_BAR; PG8_MMA(1, 1, At, B1); PG8_BAR;
;       PG8_LDB(B0, 1, 0); PG8_SCHED; PG8_LDA(At, 1, 0); PG8_STA(PG8_SA(0, 1), a2 + xhA, xa2);
;       PG8_WAIT_L(8); PG8_BAR; PG8_WAIT_L(0); PG8_MMA(0, 0, At, B0); PG8_BAR; PG8_SCHED;
;       PG8_LDB(B1, 1, 1); PG8_STB(PG8_SB(1, 0), b3, xb2);
;       PG8_BAR; PG8_WAIT_L(0); PG8_MMA(0, 1, At, B1); PG8_BAR;
	s_add_u32 s56, s88, s56
	s_addc_u32 s57, s89, s57
	s_add_i32 s64, s65, s60
	s_mov_b32 m0, s64
	s_nop 0
	global_load_lds_dwordx4 v200, s[56:57]
	s_add_i32 m0, s64, 0x2000
	v_lshl_add_u64 v[200:201], s[56:57], 0, v[200:201]
	global_load_lds_dwordx4 v202, s[56:57]
	s_waitcnt vmcnt(6)
	v_lshl_add_u64 v[202:203], s[56:57], 0, v[202:203]
	s_barrier
	v_mfma_f32_16x16x32_bf16 v[44:47], v[180:183], v[148:151], v[44:47]
	v_mfma_f32_16x16x32_bf16 v[40:43], v[188:191], v[148:151], v[40:43]
	v_mfma_f32_16x16x32_bf16 v[28:31], v[180:183], v[156:159], v[28:31]
	v_mfma_f32_16x16x32_bf16 v[24:27], v[188:191], v[156:159], v[24:27]
	v_mfma_f32_16x16x32_bf16 v[12:15], v[180:183], v[164:167], v[12:15]
	v_mfma_f32_16x16x32_bf16 v[8:11], v[188:191], v[164:167], v[8:11]
	v_mfma_f32_16x16x32_bf16 v[4:7], v[180:183], v[172:175], v[4:7]
	v_mfma_f32_16x16x32_bf16 v[0:3], v[188:191], v[172:175], v[0:3]
	v_mfma_f32_16x16x32_bf16 v[44:47], v[184:187], v[152:155], v[44:47]
	v_mfma_f32_16x16x32_bf16 v[40:43], v[210:213], v[152:155], v[40:43]
	v_mfma_f32_16x16x32_bf16 v[28:31], v[184:187], v[160:163], v[28:31]
	v_mfma_f32_16x16x32_bf16 v[24:27], v[210:213], v[160:163], v[24:27]
	v_mfma_f32_16x16x32_bf16 v[12:15], v[184:187], v[168:171], v[12:15]
	v_mfma_f32_16x16x32_bf16 v[8:11], v[210:213], v[168:171], v[8:11]
	v_mfma_f32_16x16x32_bf16 v[4:7], v[184:187], v[176:179], v[4:7]
	v_mfma_f32_16x16x32_bf16 v[0:3], v[210:213], v[176:179], v[0:3]
	s_add_i32 s56, 0, 0x18000
	v_add_u32_e32 v144, s56, v239
	s_barrier
	ds_read_b128 v[132:135], v144
	ds_read_b128 v[136:139], v144 offset:1024
	ds_read_b128 v[140:143], v144 offset:2048
	ds_read_b128 v[144:147], v144 offset:3072
	s_add_u32 s46, s46, s50
	s_addc_u32 s47, s47, s51
	s_mov_b32 m0, s9
	ds_read_b128 v[148:151], v241 offset:32768
	ds_read_b128 v[152:155], v241 offset:33792
	ds_read_b128 v[156:159], v241 offset:34816
	ds_read_b128 v[160:163], v241 offset:35840
	ds_read_b128 v[164:167], v241 offset:36864
	ds_read_b128 v[168:171], v241 offset:37888
	ds_read_b128 v[172:175], v241 offset:38912
	ds_read_b128 v[176:179], v241 offset:39936
	global_load_lds_dwordx4 v218, s[46:47]
	s_mov_b32 m0, s26
	s_nop 0
	global_load_lds_dwordx4 v222, s[46:47]
	s_waitcnt lgkmcnt(8)
	s_barrier
	s_waitcnt lgkmcnt(0)
	s_waitcnt lgkmcnt(0)
	v_mfma_f32_16x16x32_bf16 v[124:127], v[132:135], v[148:151], v[124:127]
	v_mfma_f32_16x16x32_bf16 v[120:123], v[140:143], v[148:151], v[120:123]
	v_mfma_f32_16x16x32_bf16 v[116:119], v[132:135], v[156:159], v[116:119]
	v_mfma_f32_16x16x32_bf16 v[112:115], v[140:143], v[156:159], v[112:115]
	v_mfma_f32_16x16x32_bf16 v[100:103], v[132:135], v[164:167], v[100:103]
	v_mfma_f32_16x16x32_bf16 v[96:99], v[140:143], v[164:167], v[96:99]
	v_mfma_f32_16x16x32_bf16 v[84:87], v[132:135], v[172:175], v[84:87]
	v_mfma_f32_16x16x32_bf16 v[80:83], v[140:143], v[172:175], v[80:83]
	v_mfma_f32_16x16x32_bf16 v[124:127], v[136:139], v[152:155], v[124:127]
	v_mfma_f32_16x16x32_bf16 v[120:123], v[144:147], v[152:155], v[120:123]
	v_mfma_f32_16x16x32_bf16 v[116:119], v[136:139], v[160:163], v[116:119]
	v_mfma_f32_16x16x32_bf16 v[112:115], v[144:147], v[160:163], v[112:115]
	v_mfma_f32_16x16x32_bf16 v[100:103], v[136:139], v[168:171], v[100:103]
	v_mfma_f32_16x16x32_bf16 v[96:99], v[144:147], v[168:171], v[96:99]
	v_mfma_f32_16x16x32_bf16 v[84:87], v[136:139], v[176:179], v[84:87]
	v_mfma_f32_16x16x32_bf16 v[80:83], v[144:147], v[176:179], v[80:83]
	s_barrier
	s_add_i32 s46, 0, 0x1c000
	s_add_i32 s47, s56, s60
	v_add_u32_e32 v195, s46, v239
	v_lshl_add_u64 v[214:215], v[214:215], 0, s[58:59]
	s_mov_b32 m0, s47
	ds_read_b128 v[180:183], v195
	ds_read_b128 v[184:187], v195 offset:1024
	ds_read_b128 v[188:191], v195 offset:2048
	ds_read_b128 v[210:213], v195 offset:3072
	global_load_lds_dwordx4 v[214:215], off
	v_lshl_add_u64 v[214:215], v[216:217], 0, s[58:59]
	s_add_i32 m0, s47, 0x2000
	s_nop 0
	global_load_lds_dwordx4 v[214:215], off
	s_barrier
	s_waitcnt lgkmcnt(0)
	s_waitcnt lgkmcnt(0)
	v_mfma_f32_16x16x32_bf16 v[108:111], v[180:183], v[148:151], v[108:111]
	v_mfma_f32_16x16x32_bf16 v[104:107], v[188:191], v[148:151], v[104:107]
	v_mfma_f32_16x16x32_bf16 v[92:95], v[180:183], v[156:159], v[92:95]
	v_mfma_f32_16x16x32_bf16 v[88:91], v[188:191], v[156:159], v[88:91]
	v_mfma_f32_16x16x32_bf16 v[76:79], v[180:183], v[164:167], v[76:79]
	v_mfma_f32_16x16x32_bf16 v[72:75], v[188:191], v[164:167], v[72:75]
	v_mfma_f32_16x16x32_bf16 v[68:71], v[180:183], v[172:175], v[68:71]
	v_mfma_f32_16x16x32_bf16 v[64:67], v[188:191], v[172:175], v[64:67]
	v_mfma_f32_16x16x32_bf16 v[108:111], v[184:187], v[152:155], v[108:111]
	v_mfma_f32_16x16x32_bf16 v[104:107], v[210:213], v[152:155], v[104:107]
	v_mfma_f32_16x16x32_bf16 v[92:95], v[184:187], v[160:163], v[92:95]
	v_mfma_f32_16x16x32_bf16 v[88:91], v[210:213], v[160:163], v[88:91]
	v_mfma_f32_16x16x32_bf16 v[76:79], v[184:187], v[168:171], v[76:79]
	v_mfma_f32_16x16x32_bf16 v[72:75], v[210:213], v[168:171], v[72:75]
	v_mfma_f32_16x16x32_bf16 v[68:71], v[184:187], v[176:179], v[68:71]
	v_mfma_f32_16x16x32_bf16 v[64:67], v[210:213], v[176:179], v[64:67]
	s_mov_b32 m0, s27
	v_lshl_add_u64 v[214:215], v[242:243], 0, s[58:59]
	s_barrier
; DI int get_tid() { int t = threadIdx.x; asm volatile("" : "+v"(t)); return t; }
; #define MEMBAR() asm volatile("" ::: "memory")
; #define PG8_LDA(dst, b, h) do { _Pragma("unroll") for (int m = 0; m < 4; ++m) _Pragma("unroll") for (int k = 0; k < 2; ++k) dst[m][k] = *(const LAS bf16x8*)(lds + PG8_SA(b, h) + aoff + m * 2048 + k * 1024); } while (0)
; #define PG8_MMA(ai, bj, At, Bt_) do { __builtin_amdgcn_s_setprio(1); _Pragma("unroll") for (int m = 0; m < 4; ++m) _Pragma("unroll") for (int n = 0; n < 2; ++n) _Pragma("unroll") for (int k = 0; k < 2; ++k) \
;     acc[ai][bj][m][n] = __builtin_amdgcn_mfma_f32_16x16x32_bf16(Bt_[n][k], At[m][k], acc[ai][bj][m][n], 0, 0, 0); __builtin_amdgcn_s_setprio(0); } while (0)
; #define PG8_WAIT_V(n) asm volatile("s_waitcnt vmcnt(" #n ")" ::: "memory")
; #define PG8_WAIT_L(n) asm volatile("s_waitcnt lgkmcnt(" #n ")" ::: "memory")
; #define PG8_BAR __builtin_amdgcn_s_barrier()
; #define PG8_SCHED __builtin_amdgcn_sched_barrier(0)
; #define PG8_STA(bufoff, gbase, ld2) PG8_STAGE3(bufoff, gbase, ld2, R0, R1)
; template <class Sched, class Epi>
; DI void gemm_stream(char* smem, const Sched& S_, const Epi& E) {
;     ...
;       PG8_LDA(At, 1, 1); PG8_STA(PG8_SA(1, 0), a3, xa2);
;       PG8_BAR; PG8_WAIT_L(0); PG8_MMA(1, 0, At, B0); PG8_BAR; PG8_SCHED;
;       PG8_STB(PG8_SB(1, 1), b3 + xhB, xb2);
;       PG8_WAIT_V(6); PG8_BAR; PG8_MMA(1, 1, At, B1); PG8_BAR;
;     }
;   DI void operator()(const acc_t& acc, const Desc& u, int wr, int wc, int fr, int fq) const {
;     u32x4* sp = slab + get_tid(); asm volatile("" : "+v"(sp));
;     if (!(u.kind & 1)) {
; #pragma unroll
;       for (int ai = 0; ai < 2; ++ai)
; #pragma unroll
;         for (int m = 0; m < 4; ++m)
; #pragma unroll
;           for (int bj = 0; bj < 2; ++bj) sp[((ai * 4 + m) * 2 + bj) * 512] = pack8v(acc[ai][bj][m][0], acc[ai][bj][m][1]);
;     } else {
;       const int first = u.kind == 1, lastx = u.kind == 5;
;       const int row0 = u.pm * BM + wr * 64 + fr, col0 = u.pn * BM + wc * 32 + 8 * fq;
; #pragma unroll
;       for (int ai = 0; ai < 2; ++ai) {
;         MEMBAR();
;         u32x4 pv[4][2], mv[4][2];
; #pragma unroll
;         for (int m = 0; m < 4; ++m)
; #pragma unroll
;           for (int bj = 0; bj < 2; ++bj) {
;             pv[m][bj] = sp[((ai * 4 + m) * 2 + bj) * 512];
;             if (!first) mv[m][bj] = sp[(16 + (ai * 4 + m) * 2 + bj) * 512];
	ds_read_b128 v[148:151], v241 offset:49152
	ds_read_b128 v[152:155], v241 offset:50176
	ds_read_b128 v[156:159], v241 offset:51200
	ds_read_b128 v[160:163], v241 offset:52224
	ds_read_b128 v[164:167], v241 offset:53248
	ds_read_b128 v[168:171], v241 offset:54272
	ds_read_b128 v[172:175], v241 offset:55296
	ds_read_b128 v[176:179], v241 offset:56320
	global_load_lds_dwordx4 v[214:215], off
	v_lshl_add_u64 v[214:215], v[244:245], 0, s[58:59]
	s_mov_b32 m0, s33
	s_nop 0
	global_load_lds_dwordx4 v[214:215], off
	s_barrier
	s_waitcnt lgkmcnt(0)
	s_waitcnt lgkmcnt(0)
	v_mfma_f32_16x16x32_bf16 v[60:63], v[132:135], v[148:151], v[60:63]
	v_mfma_f32_16x16x32_bf16 v[56:59], v[140:143], v[148:151], v[56:59]
	v_mfma_f32_16x16x32_bf16 v[52:55], v[132:135], v[156:159], v[52:55]
	v_mfma_f32_16x16x32_bf16 v[48:51], v[140:143], v[156:159], v[48:51]
	v_mfma_f32_16x16x32_bf16 v[36:39], v[132:135], v[164:167], v[36:39]
	v_mfma_f32_16x16x32_bf16 v[32:35], v[140:143], v[164:167], v[32:35]
	v_mfma_f32_16x16x32_bf16 v[20:23], v[132:135], v[172:175], v[20:23]
	v_mfma_f32_16x16x32_bf16 v[16:19], v[140:143], v[172:175], v[16:19]
	v_mfma_f32_16x16x32_bf16 v[60:63], v[136:139], v[152:155], v[60:63]
	v_mfma_f32_16x16x32_bf16 v[56:59], v[144:147], v[152:155], v[56:59]
	v_mfma_f32_16x16x32_bf16 v[52:55], v[136:139], v[160:163], v[52:55]
	v_mfma_f32_16x16x32_bf16 v[48:51], v[144:147], v[160:163], v[48:51]
	v_mfma_f32_16x16x32_bf16 v[36:39], v[136:139], v[168:171], v[36:39]
	v_mfma_f32_16x16x32_bf16 v[32:35], v[144:147], v[168:171], v[32:35]
	v_mfma_f32_16x16x32_bf16 v[20:23], v[136:139], v[176:179], v[20:23]
	v_mfma_f32_16x16x32_bf16 v[16:19], v[144:147], v[176:179], v[16:19]
	s_barrier
	s_add_i32 s46, s46, s60
	v_lshl_add_u64 v[132:133], v[200:201], 0, s[58:59]
	s_mov_b32 m0, s46
	s_nop 0
	global_load_lds_dwordx4 v[132:133], off
	v_lshl_add_u64 v[132:133], v[202:203], 0, s[58:59]
	s_add_i32 m0, s46, 0x2000
	s_nop 0
	global_load_lds_dwordx4 v[132:133], off
	s_waitcnt vmcnt(6)
	s_barrier
	v_mfma_f32_16x16x32_bf16 v[44:47], v[180:183], v[148:151], v[44:47]
	v_mfma_f32_16x16x32_bf16 v[40:43], v[188:191], v[148:151], v[40:43]
	v_mfma_f32_16x16x32_bf16 v[28:31], v[180:183], v[156:159], v[28:31]
	v_mfma_f32_16x16x32_bf16 v[24:27], v[188:191], v[156:159], v[24:27]
	v_mfma_f32_16x16x32_bf16 v[12:15], v[180:183], v[164:167], v[12:15]
	v_mfma_f32_16x16x32_bf16 v[8:11], v[188:191], v[164:167], v[8:11]
	v_mfma_f32_16x16x32_bf16 v[4:7], v[180:183], v[172:175], v[4:7]
	v_mfma_f32_16x16x32_bf16 v[0:3], v[188:191], v[172:175], v[0:3]
	v_mfma_f32_16x16x32_bf16 v[44:47], v[184:187], v[152:155], v[44:47]
	v_mfma_f32_16x16x32_bf16 v[40:43], v[210:213], v[152:155], v[40:43]
	v_mfma_f32_16x16x32_bf16 v[28:31], v[184:187], v[160:163], v[28:31]
	v_mfma_f32_16x16x32_bf16 v[24:27], v[210:213], v[160:163], v[24:27]
	v_mfma_f32_16x16x32_bf16 v[12:15], v[184:187], v[168:171], v[12:15]
	v_mfma_f32_16x16x32_bf16 v[8:11], v[210:213], v[168:171], v[8:11]
	v_mfma_f32_16x16x32_bf16 v[4:7], v[184:187], v[176:179], v[4:7]
	v_mfma_f32_16x16x32_bf16 v[0:3], v[210:213], v[176:179], v[0:3]
	s_add_u32 s44, s44, 0x100
	s_addc_u32 s45, s45, 0
	s_add_u32 s63, s63, 0x100
	s_addc_u32 s52, s52, 0
	s_cmp_ge_i32 s53, s5
	s_mov_b32 s46, s53
	s_barrier
	s_cbranch_scc0 .LBB0_1166
	v_mov_b32_e32 v128, v192
	v_readlane_b32 s44, v252, 45
	s_bitcmp1_b32 s4, 0
	v_readlane_b32 s45, v252, 46
	v_ashrrev_i32_e32 v129, 31, v128
	s_cselect_b64 s[46:47], -1, 0
	v_readlane_b32 s62, v254, 39
	v_readlane_b32 s88, v254, 43
	v_lshl_add_u64 v[210:211], v[128:129], 4, s[44:45]
	s_mov_b64 s[44:45], -1
	s_and_b64 vcc, exec, s[46:47]
	v_readlane_b32 s63, v254, 40
	v_readlane_b32 s89, v254, 44
	v_readlane_b32 s53, v253, 4
	s_movk_i32 s80, 0xef00
	s_cbranch_vccz .LBB0_1297
	flat_load_dwordx4 v[188:191], v[210:211]
	s_cmp_lg_u32 s4, 1
	s_cselect_b64 s[46:47], -1, 0
	s_cmp_eq_u32 s4, 1
	s_cbranch_scc1 .LBB0_1170
	v_add_co_u32_e32 v128, vcc, 0x20000, v210
	s_nop 1
	v_addc_co_u32_e32 v129, vcc, 0, v211, vcc
	flat_load_dwordx4 v[156:159], v[128:129]

; #define PG8_STAGE(bufoff, gbase, voff) do { _Pragma("unroll") for (int _i = 0; _i < 2; ++_i) \
;     __builtin_amdgcn_global_load_lds((const unsigned*)((const char*)(gbase) + (voff)[_i]), (LAS unsigned*)(lds + (bufoff) + ldsw + _i * 8192), 16, 0, 0); } while (0)
; #define PG8_LDA(dst, b, h) do { _Pragma("unroll") for (int m = 0; m < 4; ++m) _Pragma("unroll") for (int k = 0; k < 2; ++k) dst[m][k] = *(const LAS bf16x8*)(lds + PG8_SA(b, h) + aoff + m * 2048 + k * 1024); } while (0)
; #define PG8_LDB(dst, b, h) do { _Pragma("unroll") for (int n = 0; n < 2; ++n) _Pragma("unroll") for (int k = 0; k < 2; ++k) dst[n][k] = *(const LAS bf16x8*)(lds + PG8_SB(b, h) + boff + n * 2048 + k * 1024); } while (0)
; #define PG8_MMA(ai, bj, At, Bt_) do { __builtin_amdgcn_s_setprio(1); _Pragma("unroll") for (int m = 0; m < 4; ++m) _Pragma("unroll") for (int n = 0; n < 2; ++n) _Pragma("unroll") for (int k = 0; k < 2; ++k) \
;     acc[ai][bj][m][n] = __builtin_amdgcn_mfma_f32_16x16x32_bf16(Bt_[n][k], At[m][k], acc[ai][bj][m][n], 0, 0, 0); __builtin_amdgcn_s_setprio(0); } while (0)
; #define PG8_WAIT_L(n) asm volatile("s_waitcnt lgkmcnt(" #n ")" ::: "memory")
; #define PG8_BAR __builtin_amdgcn_s_barrier()
; #define PG8_SCHED __builtin_amdgcn_sched_barrier(0)
; #define PG8_WAIT_L(n) asm volatile("s_waitcnt lgkmcnt(" #n ")" ::: "memory")
; #define PG8_BAR __builtin_amdgcn_s_barrier()
; #define PG8_SCHED __builtin_amdgcn_sched_barrier(0)
; template <class Epi>
; DI void gemm_phase(char* smem, const bf16_t* A, int lda, const bf16_t* Bt, int ldb, int K, const Order& S_, const Epi& E) {
;     ...
;     for (int t = 0; t < nt; t += 2) {
;       const bool last = (t == nt - 2);
;       const char* a1 = cA + (size_t)(t + 1) * kstep;
;       const char* a2 = last ? nA : cA + (size_t)(t + 2) * kstep; const char* b2 = last ? nB : cB + (size_t)(t + 2) * kstep;
;       const char* a3 = a2 + kstep; const char* b3 = b2 + kstep;
;       PG8_LDB(B0, 0, 0); PG8_SCHED; PG8_LDA(At, 0, 0); PG8_STAGE(PG8_SA(1, 1), a1 + hstepA, voffA);
;       PG8_WAIT_L(8); PG8_BAR; PG8_WAIT_L(0); PG8_MMA(0, 0, At, B0); PG8_BAR; PG8_SCHED;
;       PG8_LDB(B1, 0, 1); PG8_STAGE(PG8_SB(0, 0), b2, voffB);
;       PG8_BAR; PG8_WAIT_L(0); PG8_MMA(0, 1, At, B1); PG8_BAR;
;       PG8_LDA(At, 0, 1); PG8_STAGE(PG8_SA(0, 0), a2, voffA);
;       PG8_BAR; PG8_WAIT_L(0); PG8_MMA(1, 0, At, B0); PG8_BAR; PG8_SCHED;
.LBB0_1701:
	s_add_u32 s0, s90, 0x100
	s_addc_u32 s1, s91, 0
	s_add_i32 s41, 0, 0x10000
	v_add_u32_e32 v76, s41, v185
	ds_read_b128 v[64:67], v76
	ds_read_b128 v[68:71], v76 offset:1024
	ds_read_b128 v[72:75], v76 offset:2048
	ds_read_b128 v[76:79], v76 offset:3072
	s_cmp_eq_u32 s29, 12
	s_cselect_b32 s51, s45, s1
	s_cselect_b32 s50, s44, s0
	s_cselect_b32 s47, s5, s20
	s_cselect_b32 s46, s15, s16
	v_lshl_add_u64 v[182:183], s[90:91], 0, v[166:167]
	s_add_i32 m0, s27, 0xc000
	ds_read_b128 v[144:147], v187
	ds_read_b128 v[148:151], v187 offset:1024
	ds_read_b128 v[152:155], v187 offset:2048
	ds_read_b128 v[156:159], v187 offset:3072
	ds_read_b128 v[170:173], v187 offset:4096
	ds_read_b128 v[174:177], v187 offset:5120
	ds_read_b128 v[178:181], v187 offset:6144
	ds_read_b128 v[188:191], v187 offset:7168
	global_load_lds_dwordx4 v[182:183], off
	v_lshl_add_u64 v[182:183], s[90:91], 0, v[168:169]
	s_add_i32 m0, s27, 0xe000
	s_nop 0
	global_load_lds_dwordx4 v[182:183], off
	s_waitcnt lgkmcnt(8)
	s_barrier
	s_waitcnt lgkmcnt(0)
	s_waitcnt lgkmcnt(0)
	v_mfma_f32_16x16x32_bf16 v[140:143], v[64:67], v[144:147], v[140:143]
	v_mfma_f32_16x16x32_bf16 v[136:139], v[72:75], v[144:147], v[136:139]
	v_mfma_f32_16x16x32_bf16 v[132:135], v[64:67], v[152:155], v[132:135]
	v_mfma_f32_16x16x32_bf16 v[124:127], v[72:75], v[152:155], v[124:127]
	v_mfma_f32_16x16x32_bf16 v[108:111], v[64:67], v[170:173], v[108:111]
	v_mfma_f32_16x16x32_bf16 v[104:107], v[72:75], v[170:173], v[104:107]
	v_mfma_f32_16x16x32_bf16 v[100:103], v[64:67], v[178:181], v[100:103]
	v_mfma_f32_16x16x32_bf16 v[92:95], v[72:75], v[178:181], v[92:95]
	v_mfma_f32_16x16x32_bf16 v[140:143], v[68:71], v[148:151], v[140:143]
	v_mfma_f32_16x16x32_bf16 v[136:139], v[76:79], v[148:151], v[136:139]
	v_mfma_f32_16x16x32_bf16 v[132:135], v[68:71], v[156:159], v[132:135]
	v_mfma_f32_16x16x32_bf16 v[124:127], v[76:79], v[156:159], v[124:127]
	v_mfma_f32_16x16x32_bf16 v[108:111], v[68:71], v[174:177], v[108:111]
	v_mfma_f32_16x16x32_bf16 v[104:107], v[76:79], v[174:177], v[104:107]
	v_mfma_f32_16x16x32_bf16 v[100:103], v[68:71], v[188:191], v[100:103]
	v_mfma_f32_16x16x32_bf16 v[92:95], v[76:79], v[188:191], v[92:95]
	s_barrier
	s_add_i32 s43, 0, 0x14000
	v_add_u32_e32 v182, s43, v185
	s_add_i32 s41, s41, s26
	ds_read_b128 v[210:213], v182
	ds_read_b128 v[214:217], v182 offset:1024
	ds_read_b128 v[234:237], v182 offset:2048
	ds_read_b128 v[238:241], v182 offset:3072
	v_lshl_add_u64 v[182:183], s[46:47], 0, v[220:221]
	s_mov_b32 m0, s41
	v_lshl_add_u64 v[194:195], s[46:47], 0, v[164:165]
	global_load_lds_dwordx4 v[182:183], off
	s_add_i32 m0, s41, 0x2000
	s_nop 0
	global_load_lds_dwordx4 v[194:195], off
	s_barrier
	s_waitcnt lgkmcnt(0)
	s_waitcnt lgkmcnt(0)
	v_mfma_f32_16x16x32_bf16 v[128:131], v[210:213], v[144:147], v[128:131]
	v_mfma_f32_16x16x32_bf16 v[120:123], v[234:237], v[144:147], v[120:123]
	v_mfma_f32_16x16x32_bf16 v[116:119], v[210:213], v[152:155], v[116:119]
	v_mfma_f32_16x16x32_bf16 v[112:115], v[234:237], v[152:155], v[112:115]
	v_mfma_f32_16x16x32_bf16 v[96:99], v[210:213], v[170:173], v[96:99]
	v_mfma_f32_16x16x32_bf16 v[88:91], v[234:237], v[170:173], v[88:91]
	v_mfma_f32_16x16x32_bf16 v[84:87], v[210:213], v[178:181], v[84:87]
	v_mfma_f32_16x16x32_bf16 v[80:83], v[234:237], v[178:181], v[80:83]
	v_mfma_f32_16x16x32_bf16 v[128:131], v[214:217], v[148:151], v[128:131]
	v_mfma_f32_16x16x32_bf16 v[120:123], v[238:241], v[148:151], v[120:123]
	v_mfma_f32_16x16x32_bf16 v[116:119], v[214:217], v[156:159], v[116:119]
	v_mfma_f32_16x16x32_bf16 v[112:115], v[238:241], v[156:159], v[112:115]
	v_mfma_f32_16x16x32_bf16 v[96:99], v[214:217], v[174:177], v[96:99]
	v_mfma_f32_16x16x32_bf16 v[88:91], v[238:241], v[174:177], v[88:91]
	v_mfma_f32_16x16x32_bf16 v[84:87], v[214:217], v[188:191], v[84:87]
	v_mfma_f32_16x16x32_bf16 v[80:83], v[238:241], v[188:191], v[80:83]
	s_mov_b32 m0, s27
	v_lshl_add_u64 v[200:201], s[50:51], 0, v[160:161]
	s_barrier
	ds_read_b128 v[144:147], v187 offset:16384
	ds_read_b128 v[148:151], v187 offset:17408
	ds_read_b128 v[152:155], v187 offset:18432
	ds_read_b128 v[156:159], v187 offset:19456
	ds_read_b128 v[170:173], v187 offset:20480
	ds_read_b128 v[174:177], v187 offset:21504
	ds_read_b128 v[178:181], v187 offset:22528
	ds_read_b128 v[188:191], v187 offset:23552
	global_load_lds_dwordx4 v[200:201], off
	v_lshl_add_u64 v[202:203], s[50:51], 0, v[162:163]
	s_mov_b32 m0, s33
	s_nop 0
	global_load_lds_dwordx4 v[202:203], off
	s_barrier
	s_waitcnt lgkmcnt(0)
	s_waitcnt lgkmcnt(0)
	v_mfma_f32_16x16x32_bf16 v[60:63], v[64:67], v[144:147], v[60:63]
	v_mfma_f32_16x16x32_bf16 v[56:59], v[72:75], v[144:147], v[56:59]
	v_mfma_f32_16x16x32_bf16 v[52:55], v[64:67], v[152:155], v[52:55]
	v_mfma_f32_16x16x32_bf16 v[44:47], v[72:75], v[152:155], v[44:47]
	v_mfma_f32_16x16x32_bf16 v[28:31], v[64:67], v[170:173], v[28:31]
	v_mfma_f32_16x16x32_bf16 v[24:27], v[72:75], v[170:173], v[24:27]
	v_mfma_f32_16x16x32_bf16 v[20:23], v[64:67], v[178:181], v[20:23]
	v_mfma_f32_16x16x32_bf16 v[12:15], v[72:75], v[178:181], v[12:15]
	v_mfma_f32_16x16x32_bf16 v[60:63], v[68:71], v[148:151], v[60:63]
	v_mfma_f32_16x16x32_bf16 v[56:59], v[76:79], v[148:151], v[56:59]
	v_mfma_f32_16x16x32_bf16 v[52:55], v[68:71], v[156:159], v[52:55]
	v_mfma_f32_16x16x32_bf16 v[44:47], v[76:79], v[156:159], v[44:47]
	v_mfma_f32_16x16x32_bf16 v[28:31], v[68:71], v[174:177], v[28:31]
	v_mfma_f32_16x16x32_bf16 v[24:27], v[76:79], v[174:177], v[24:27]
	v_mfma_f32_16x16x32_bf16 v[20:23], v[68:71], v[188:191], v[20:23]
	v_mfma_f32_16x16x32_bf16 v[12:15], v[76:79], v[188:191], v[12:15]
	s_barrier
; #define PG8_STAGE(bufoff, gbase, voff) do { _Pragma("unroll") for (int _i = 0; _i < 2; ++_i) \
;     __builtin_amdgcn_global_load_lds((const unsigned*)((const char*)(gbase) + (voff)[_i]), (LAS unsigned*)(lds + (bufoff) + ldsw + _i * 8192), 16, 0, 0); } while (0)
; #define PG8_LDA(dst, b, h) do { _Pragma("unroll") for (int m = 0; m < 4; ++m) _Pragma("unroll") for (int k = 0; k < 2; ++k) dst[m][k] = *(const LAS bf16x8*)(lds + PG8_SA(b, h) + aoff + m * 2048 + k * 1024); } while (0)
; #define PG8_LDB(dst, b, h) do { _Pragma("unroll") for (int n = 0; n < 2; ++n) _Pragma("unroll") for (int k = 0; k < 2; ++k) dst[n][k] = *(const LAS bf16x8*)(lds + PG8_SB(b, h) + boff + n * 2048 + k * 1024); } while (0)
; #define PG8_MMA(ai, bj, At, Bt_) do { __builtin_amdgcn_s_setprio(1); _Pragma("unroll") for (int m = 0; m < 4; ++m) _Pragma("unroll") for (int n = 0; n < 2; ++n) _Pragma("unroll") for (int k = 0; k < 2; ++k) \
;     acc[ai][bj][m][n] = __builtin_amdgcn_mfma_f32_16x16x32_bf16(Bt_[n][k], At[m][k], acc[ai][bj][m][n], 0, 0, 0); __builtin_amdgcn_s_setprio(0); } while (0)
; #define PG8_WAIT_V(n) asm volatile("s_waitcnt vmcnt(" #n ")" ::: "memory")
; #define PG8_WAIT_L(n) asm volatile("s_waitcnt lgkmcnt(" #n ")" ::: "memory")
; #define PG8_BAR __builtin_amdgcn_s_barrier()
; #define PG8_SCHED __builtin_amdgcn_sched_barrier(0)
; #define PG8_LDA(dst, b, h) do { _Pragma("unroll") for (int m = 0; m < 4; ++m) _Pragma("unroll") for (int k = 0; k < 2; ++k) dst[m][k] = *(const LAS bf16x8*)(lds + PG8_SA(b, h) + aoff + m * 2048 + k * 1024); } while (0)
; #define PG8_WAIT_V(n) asm volatile("s_waitcnt vmcnt(" #n ")" ::: "memory")
; template <class Epi>
; DI void gemm_phase(char* smem, const bf16_t* A, int lda, const bf16_t* Bt, int ldb, int K, const Order& S_, const Epi& E) {
;     ...
;       PG8_STAGE(PG8_SB(0, 1), b2 + hstepB, voffB);
;       PG8_WAIT_V(6); PG8_BAR; PG8_MMA(1, 1, At, B1); PG8_BAR;
;       PG8_LDB(B0, 1, 0); PG8_SCHED; PG8_LDA(At, 1, 0); PG8_STAGE(PG8_SA(0, 1), a2 + hstepA, voffA);
;       PG8_WAIT_L(8); PG8_BAR; PG8_WAIT_L(0); PG8_MMA(0, 0, At, B0); PG8_BAR; PG8_SCHED;
;       PG8_LDB(B1, 1, 1); PG8_STAGE(PG8_SB(1, 0), b3, voffB);
;       PG8_BAR; PG8_WAIT_L(0); PG8_MMA(0, 1, At, B1); PG8_BAR;
;       PG8_LDA(At, 1, 1); PG8_STAGE(PG8_SA(1, 0), a3, voffA);
;       PG8_BAR; PG8_WAIT_L(0); PG8_MMA(1, 0, At, B0); PG8_BAR; PG8_SCHED;
	s_add_u32 s52, s46, 0x40000
	s_addc_u32 s53, s47, 0
	s_add_i32 s41, s43, s26
	v_lshl_add_u64 v[64:65], s[52:53], 0, v[220:221]
	s_mov_b32 m0, s41
	s_nop 0
	global_load_lds_dwordx4 v[64:65], off
	v_lshl_add_u64 v[64:65], s[52:53], 0, v[164:165]
	s_add_i32 m0, s41, 0x2000
	s_nop 0
	global_load_lds_dwordx4 v[64:65], off
	s_waitcnt vmcnt(6)
	s_barrier
	v_mfma_f32_16x16x32_bf16 v[48:51], v[210:213], v[144:147], v[48:51]
	v_mfma_f32_16x16x32_bf16 v[40:43], v[234:237], v[144:147], v[40:43]
	v_mfma_f32_16x16x32_bf16 v[36:39], v[210:213], v[152:155], v[36:39]
	v_mfma_f32_16x16x32_bf16 v[32:35], v[234:237], v[152:155], v[32:35]
	v_mfma_f32_16x16x32_bf16 v[16:19], v[210:213], v[170:173], v[16:19]
	v_mfma_f32_16x16x32_bf16 v[8:11], v[234:237], v[170:173], v[8:11]
	v_mfma_f32_16x16x32_bf16 v[4:7], v[210:213], v[178:181], v[4:7]
	v_mfma_f32_16x16x32_bf16 v[0:3], v[234:237], v[178:181], v[0:3]
	v_mfma_f32_16x16x32_bf16 v[48:51], v[214:217], v[148:151], v[48:51]
	v_mfma_f32_16x16x32_bf16 v[40:43], v[238:241], v[148:151], v[40:43]
	v_mfma_f32_16x16x32_bf16 v[36:39], v[214:217], v[156:159], v[36:39]
	v_mfma_f32_16x16x32_bf16 v[32:35], v[238:241], v[156:159], v[32:35]
	v_mfma_f32_16x16x32_bf16 v[16:19], v[214:217], v[174:177], v[16:19]
	v_mfma_f32_16x16x32_bf16 v[8:11], v[238:241], v[174:177], v[8:11]
	v_mfma_f32_16x16x32_bf16 v[4:7], v[214:217], v[188:191], v[4:7]
	v_mfma_f32_16x16x32_bf16 v[0:3], v[238:241], v[188:191], v[0:3]
	s_add_i32 s41, 0, 0x18000
	v_add_u32_e32 v76, s41, v185
	s_barrier
	ds_read_b128 v[64:67], v76
	ds_read_b128 v[68:71], v76 offset:1024
	ds_read_b128 v[72:75], v76 offset:2048
	ds_read_b128 v[76:79], v76 offset:3072
	s_add_u32 s50, s50, 0xb0000
	s_addc_u32 s51, s51, 0
	s_mov_b32 m0, s34
	v_lshl_add_u64 v[208:209], s[50:51], 0, v[160:161]
	ds_read_b128 v[144:147], v187 offset:32768
	ds_read_b128 v[148:151], v187 offset:33792
	ds_read_b128 v[152:155], v187 offset:34816
	ds_read_b128 v[156:159], v187 offset:35840
	ds_read_b128 v[170:173], v187 offset:36864
	ds_read_b128 v[174:177], v187 offset:37888
	ds_read_b128 v[178:181], v187 offset:38912
	ds_read_b128 v[188:191], v187 offset:39936
	global_load_lds_dwordx4 v[208:209], off
	v_lshl_add_u64 v[208:209], s[50:51], 0, v[162:163]
	s_mov_b32 m0, s38
	s_nop 0
	global_load_lds_dwordx4 v[208:209], off
	s_waitcnt lgkmcnt(8)
	s_barrier
	s_waitcnt lgkmcnt(0)
	s_waitcnt lgkmcnt(0)
	v_mfma_f32_16x16x32_bf16 v[140:143], v[64:67], v[144:147], v[140:143]
	v_mfma_f32_16x16x32_bf16 v[136:139], v[72:75], v[144:147], v[136:139]
	v_mfma_f32_16x16x32_bf16 v[132:135], v[64:67], v[152:155], v[132:135]
	v_mfma_f32_16x16x32_bf16 v[124:127], v[72:75], v[152:155], v[124:127]
	v_mfma_f32_16x16x32_bf16 v[108:111], v[64:67], v[170:173], v[108:111]
	v_mfma_f32_16x16x32_bf16 v[104:107], v[72:75], v[170:173], v[104:107]
	v_mfma_f32_16x16x32_bf16 v[100:103], v[64:67], v[178:181], v[100:103]
	v_mfma_f32_16x16x32_bf16 v[92:95], v[72:75], v[178:181], v[92:95]
	v_mfma_f32_16x16x32_bf16 v[140:143], v[68:71], v[148:151], v[140:143]
	v_mfma_f32_16x16x32_bf16 v[136:139], v[76:79], v[148:151], v[136:139]
	v_mfma_f32_16x16x32_bf16 v[132:135], v[68:71], v[156:159], v[132:135]
	v_mfma_f32_16x16x32_bf16 v[124:127], v[76:79], v[156:159], v[124:127]
	v_mfma_f32_16x16x32_bf16 v[108:111], v[68:71], v[174:177], v[108:111]
	v_mfma_f32_16x16x32_bf16 v[104:107], v[76:79], v[174:177], v[104:107]
	v_mfma_f32_16x16x32_bf16 v[100:103], v[68:71], v[188:191], v[100:103]
	v_mfma_f32_16x16x32_bf16 v[92:95], v[76:79], v[188:191], v[92:95]
	s_barrier
	s_add_i32 s43, 0, 0x1c000
	s_add_i32 s41, s41, s26
	v_add_u32_e32 v204, s43, v185
	v_lshl_add_u64 v[182:183], v[182:183], 0, s[58:59]
	s_mov_b32 m0, s41
	ds_read_b128 v[210:213], v204
	ds_read_b128 v[214:217], v204 offset:1024
	ds_read_b128 v[234:237], v204 offset:2048
	ds_read_b128 v[238:241], v204 offset:3072
	global_load_lds_dwordx4 v[182:183], off
	v_lshl_add_u64 v[182:183], v[194:195], 0, s[58:59]
	s_add_i32 m0, s41, 0x2000
	s_nop 0
	global_load_lds_dwordx4 v[182:183], off
	s_barrier
	s_waitcnt lgkmcnt(0)
	s_waitcnt lgkmcnt(0)
	v_mfma_f32_16x16x32_bf16 v[128:131], v[210:213], v[144:147], v[128:131]
	v_mfma_f32_16x16x32_bf16 v[120:123], v[234:237], v[144:147], v[120:123]
	v_mfma_f32_16x16x32_bf16 v[116:119], v[210:213], v[152:155], v[116:119]
	v_mfma_f32_16x16x32_bf16 v[112:115], v[234:237], v[152:155], v[112:115]
	v_mfma_f32_16x16x32_bf16 v[96:99], v[210:213], v[170:173], v[96:99]
	v_mfma_f32_16x16x32_bf16 v[88:91], v[234:237], v[170:173], v[88:91]
	v_mfma_f32_16x16x32_bf16 v[84:87], v[210:213], v[178:181], v[84:87]
	v_mfma_f32_16x16x32_bf16 v[80:83], v[234:237], v[178:181], v[80:83]
	v_mfma_f32_16x16x32_bf16 v[128:131], v[214:217], v[148:151], v[128:131]
	v_mfma_f32_16x16x32_bf16 v[120:123], v[238:241], v[148:151], v[120:123]
	v_mfma_f32_16x16x32_bf16 v[116:119], v[214:217], v[156:159], v[116:119]
	v_mfma_f32_16x16x32_bf16 v[112:115], v[238:241], v[156:159], v[112:115]
	v_mfma_f32_16x16x32_bf16 v[96:99], v[214:217], v[174:177], v[96:99]
	v_mfma_f32_16x16x32_bf16 v[88:91], v[238:241], v[174:177], v[88:91]
	v_mfma_f32_16x16x32_bf16 v[84:87], v[214:217], v[188:191], v[84:87]
	v_mfma_f32_16x16x32_bf16 v[80:83], v[238:241], v[188:191], v[80:83]
	s_mov_b32 m0, s39
	v_lshl_add_u64 v[182:183], v[200:201], 0, s[58:59]
	s_barrier
; #define MEMBAR() asm volatile("" ::: "memory")
; DI float* modp(const Params& p, int layer, int g, int chunk) { return (float*)(p.ws + OFF_MOD) + ((size_t)(layer * 9 + g) * 6 + chunk) * 1024; }
; #define PG8_STAGE(bufoff, gbase, voff) do { _Pragma("unroll") for (int _i = 0; _i < 2; ++_i) \
;     __builtin_amdgcn_global_load_lds((const unsigned*)((const char*)(gbase) + (voff)[_i]), (LAS unsigned*)(lds + (bufoff) + ldsw + _i * 8192), 16, 0, 0); } while (0)
; #define PG8_MMA(ai, bj, At, Bt_) do { __builtin_amdgcn_s_setprio(1); _Pragma("unroll") for (int m = 0; m < 4; ++m) _Pragma("unroll") for (int n = 0; n < 2; ++n) _Pragma("unroll") for (int k = 0; k < 2; ++k) \
;     acc[ai][bj][m][n] = __builtin_amdgcn_mfma_f32_16x16x32_bf16(Bt_[n][k], At[m][k], acc[ai][bj][m][n], 0, 0, 0); __builtin_amdgcn_s_setprio(0); } while (0)
; #define PG8_WAIT_V(n) asm volatile("s_waitcnt vmcnt(" #n ")" ::: "memory")
; #define PG8_WAIT_L(n) asm volatile("s_waitcnt lgkmcnt(" #n ")" ::: "memory")
; #define PG8_BAR __builtin_amdgcn_s_barrier()
; template <class Epi>
; DI void gemm_phase(char* smem, const bf16_t* A, int lda, const bf16_t* Bt, int ldb, int K, const Order& S_, const Epi& E) {
;     ...
;       PG8_BAR; PG8_WAIT_L(0); PG8_MMA(1, 0, At, B0); PG8_BAR; PG8_SCHED;
;       PG8_STAGE(PG8_SB(1, 1), b3 + hstepB, voffB);
;       PG8_WAIT_V(6); PG8_BAR; PG8_MMA(1, 1, At, B1); PG8_BAR;
;   DI void operator()(const acc_t& acc, const Unit& u, int wr, int wc, int fr, int fq) const {
;     const int row0 = u.pm * BM + wr * 64 + fr, col0 = u.pn * BM + wc * 32 + 4 * fq;
;     const int b = u.pm / 17, g = (u.pm - b * 17) == 0 ? 8 : b;
;     const float* gate = modp(p, layer, g, chunk);
;     f32x4 gv[2][2];
; #pragma unroll
;     for (int bj = 0; bj < 2; ++bj)
; #pragma unroll
;       for (int n = 0; n < 2; ++n) gv[bj][n] = *(const f32x4*)(gate + col0 + bj * HALF + n * 16);
; #pragma unroll
;     for (int q = 0; q < 4; ++q) {
;       const int ai = q >> 1, mh = q & 1;
;       MEMBAR();
;       f32x4 xv[2][2][2];
; #pragma unroll
;       for (int mm = 0; mm < 2; ++mm) { const int t = row0 + ai * HALF + (2 * mh + mm) * 16;
;         const float* xi = from_input ? xrow_in(p, t) : xrow_ws(p, t);
; #pragma unroll
;         for (int bj = 0; bj < 2; ++bj)
; #pragma unroll
;           for (int n = 0; n < 2; ++n) xv[mm][bj][n] = *(const f32x4*)(xi + col0 + bj * HALF + n * 16); }
	ds_read_b128 v[144:147], v187 offset:49152
	ds_read_b128 v[148:151], v187 offset:50176
	ds_read_b128 v[152:155], v187 offset:51200
	ds_read_b128 v[156:159], v187 offset:52224
	ds_read_b128 v[170:173], v187 offset:53248
	ds_read_b128 v[174:177], v187 offset:54272
	ds_read_b128 v[178:181], v187 offset:55296
	ds_read_b128 v[188:191], v187 offset:56320
	global_load_lds_dwordx4 v[182:183], off
	v_lshl_add_u64 v[182:183], v[202:203], 0, s[58:59]
	s_mov_b32 m0, s49
	s_nop 0
	global_load_lds_dwordx4 v[182:183], off
	s_barrier
	s_waitcnt lgkmcnt(0)
	s_waitcnt lgkmcnt(0)
	v_mfma_f32_16x16x32_bf16 v[60:63], v[64:67], v[144:147], v[60:63]
	v_mfma_f32_16x16x32_bf16 v[56:59], v[72:75], v[144:147], v[56:59]
	v_mfma_f32_16x16x32_bf16 v[52:55], v[64:67], v[152:155], v[52:55]
	v_mfma_f32_16x16x32_bf16 v[44:47], v[72:75], v[152:155], v[44:47]
	v_mfma_f32_16x16x32_bf16 v[28:31], v[64:67], v[170:173], v[28:31]
	v_mfma_f32_16x16x32_bf16 v[24:27], v[72:75], v[170:173], v[24:27]
	v_mfma_f32_16x16x32_bf16 v[20:23], v[64:67], v[178:181], v[20:23]
	v_mfma_f32_16x16x32_bf16 v[12:15], v[72:75], v[178:181], v[12:15]
	v_mfma_f32_16x16x32_bf16 v[60:63], v[68:71], v[148:151], v[60:63]
	v_mfma_f32_16x16x32_bf16 v[56:59], v[76:79], v[148:151], v[56:59]
	v_mfma_f32_16x16x32_bf16 v[52:55], v[68:71], v[156:159], v[52:55]
	v_mfma_f32_16x16x32_bf16 v[44:47], v[76:79], v[156:159], v[44:47]
	v_mfma_f32_16x16x32_bf16 v[28:31], v[68:71], v[174:177], v[28:31]
	v_mfma_f32_16x16x32_bf16 v[24:27], v[76:79], v[174:177], v[24:27]
	v_mfma_f32_16x16x32_bf16 v[20:23], v[68:71], v[188:191], v[20:23]
	v_mfma_f32_16x16x32_bf16 v[12:15], v[76:79], v[188:191], v[12:15]
	s_barrier
	s_add_u32 s46, s46, 0x40080
	s_addc_u32 s47, s47, 0
	s_add_i32 s41, s43, s26
	v_lshl_add_u64 v[64:65], s[46:47], 0, v[220:221]
	s_mov_b32 m0, s41
	s_nop 0
	global_load_lds_dwordx4 v[64:65], off
	v_lshl_add_u64 v[64:65], s[46:47], 0, v[164:165]
	s_add_i32 m0, s41, 0x2000
	s_nop 0
	global_load_lds_dwordx4 v[64:65], off
	s_waitcnt vmcnt(6)
	s_barrier
	v_mfma_f32_16x16x32_bf16 v[48:51], v[210:213], v[144:147], v[48:51]
	v_mfma_f32_16x16x32_bf16 v[40:43], v[234:237], v[144:147], v[40:43]
	v_mfma_f32_16x16x32_bf16 v[36:39], v[210:213], v[152:155], v[36:39]
	v_mfma_f32_16x16x32_bf16 v[32:35], v[234:237], v[152:155], v[32:35]
	v_mfma_f32_16x16x32_bf16 v[16:19], v[210:213], v[170:173], v[16:19]
	v_mfma_f32_16x16x32_bf16 v[8:11], v[234:237], v[170:173], v[8:11]
	v_mfma_f32_16x16x32_bf16 v[4:7], v[210:213], v[178:181], v[4:7]
	v_mfma_f32_16x16x32_bf16 v[0:3], v[234:237], v[178:181], v[0:3]
	v_mfma_f32_16x16x32_bf16 v[48:51], v[214:217], v[148:151], v[48:51]
	v_mfma_f32_16x16x32_bf16 v[40:43], v[238:241], v[148:151], v[40:43]
	v_mfma_f32_16x16x32_bf16 v[36:39], v[214:217], v[156:159], v[36:39]
	v_mfma_f32_16x16x32_bf16 v[32:35], v[238:241], v[156:159], v[32:35]
	v_mfma_f32_16x16x32_bf16 v[16:19], v[214:217], v[174:177], v[16:19]
	v_mfma_f32_16x16x32_bf16 v[8:11], v[238:241], v[174:177], v[8:11]
	v_mfma_f32_16x16x32_bf16 v[4:7], v[214:217], v[188:191], v[4:7]
	v_mfma_f32_16x16x32_bf16 v[0:3], v[238:241], v[188:191], v[0:3]
	s_add_i32 s29, s29, 2
	s_add_u32 s16, s16, 0x100
	s_addc_u32 s20, s20, 0
	s_cmp_gt_u32 s29, 13
	s_mov_b64 s[90:91], s[0:1]
	s_barrier
	s_cbranch_scc0 .LBB0_1701
	s_mul_hi_i32 s0, s4, 0x78787879
	s_lshr_b32 s1, s0, 31
	s_ashr_i32 s0, s0, 3
	s_add_i32 s0, s0, s1
	s_mul_i32 s1, s0, 0xffffffef
	s_sub_i32 s5, 0, s4
	s_cmp_lg_u32 s1, s5
	s_cselect_b32 s0, s0, 8
	v_readlane_b32 s1, v254, 59
	s_add_i32 s0, s0, s1
	s_mul_i32 s0, s0, 6
	s_ashr_i32 s1, s0, 31
	s_lshl_b64 s[0:1], s[0:1], 12
	v_readlane_b32 s5, v253, 27
	v_lshl_or_b32 v172, s42, 8, v186
	s_add_u32 s0, s5, s0
	v_readlane_b32 s5, v253, 28
	s_addc_u32 s1, s5, s1
	v_ashrrev_i32_e32 v173, 31, v172
	v_lshl_add_u64 v[64:65], v[172:173], 2, s[0:1]
	global_load_dwordx4 v[76:79], v[64:65], off
	global_load_dwordx4 v[72:75], v[64:65], off offset:64
	global_load_dwordx4 v[68:71], v[64:65], off offset:512
	s_nop 0
	global_load_dwordx4 v[64:67], v[64:65], off offset:576
	v_lshl_add_u32 v188, s4, 8, v184
	s_mov_b32 s51, 0x78787879
	v_mul_hi_i32 v144, v188, s51
	v_lshrrev_b32_e32 v145, 31, v144
	v_ashrrev_i32_e32 v144, 11, v144
	v_add_u32_e32 v144, v144, v145
	s_movk_i32 s4, 0xef00
	v_mad_i32_i24 v145, v144, s4, v188
	v_readlane_b32 s90, v254, 51
	s_movk_i32 s50, 0x100
	v_readlane_b32 s91, v254, 52
	v_ashrrev_i32_e32 v146, 31, v145
	v_add_u32_e32 v147, 0xffffff00, v145
	v_cmp_gt_i32_e64 s[0:1], s50, v145
	s_mov_b64 s[42:43], -1
	s_and_b64 vcc, exec, s[90:91]
	v_cndmask_b32_e64 v175, 0, v146, s[0:1]
	v_cndmask_b32_e64 v174, v147, v145, s[0:1]
	v_readlane_b32 s29, v254, 42
	s_cbranch_vccz .LBB0_1704
	v_mov_b32_e32 v145, s93
	v_mov_b32_e32 v146, s83
	v_cndmask_b32_e64 v147, v145, v146, s[0:1]
	v_mov_b32_e32 v145, s92
	v_mov_b32_e32 v146, s29
	v_cndmask_b32_e64 v146, v145, v146, s[0:1]
	s_mov_b64 s[42:43], 0

; #define PG8_STAGE(bufoff, gbase, voff) do { _Pragma("unroll") for (int _i = 0; _i < 2; ++_i) \
;     __builtin_amdgcn_global_load_lds((const unsigned*)((const char*)(gbase) + (voff)[_i]), (LAS unsigned*)(lds + (bufoff) + ldsw + _i * 8192), 16, 0, 0); } while (0)
; #define PG8_LDA(dst, b, h) do { _Pragma("unroll") for (int m = 0; m < 4; ++m) _Pragma("unroll") for (int k = 0; k < 2; ++k) dst[m][k] = *(const LAS bf16x8*)(lds + PG8_SA(b, h) + aoff + m * 2048 + k * 1024); } while (0)
; #define PG8_LDB(dst, b, h) do { _Pragma("unroll") for (int n = 0; n < 2; ++n) _Pragma("unroll") for (int k = 0; k < 2; ++k) dst[n][k] = *(const LAS bf16x8*)(lds + PG8_SB(b, h) + boff + n * 2048 + k * 1024); } while (0)
; #define PG8_MMA(ai, bj, At, Bt_) do { __builtin_amdgcn_s_setprio(1); _Pragma("unroll") for (int m = 0; m < 4; ++m) _Pragma("unroll") for (int n = 0; n < 2; ++n) _Pragma("unroll") for (int k = 0; k < 2; ++k) \
;     acc[ai][bj][m][n] = __builtin_amdgcn_mfma_f32_16x16x32_bf16(Bt_[n][k], At[m][k], acc[ai][bj][m][n], 0, 0, 0); __builtin_amdgcn_s_setprio(0); } while (0)
; #define PG8_WAIT_L(n) asm volatile("s_waitcnt lgkmcnt(" #n ")" ::: "memory")
; #define PG8_BAR __builtin_amdgcn_s_barrier()
; #define PG8_SCHED __builtin_amdgcn_sched_barrier(0)
; #define PG8_WAIT_L(n) asm volatile("s_waitcnt lgkmcnt(" #n ")" ::: "memory")
; #define PG8_BAR __builtin_amdgcn_s_barrier()
; #define PG8_SCHED __builtin_amdgcn_sched_barrier(0)
; template <class Epi>
; DI void gemm_phase(char* smem, const bf16_t* A, int lda, const bf16_t* Bt, int ldb, int K, const Order& S_, const Epi& E) {
;     ...
;     for (int t = 0; t < nt; t += 2) {
;       const bool last = (t == nt - 2);
;       const char* a1 = cA + (size_t)(t + 1) * kstep;
;       const char* a2 = last ? nA : cA + (size_t)(t + 2) * kstep; const char* b2 = last ? nB : cB + (size_t)(t + 2) * kstep;
;       const char* a3 = a2 + kstep; const char* b3 = b2 + kstep;
;       PG8_LDB(B0, 0, 0); PG8_SCHED; PG8_LDA(At, 0, 0); PG8_STAGE(PG8_SA(1, 1), a1 + hstepA, voffA);
;       PG8_WAIT_L(8); PG8_BAR; PG8_WAIT_L(0); PG8_MMA(0, 0, At, B0); PG8_BAR; PG8_SCHED;
;       PG8_LDB(B1, 0, 1); PG8_STAGE(PG8_SB(0, 0), b2, voffB);
;       PG8_BAR; PG8_WAIT_L(0); PG8_MMA(0, 1, At, B1); PG8_BAR;
;       PG8_LDA(At, 0, 1); PG8_STAGE(PG8_SA(0, 0), a2, voffA);
;       PG8_BAR; PG8_WAIT_L(0); PG8_MMA(1, 0, At, B0); PG8_BAR; PG8_SCHED;
.LBB0_1858:
	s_add_u32 s42, vcc_lo, 0xfffc0080
	s_addc_u32 s43, vcc_hi, -1
	s_add_i32 s52, 0, 0x10000
	v_add_u32_e32 v154, s52, v139
	ds_read_b128 v[142:145], v154
	ds_read_b128 v[146:149], v154 offset:1024
	ds_read_b128 v[150:153], v154 offset:2048
	ds_read_b128 v[154:157], v154 offset:3072
	s_cmp_eq_u32 s41, 12
	s_cselect_b32 s89, s4, s43
	s_cselect_b32 s88, s5, s42
	s_cselect_b32 s43, s15, s29
	s_cselect_b32 s42, s16, s20
	v_lshl_add_u64 v[190:191], vcc, 0, v[134:135]
	s_add_i32 m0, s1, 0xc000
	ds_read_b128 v[158:161], v141
	ds_read_b128 v[162:165], v141 offset:1024
	ds_read_b128 v[166:169], v141 offset:2048
	ds_read_b128 v[170:173], v141 offset:3072
	ds_read_b128 v[174:177], v141 offset:4096
	ds_read_b128 v[178:181], v141 offset:5120
	ds_read_b128 v[182:185], v141 offset:6144
	ds_read_b128 v[186:189], v141 offset:7168
	global_load_lds_dwordx4 v[190:191], off
	v_lshl_add_u64 v[190:191], vcc, 0, v[136:137]
	s_add_i32 m0, s1, 0xe000
	s_nop 0
	global_load_lds_dwordx4 v[190:191], off
	s_waitcnt lgkmcnt(8)
	s_barrier
	s_waitcnt lgkmcnt(0)
	s_waitcnt lgkmcnt(0)
	v_mfma_f32_16x16x32_bf16 v[124:127], v[142:145], v[158:161], v[124:127]
	v_mfma_f32_16x16x32_bf16 v[116:119], v[150:153], v[158:161], v[116:119]
	v_mfma_f32_16x16x32_bf16 v[108:111], v[142:145], v[166:169], v[108:111]
	v_mfma_f32_16x16x32_bf16 v[100:103], v[150:153], v[166:169], v[100:103]
	v_mfma_f32_16x16x32_bf16 v[92:95], v[142:145], v[174:177], v[92:95]
	v_mfma_f32_16x16x32_bf16 v[84:87], v[150:153], v[174:177], v[84:87]
	v_mfma_f32_16x16x32_bf16 v[76:79], v[142:145], v[182:185], v[76:79]
	v_mfma_f32_16x16x32_bf16 v[68:71], v[150:153], v[182:185], v[68:71]
	v_mfma_f32_16x16x32_bf16 v[124:127], v[146:149], v[162:165], v[124:127]
	v_mfma_f32_16x16x32_bf16 v[116:119], v[154:157], v[162:165], v[116:119]
	v_mfma_f32_16x16x32_bf16 v[108:111], v[146:149], v[170:173], v[108:111]
	v_mfma_f32_16x16x32_bf16 v[100:103], v[154:157], v[170:173], v[100:103]
	v_mfma_f32_16x16x32_bf16 v[92:95], v[146:149], v[178:181], v[92:95]
	v_mfma_f32_16x16x32_bf16 v[84:87], v[154:157], v[178:181], v[84:87]
	v_mfma_f32_16x16x32_bf16 v[76:79], v[146:149], v[186:189], v[76:79]
	v_mfma_f32_16x16x32_bf16 v[68:71], v[154:157], v[186:189], v[68:71]
	s_barrier
	s_add_i32 s56, 0, 0x14000
	v_add_u32_e32 v190, s56, v139
	s_add_i32 s52, s52, s33
	ds_read_b128 v[210:213], v190
	ds_read_b128 v[214:217], v190 offset:1024
	ds_read_b128 v[234:237], v190 offset:2048
	ds_read_b128 v[238:241], v190 offset:3072
	v_lshl_add_u64 v[190:191], s[42:43], 0, v[220:221]
	s_mov_b32 m0, s52
	v_lshl_add_u64 v[194:195], s[42:43], 0, v[132:133]
	global_load_lds_dwordx4 v[190:191], off
	s_add_i32 m0, s52, 0x2000
	s_nop 0
	global_load_lds_dwordx4 v[194:195], off
	s_barrier
	s_waitcnt lgkmcnt(0)
	s_waitcnt lgkmcnt(0)
	v_mfma_f32_16x16x32_bf16 v[120:123], v[210:213], v[158:161], v[120:123]
	v_mfma_f32_16x16x32_bf16 v[112:115], v[234:237], v[158:161], v[112:115]
	v_mfma_f32_16x16x32_bf16 v[104:107], v[210:213], v[166:169], v[104:107]
	v_mfma_f32_16x16x32_bf16 v[96:99], v[234:237], v[166:169], v[96:99]
	v_mfma_f32_16x16x32_bf16 v[88:91], v[210:213], v[174:177], v[88:91]
	v_mfma_f32_16x16x32_bf16 v[80:83], v[234:237], v[174:177], v[80:83]
	v_mfma_f32_16x16x32_bf16 v[72:75], v[210:213], v[182:185], v[72:75]
	v_mfma_f32_16x16x32_bf16 v[64:67], v[234:237], v[182:185], v[64:67]
	v_mfma_f32_16x16x32_bf16 v[120:123], v[214:217], v[162:165], v[120:123]
	v_mfma_f32_16x16x32_bf16 v[112:115], v[238:241], v[162:165], v[112:115]
	v_mfma_f32_16x16x32_bf16 v[104:107], v[214:217], v[170:173], v[104:107]
	v_mfma_f32_16x16x32_bf16 v[96:99], v[238:241], v[170:173], v[96:99]
	v_mfma_f32_16x16x32_bf16 v[88:91], v[214:217], v[178:181], v[88:91]
	v_mfma_f32_16x16x32_bf16 v[80:83], v[238:241], v[178:181], v[80:83]
	v_mfma_f32_16x16x32_bf16 v[72:75], v[214:217], v[186:189], v[72:75]
	v_mfma_f32_16x16x32_bf16 v[64:67], v[238:241], v[186:189], v[64:67]
	s_mov_b32 m0, s1
	v_lshl_add_u64 v[200:201], s[88:89], 0, v[128:129]
	s_barrier
	ds_read_b128 v[158:161], v141 offset:16384
	ds_read_b128 v[162:165], v141 offset:17408
	ds_read_b128 v[166:169], v141 offset:18432
	ds_read_b128 v[170:173], v141 offset:19456
	ds_read_b128 v[174:177], v141 offset:20480
	ds_read_b128 v[178:181], v141 offset:21504
	ds_read_b128 v[182:185], v141 offset:22528
	ds_read_b128 v[186:189], v141 offset:23552
	global_load_lds_dwordx4 v[200:201], off
	v_lshl_add_u64 v[202:203], s[88:89], 0, v[130:131]
	s_mov_b32 m0, s34
	s_nop 0
	global_load_lds_dwordx4 v[202:203], off
	s_barrier
	s_waitcnt lgkmcnt(0)
	s_waitcnt lgkmcnt(0)
	v_mfma_f32_16x16x32_bf16 v[60:63], v[142:145], v[158:161], v[60:63]
	v_mfma_f32_16x16x32_bf16 v[52:55], v[150:153], v[158:161], v[52:55]
	v_mfma_f32_16x16x32_bf16 v[44:47], v[142:145], v[166:169], v[44:47]
	v_mfma_f32_16x16x32_bf16 v[36:39], v[150:153], v[166:169], v[36:39]
	v_mfma_f32_16x16x32_bf16 v[28:31], v[142:145], v[174:177], v[28:31]
	v_mfma_f32_16x16x32_bf16 v[20:23], v[150:153], v[174:177], v[20:23]
	v_mfma_f32_16x16x32_bf16 v[12:15], v[142:145], v[182:185], v[12:15]
	v_mfma_f32_16x16x32_bf16 v[4:7], v[150:153], v[182:185], v[4:7]
	v_mfma_f32_16x16x32_bf16 v[60:63], v[146:149], v[162:165], v[60:63]
	v_mfma_f32_16x16x32_bf16 v[52:55], v[154:157], v[162:165], v[52:55]
	v_mfma_f32_16x16x32_bf16 v[44:47], v[146:149], v[170:173], v[44:47]
	v_mfma_f32_16x16x32_bf16 v[36:39], v[154:157], v[170:173], v[36:39]
	v_mfma_f32_16x16x32_bf16 v[28:31], v[146:149], v[178:181], v[28:31]
	v_mfma_f32_16x16x32_bf16 v[20:23], v[154:157], v[178:181], v[20:23]
	v_mfma_f32_16x16x32_bf16 v[12:15], v[146:149], v[186:189], v[12:15]
	v_mfma_f32_16x16x32_bf16 v[4:7], v[154:157], v[186:189], v[4:7]
	s_barrier
; #define PG8_STAGE(bufoff, gbase, voff) do { _Pragma("unroll") for (int _i = 0; _i < 2; ++_i) \
;     __builtin_amdgcn_global_load_lds((const unsigned*)((const char*)(gbase) + (voff)[_i]), (LAS unsigned*)(lds + (bufoff) + ldsw + _i * 8192), 16, 0, 0); } while (0)
; #define PG8_LDA(dst, b, h) do { _Pragma("unroll") for (int m = 0; m < 4; ++m) _Pragma("unroll") for (int k = 0; k < 2; ++k) dst[m][k] = *(const LAS bf16x8*)(lds + PG8_SA(b, h) + aoff + m * 2048 + k * 1024); } while (0)
; #define PG8_LDB(dst, b, h) do { _Pragma("unroll") for (int n = 0; n < 2; ++n) _Pragma("unroll") for (int k = 0; k < 2; ++k) dst[n][k] = *(const LAS bf16x8*)(lds + PG8_SB(b, h) + boff + n * 2048 + k * 1024); } while (0)
; #define PG8_MMA(ai, bj, At, Bt_) do { __builtin_amdgcn_s_setprio(1); _Pragma("unroll") for (int m = 0; m < 4; ++m) _Pragma("unroll") for (int n = 0; n < 2; ++n) _Pragma("unroll") for (int k = 0; k < 2; ++k) \
;     acc[ai][bj][m][n] = __builtin_amdgcn_mfma_f32_16x16x32_bf16(Bt_[n][k], At[m][k], acc[ai][bj][m][n], 0, 0, 0); __builtin_amdgcn_s_setprio(0); } while (0)
; #define PG8_WAIT_V(n) asm volatile("s_waitcnt vmcnt(" #n ")" ::: "memory")
; #define PG8_WAIT_L(n) asm volatile("s_waitcnt lgkmcnt(" #n ")" ::: "memory")
; #define PG8_BAR __builtin_amdgcn_s_barrier()
; #define PG8_SCHED __builtin_amdgcn_sched_barrier(0)
; #define PG8_LDA(dst, b, h) do { _Pragma("unroll") for (int m = 0; m < 4; ++m) _Pragma("unroll") for (int k = 0; k < 2; ++k) dst[m][k] = *(const LAS bf16x8*)(lds + PG8_SA(b, h) + aoff + m * 2048 + k * 1024); } while (0)
; #define PG8_WAIT_V(n) asm volatile("s_waitcnt vmcnt(" #n ")" ::: "memory")
; template <class Epi>
; DI void gemm_phase(char* smem, const bf16_t* A, int lda, const bf16_t* Bt, int ldb, int K, const Order& S_, const Epi& E) {
;     ...
;       PG8_STAGE(PG8_SB(0, 1), b2 + hstepB, voffB);
;       PG8_WAIT_V(6); PG8_BAR; PG8_MMA(1, 1, At, B1); PG8_BAR;
;       PG8_LDB(B0, 1, 0); PG8_SCHED; PG8_LDA(At, 1, 0); PG8_STAGE(PG8_SA(0, 1), a2 + hstepA, voffA);
;       PG8_WAIT_L(8); PG8_BAR; PG8_WAIT_L(0); PG8_MMA(0, 0, At, B0); PG8_BAR; PG8_SCHED;
;       PG8_LDB(B1, 1, 1); PG8_STAGE(PG8_SB(1, 0), b3, voffB);
;       PG8_BAR; PG8_WAIT_L(0); PG8_MMA(0, 1, At, B1); PG8_BAR;
;       PG8_LDA(At, 1, 1); PG8_STAGE(PG8_SA(1, 0), a3, voffA);
;       PG8_BAR; PG8_WAIT_L(0); PG8_MMA(1, 0, At, B0); PG8_BAR; PG8_SCHED;
	s_add_u32 s52, s42, 0x40000
	s_addc_u32 s53, s43, 0
	s_add_i32 s56, s56, s33
	v_lshl_add_u64 v[142:143], s[52:53], 0, v[220:221]
	s_mov_b32 m0, s56
	s_nop 0
	global_load_lds_dwordx4 v[142:143], off
	v_lshl_add_u64 v[142:143], s[52:53], 0, v[132:133]
	s_add_i32 m0, s56, 0x2000
	s_nop 0
	global_load_lds_dwordx4 v[142:143], off
	s_waitcnt vmcnt(6)
	s_barrier
	v_mfma_f32_16x16x32_bf16 v[56:59], v[210:213], v[158:161], v[56:59]
	v_mfma_f32_16x16x32_bf16 v[48:51], v[234:237], v[158:161], v[48:51]
	v_mfma_f32_16x16x32_bf16 v[40:43], v[210:213], v[166:169], v[40:43]
	v_mfma_f32_16x16x32_bf16 v[32:35], v[234:237], v[166:169], v[32:35]
	v_mfma_f32_16x16x32_bf16 v[24:27], v[210:213], v[174:177], v[24:27]
	v_mfma_f32_16x16x32_bf16 v[16:19], v[234:237], v[174:177], v[16:19]
	v_mfma_f32_16x16x32_bf16 v[8:11], v[210:213], v[182:185], v[8:11]
	v_mfma_f32_16x16x32_bf16 v[0:3], v[234:237], v[182:185], v[0:3]
	v_mfma_f32_16x16x32_bf16 v[56:59], v[214:217], v[162:165], v[56:59]
	v_mfma_f32_16x16x32_bf16 v[48:51], v[238:241], v[162:165], v[48:51]
	v_mfma_f32_16x16x32_bf16 v[40:43], v[214:217], v[170:173], v[40:43]
	v_mfma_f32_16x16x32_bf16 v[32:35], v[238:241], v[170:173], v[32:35]
	v_mfma_f32_16x16x32_bf16 v[24:27], v[214:217], v[178:181], v[24:27]
	v_mfma_f32_16x16x32_bf16 v[16:19], v[238:241], v[178:181], v[16:19]
	v_mfma_f32_16x16x32_bf16 v[8:11], v[214:217], v[186:189], v[8:11]
	v_mfma_f32_16x16x32_bf16 v[0:3], v[238:241], v[186:189], v[0:3]
	s_add_i32 s56, 0, 0x18000
	v_add_u32_e32 v154, s56, v139
	s_barrier
	ds_read_b128 v[142:145], v154
	ds_read_b128 v[146:149], v154 offset:1024
	ds_read_b128 v[150:153], v154 offset:2048
	ds_read_b128 v[154:157], v154 offset:3072
	s_add_u32 s52, s88, 0x40000
	s_addc_u32 s53, s89, 0
	s_mov_b32 m0, s38
	v_lshl_add_u64 v[208:209], s[52:53], 0, v[128:129]
	ds_read_b128 v[158:161], v141 offset:32768
	ds_read_b128 v[162:165], v141 offset:33792
	ds_read_b128 v[166:169], v141 offset:34816
	ds_read_b128 v[170:173], v141 offset:35840
	ds_read_b128 v[174:177], v141 offset:36864
	ds_read_b128 v[178:181], v141 offset:37888
	ds_read_b128 v[182:185], v141 offset:38912
	ds_read_b128 v[186:189], v141 offset:39936
	global_load_lds_dwordx4 v[208:209], off
	v_lshl_add_u64 v[208:209], s[52:53], 0, v[130:131]
	s_mov_b32 m0, s39
	s_nop 0
	global_load_lds_dwordx4 v[208:209], off
	s_waitcnt lgkmcnt(8)
	s_barrier
	s_waitcnt lgkmcnt(0)
	s_waitcnt lgkmcnt(0)
	v_mfma_f32_16x16x32_bf16 v[124:127], v[142:145], v[158:161], v[124:127]
	v_mfma_f32_16x16x32_bf16 v[116:119], v[150:153], v[158:161], v[116:119]
	v_mfma_f32_16x16x32_bf16 v[108:111], v[142:145], v[166:169], v[108:111]
	v_mfma_f32_16x16x32_bf16 v[100:103], v[150:153], v[166:169], v[100:103]
	v_mfma_f32_16x16x32_bf16 v[92:95], v[142:145], v[174:177], v[92:95]
	v_mfma_f32_16x16x32_bf16 v[84:87], v[150:153], v[174:177], v[84:87]
	v_mfma_f32_16x16x32_bf16 v[76:79], v[142:145], v[182:185], v[76:79]
	v_mfma_f32_16x16x32_bf16 v[68:71], v[150:153], v[182:185], v[68:71]
	v_mfma_f32_16x16x32_bf16 v[124:127], v[146:149], v[162:165], v[124:127]
	v_mfma_f32_16x16x32_bf16 v[116:119], v[154:157], v[162:165], v[116:119]
	v_mfma_f32_16x16x32_bf16 v[108:111], v[146:149], v[170:173], v[108:111]
	v_mfma_f32_16x16x32_bf16 v[100:103], v[154:157], v[170:173], v[100:103]
	v_mfma_f32_16x16x32_bf16 v[92:95], v[146:149], v[178:181], v[92:95]
	v_mfma_f32_16x16x32_bf16 v[84:87], v[154:157], v[178:181], v[84:87]
	v_mfma_f32_16x16x32_bf16 v[76:79], v[146:149], v[186:189], v[76:79]
	v_mfma_f32_16x16x32_bf16 v[68:71], v[154:157], v[186:189], v[68:71]
	s_barrier
	s_add_i32 s52, 0, 0x1c000
	s_add_i32 s53, s56, s33
	v_add_u32_e32 v204, s52, v139
	v_lshl_add_u64 v[190:191], v[190:191], 0, s[58:59]
	s_mov_b32 m0, s53
	ds_read_b128 v[210:213], v204
	ds_read_b128 v[214:217], v204 offset:1024
	ds_read_b128 v[234:237], v204 offset:2048
	ds_read_b128 v[238:241], v204 offset:3072
	global_load_lds_dwordx4 v[190:191], off
	v_lshl_add_u64 v[190:191], v[194:195], 0, s[58:59]
	s_add_i32 m0, s53, 0x2000
	s_nop 0
	global_load_lds_dwordx4 v[190:191], off
	s_barrier
	s_waitcnt lgkmcnt(0)
	s_waitcnt lgkmcnt(0)
	v_mfma_f32_16x16x32_bf16 v[120:123], v[210:213], v[158:161], v[120:123]
	v_mfma_f32_16x16x32_bf16 v[112:115], v[234:237], v[158:161], v[112:115]
	v_mfma_f32_16x16x32_bf16 v[104:107], v[210:213], v[166:169], v[104:107]
	v_mfma_f32_16x16x32_bf16 v[96:99], v[234:237], v[166:169], v[96:99]
	v_mfma_f32_16x16x32_bf16 v[88:91], v[210:213], v[174:177], v[88:91]
	v_mfma_f32_16x16x32_bf16 v[80:83], v[234:237], v[174:177], v[80:83]
	v_mfma_f32_16x16x32_bf16 v[72:75], v[210:213], v[182:185], v[72:75]
	v_mfma_f32_16x16x32_bf16 v[64:67], v[234:237], v[182:185], v[64:67]
	v_mfma_f32_16x16x32_bf16 v[120:123], v[214:217], v[162:165], v[120:123]
	v_mfma_f32_16x16x32_bf16 v[112:115], v[238:241], v[162:165], v[112:115]
	v_mfma_f32_16x16x32_bf16 v[104:107], v[214:217], v[170:173], v[104:107]
	v_mfma_f32_16x16x32_bf16 v[96:99], v[238:241], v[170:173], v[96:99]
	v_mfma_f32_16x16x32_bf16 v[88:91], v[214:217], v[178:181], v[88:91]
	v_mfma_f32_16x16x32_bf16 v[80:83], v[238:241], v[178:181], v[80:83]
	v_mfma_f32_16x16x32_bf16 v[72:75], v[214:217], v[186:189], v[72:75]
	v_mfma_f32_16x16x32_bf16 v[64:67], v[238:241], v[186:189], v[64:67]
	s_mov_b32 m0, s47
	v_lshl_add_u64 v[190:191], v[200:201], 0, s[58:59]
	s_barrier
	ds_read_b128 v[158:161], v141 offset:49152
	ds_read_b128 v[162:165], v141 offset:50176
	ds_read_b128 v[166:169], v141 offset:51200
	ds_read_b128 v[170:173], v141 offset:52224
	ds_read_b128 v[174:177], v141 offset:53248
	ds_read_b128 v[178:181], v141 offset:54272
	ds_read_b128 v[182:185], v141 offset:55296
	ds_read_b128 v[186:189], v141 offset:56320
	global_load_lds_dwordx4 v[190:191], off
	v_lshl_add_u64 v[190:191], v[202:203], 0, s[58:59]
	s_mov_b32 m0, s49
	s_nop 0
	global_load_lds_dwordx4 v[190:191], off
	s_barrier
; DI float siluf_(float x) { return x * sigmoidf_(x); }
; #define PG8_STAGE(bufoff, gbase, voff) do { _Pragma("unroll") for (int _i = 0; _i < 2; ++_i) \
;     __builtin_amdgcn_global_load_lds((const unsigned*)((const char*)(gbase) + (voff)[_i]), (LAS unsigned*)(lds + (bufoff) + ldsw + _i * 8192), 16, 0, 0); } while (0)
; #define PG8_MMA(ai, bj, At, Bt_) do { __builtin_amdgcn_s_setprio(1); _Pragma("unroll") for (int m = 0; m < 4; ++m) _Pragma("unroll") for (int n = 0; n < 2; ++n) _Pragma("unroll") for (int k = 0; k < 2; ++k) \
;     acc[ai][bj][m][n] = __builtin_amdgcn_mfma_f32_16x16x32_bf16(Bt_[n][k], At[m][k], acc[ai][bj][m][n], 0, 0, 0); __builtin_amdgcn_s_setprio(0); } while (0)
; #define PG8_WAIT_V(n) asm volatile("s_waitcnt vmcnt(" #n ")" ::: "memory")
; #define PG8_WAIT_L(n) asm volatile("s_waitcnt lgkmcnt(" #n ")" ::: "memory")
; #define PG8_BAR __builtin_amdgcn_s_barrier()
; #define PG8_SCHED __builtin_amdgcn_sched_barrier(0)
; DI u32x4 pack8v(const f32x4& a, const f32x4& b) { u32x4 w; w.x = pk2(a[0], a[1]); w.y = pk2(a[2], a[3]); w.z = pk2(b[0], b[1]); w.w = pk2(b[2], b[3]); return w; }
; #define PG8_WAIT_V(n) asm volatile("s_waitcnt vmcnt(" #n ")" ::: "memory")
; #define PG8_WAIT_L(n) asm volatile("s_waitcnt lgkmcnt(" #n ")" ::: "memory")
; #define PG8_BAR __builtin_amdgcn_s_barrier()
; #define PG8_SCHED __builtin_amdgcn_sched_barrier(0)
; template <class Epi>
; DI void gemm_phase(char* smem, const bf16_t* A, int lda, const bf16_t* Bt, int ldb, int K, const Order& S_, const Epi& E) {
;     ...
;       PG8_BAR; PG8_WAIT_L(0); PG8_MMA(1, 0, At, B0); PG8_BAR; PG8_SCHED;
;       PG8_STAGE(PG8_SB(1, 1), b3 + hstepB, voffB);
;       PG8_WAIT_V(6); PG8_BAR; PG8_MMA(1, 1, At, B1); PG8_BAR;
;   DI void operator()(const acc_t& acc, const Unit& u, int wr, int wc, int fr, int fq) const {
;     const int row0 = u.pm * BM + wr * 64 + fr, col0 = u.pn * HALF + wc * 32 + 8 * fq;
; #pragma unroll
;     for (int ai = 0; ai < 2; ++ai)
; #pragma unroll
;       for (int m = 0; m < 4; ++m) {
;         f32x4 r0, r1;
; #pragma unroll
;         for (int e = 0; e < 4; ++e) { r0[e] = siluf_(acc[ai][0][m][0][e]) * acc[ai][1][m][0][e]; r1[e] = siluf_(acc[ai][0][m][1][e]) * acc[ai][1][m][1][e]; }
;         *(u32x4*)(G + (size_t)(row0 + ai * HALF + m * 16) * DFF + col0) = pack8v(r0, r1); }
	s_waitcnt lgkmcnt(0)
	s_waitcnt lgkmcnt(0)
	v_mfma_f32_16x16x32_bf16 v[60:63], v[142:145], v[158:161], v[60:63]
	v_mfma_f32_16x16x32_bf16 v[52:55], v[150:153], v[158:161], v[52:55]
	v_mfma_f32_16x16x32_bf16 v[44:47], v[142:145], v[166:169], v[44:47]
	v_mfma_f32_16x16x32_bf16 v[36:39], v[150:153], v[166:169], v[36:39]
	v_mfma_f32_16x16x32_bf16 v[28:31], v[142:145], v[174:177], v[28:31]
	v_mfma_f32_16x16x32_bf16 v[20:23], v[150:153], v[174:177], v[20:23]
	v_mfma_f32_16x16x32_bf16 v[12:15], v[142:145], v[182:185], v[12:15]
	v_mfma_f32_16x16x32_bf16 v[4:7], v[150:153], v[182:185], v[4:7]
	v_mfma_f32_16x16x32_bf16 v[60:63], v[146:149], v[162:165], v[60:63]
	v_mfma_f32_16x16x32_bf16 v[52:55], v[154:157], v[162:165], v[52:55]
	v_mfma_f32_16x16x32_bf16 v[44:47], v[146:149], v[170:173], v[44:47]
	v_mfma_f32_16x16x32_bf16 v[36:39], v[154:157], v[170:173], v[36:39]
	v_mfma_f32_16x16x32_bf16 v[28:31], v[146:149], v[178:181], v[28:31]
	v_mfma_f32_16x16x32_bf16 v[20:23], v[154:157], v[178:181], v[20:23]
	v_mfma_f32_16x16x32_bf16 v[12:15], v[146:149], v[186:189], v[12:15]
	v_mfma_f32_16x16x32_bf16 v[4:7], v[154:157], v[186:189], v[4:7]
	s_barrier
	s_add_u32 s42, s42, 0x40080
	s_addc_u32 s43, s43, 0
	s_add_i32 s52, s52, s33
	v_lshl_add_u64 v[142:143], s[42:43], 0, v[220:221]
	s_mov_b32 m0, s52
	s_nop 0
	global_load_lds_dwordx4 v[142:143], off
	v_lshl_add_u64 v[142:143], s[42:43], 0, v[132:133]
	s_add_i32 m0, s52, 0x2000
	s_nop 0
	global_load_lds_dwordx4 v[142:143], off
	s_waitcnt vmcnt(6)
	s_barrier
	v_mfma_f32_16x16x32_bf16 v[56:59], v[210:213], v[158:161], v[56:59]
	v_mfma_f32_16x16x32_bf16 v[48:51], v[234:237], v[158:161], v[48:51]
	v_mfma_f32_16x16x32_bf16 v[40:43], v[210:213], v[166:169], v[40:43]
	v_mfma_f32_16x16x32_bf16 v[32:35], v[234:237], v[166:169], v[32:35]
	v_mfma_f32_16x16x32_bf16 v[24:27], v[210:213], v[174:177], v[24:27]
	v_mfma_f32_16x16x32_bf16 v[16:19], v[234:237], v[174:177], v[16:19]
	v_mfma_f32_16x16x32_bf16 v[8:11], v[210:213], v[182:185], v[8:11]
	v_mfma_f32_16x16x32_bf16 v[0:3], v[234:237], v[182:185], v[0:3]
	v_mfma_f32_16x16x32_bf16 v[56:59], v[214:217], v[162:165], v[56:59]
	v_mfma_f32_16x16x32_bf16 v[48:51], v[238:241], v[162:165], v[48:51]
	v_mfma_f32_16x16x32_bf16 v[40:43], v[214:217], v[170:173], v[40:43]
	v_mfma_f32_16x16x32_bf16 v[32:35], v[238:241], v[170:173], v[32:35]
	v_mfma_f32_16x16x32_bf16 v[24:27], v[214:217], v[178:181], v[24:27]
	v_mfma_f32_16x16x32_bf16 v[16:19], v[238:241], v[178:181], v[16:19]
	v_mfma_f32_16x16x32_bf16 v[8:11], v[214:217], v[186:189], v[8:11]
	v_mfma_f32_16x16x32_bf16 v[0:3], v[238:241], v[186:189], v[0:3]
	s_add_i32 s41, s41, 2
	s_add_u32 vcc_lo, vcc_lo, 0x100
	s_addc_u32 vcc_hi, vcc_hi, 0
	s_add_u32 s20, s20, 0x100
	s_addc_u32 s29, s29, 0
	s_cmp_gt_u32 s41, 13
	s_barrier
	s_cbranch_scc0 .LBB0_1858
	v_mul_f32_e32 v143, 0xbfb8aa3b, v124
	v_exp_f32_e32 v143, v143
	v_readlane_b32 s4, v254, 43
	v_lshl_or_b32 v144, s0, 7, v140
	v_readlane_b32 s5, v254, 44
	v_add_f32_e32 v143, 1.0, v143
	v_rcp_f32_e32 v146, v143
	v_mul_f32_e32 v143, 0xbfb8aa3b, v116
	v_exp_f32_e32 v143, v143
	v_lshl_add_u32 v142, s46, 8, v138
	v_ashrrev_i32_e32 v145, 31, v144
	s_and_b64 vcc, exec, s[36:37]
	v_add_f32_e32 v143, 1.0, v143
	v_rcp_f32_e32 v148, v143
	v_mul_f32_e32 v143, 0xbfb8aa3b, v125
	v_exp_f32_e32 v143, v143
	s_mov_b32 s0, s90
	s_mov_b32 s46, s40
	s_mov_b64 s[88:89], s[44:45]
	v_add_f32_e32 v143, 1.0, v143
	v_rcp_f32_e32 v147, v143
	s_mov_b64 s[42:43], s[50:51]
	s_mov_b32 s51, 0x78787879
	v_pk_mul_f32 v[124:125], v[124:125], v[146:147]
	s_nop 0
	v_pk_mul_f32 v[120:121], v[124:125], v[120:121]
	v_mul_f32_e32 v124, 0xbfb8aa3b, v117
	v_exp_f32_e32 v124, v124
	s_nop 0
	v_add_f32_e32 v124, 1.0, v124
	v_rcp_f32_e32 v149, v124
	s_nop 0
	v_pk_mul_f32 v[116:117], v[116:117], v[148:149]
	s_nop 0
	v_pk_mul_f32 v[112:113], v[116:117], v[112:113]
	v_mul_f32_e32 v117, 0xbfb8aa3b, v118
	v_exp_f32_e32 v117, v117
	v_mul_f32_e32 v116, 0xbfb8aa3b, v126
	v_exp_f32_e32 v116, v116
	v_add_f32_e32 v117, 1.0, v117
	v_rcp_f32_e32 v124, v117
	v_mul_f32_e32 v117, 0xbfb8aa3b, v127
	v_exp_f32_e32 v117, v117
	v_add_f32_e32 v116, 1.0, v116
	v_rcp_f32_e32 v116, v116
	v_add_f32_e32 v117, 1.0, v117
	v_rcp_f32_e32 v117, v117
	s_nop 0
	v_pk_mul_f32 v[116:117], v[126:127], v[116:117]
	s_nop 0
	v_pk_mul_f32 v[122:123], v[116:117], v[122:123]
	v_mul_f32_e32 v116, 0xbfb8aa3b, v119
	v_exp_f32_e32 v116, v116
	s_nop 0
	v_add_f32_e32 v116, 1.0, v116
	v_rcp_f32_e32 v125, v116
	s_nop 0
	v_pk_mul_f32 v[116:117], v[118:119], v[124:125]
	s_nop 0
	v_pk_mul_f32 v[114:115], v[116:117], v[114:115]
	v_cvt_pk_bf16_f32 v118, v112, v113
	v_mov_b64_e32 v[112:113], s[4:5]
	v_cvt_pk_bf16_f32 v116, v120, v121
	v_cvt_pk_bf16_f32 v119, v114, v115
	v_mad_i64_i32 v[120:121], s[4:5], v142, s18, v[112:113]
	v_lshlrev_b64 v[114:115], 1, v[144:145]
	v_cvt_pk_bf16_f32 v117, v122, v123
	v_lshl_add_u64 v[120:121], v[120:121], 0, v[114:115]
	global_store_dwordx4 v[120:121], v[116:119], off
	s_nop 1
	v_mul_f32_e32 v117, 0xbfb8aa3b, v100
	v_exp_f32_e32 v117, v117
	v_mul_f32_e32 v116, 0xbfb8aa3b, v108
	v_exp_f32_e32 v116, v116
	v_add_f32_e32 v117, 1.0, v117
	v_rcp_f32_e32 v118, v117
	v_mul_f32_e32 v117, 0xbfb8aa3b, v109
	v_exp_f32_e32 v117, v117
	v_add_f32_e32 v116, 1.0, v116
	v_rcp_f32_e32 v116, v116
	v_add_f32_e32 v117, 1.0, v117
	v_rcp_f32_e32 v117, v117
	s_nop 0
	v_pk_mul_f32 v[108:109], v[108:109], v[116:117]
	s_nop 0
	v_pk_mul_f32 v[104:105], v[108:109], v[104:105]
	v_mul_f32_e32 v108, 0xbfb8aa3b, v101
	v_exp_f32_e32 v108, v108
	s_nop 0
	v_add_f32_e32 v108, 1.0, v108
	v_rcp_f32_e32 v119, v108
	s_nop 0
	v_pk_mul_f32 v[100:101], v[100:101], v[118:119]
	s_nop 0
; DI float siluf_(float x) { return x * sigmoidf_(x); }
; DI u32x4 pack8v(const f32x4& a, const f32x4& b) { u32x4 w; w.x = pk2(a[0], a[1]); w.y = pk2(a[2], a[3]); w.z = pk2(b[0], b[1]); w.w = pk2(b[2], b[3]); return w; }
;   DI void operator()(const acc_t& acc, const Unit& u, int wr, int wc, int fr, int fq) const {
;     const int row0 = u.pm * BM + wr * 64 + fr, col0 = u.pn * HALF + wc * 32 + 8 * fq;
; #pragma unroll
;     for (int ai = 0; ai < 2; ++ai)
; #pragma unroll
;       for (int m = 0; m < 4; ++m) {
;         f32x4 r0, r1;
; #pragma unroll
;         for (int e = 0; e < 4; ++e) { r0[e] = siluf_(acc[ai][0][m][0][e]) * acc[ai][1][m][0][e]; r1[e] = siluf_(acc[ai][0][m][1][e]) * acc[ai][1][m][1][e]; }
;         *(u32x4*)(G + (size_t)(row0 + ai * HALF + m * 16) * DFF + col0) = pack8v(r0, r1); }
	v_pk_mul_f32 v[100:101], v[100:101], v[96:97]
	v_mul_f32_e32 v97, 0xbfb8aa3b, v102
	v_exp_f32_e32 v97, v97
	v_mul_f32_e32 v96, 0xbfb8aa3b, v110
	v_exp_f32_e32 v96, v96
	v_add_f32_e32 v97, 1.0, v97
	v_rcp_f32_e32 v108, v97
	v_mul_f32_e32 v97, 0xbfb8aa3b, v111
	v_exp_f32_e32 v97, v97
	v_add_f32_e32 v96, 1.0, v96
	v_rcp_f32_e32 v96, v96
	v_add_f32_e32 v97, 1.0, v97
	v_rcp_f32_e32 v97, v97
	s_nop 0
	v_pk_mul_f32 v[96:97], v[110:111], v[96:97]
	s_nop 0
	v_pk_mul_f32 v[106:107], v[96:97], v[106:107]
	v_mul_f32_e32 v96, 0xbfb8aa3b, v103
	v_exp_f32_e32 v96, v96
	s_nop 0
	v_add_f32_e32 v96, 1.0, v96
	v_rcp_f32_e32 v109, v96
	s_nop 0
	v_pk_mul_f32 v[96:97], v[102:103], v[108:109]
	s_nop 0
	v_pk_mul_f32 v[102:103], v[96:97], v[98:99]
	v_cvt_pk_bf16_f32 v98, v100, v101
	v_or_b32_e32 v100, 16, v142
	v_mad_i64_i32 v[100:101], s[4:5], v100, s18, v[112:113]
	v_cvt_pk_bf16_f32 v96, v104, v105
	v_cvt_pk_bf16_f32 v97, v106, v107
	v_cvt_pk_bf16_f32 v99, v102, v103
	v_lshl_add_u64 v[100:101], v[100:101], 0, v[114:115]
	global_store_dwordx4 v[100:101], v[96:99], off
	s_nop 1
	v_mul_f32_e32 v97, 0xbfb8aa3b, v84
	v_exp_f32_e32 v97, v97
	v_mul_f32_e32 v96, 0xbfb8aa3b, v92
	v_exp_f32_e32 v96, v96
	v_add_f32_e32 v97, 1.0, v97
	v_rcp_f32_e32 v98, v97
	v_mul_f32_e32 v97, 0xbfb8aa3b, v93
	v_exp_f32_e32 v97, v97
	v_add_f32_e32 v96, 1.0, v96
	v_rcp_f32_e32 v96, v96
	v_add_f32_e32 v97, 1.0, v97
	v_rcp_f32_e32 v97, v97
	s_nop 0
	v_pk_mul_f32 v[92:93], v[92:93], v[96:97]
	s_nop 0
	v_pk_mul_f32 v[88:89], v[92:93], v[88:89]
	v_mul_f32_e32 v92, 0xbfb8aa3b, v85
	v_exp_f32_e32 v92, v92
	s_nop 0
	v_add_f32_e32 v92, 1.0, v92
	v_rcp_f32_e32 v99, v92
	s_nop 0
	v_pk_mul_f32 v[84:85], v[84:85], v[98:99]
	s_nop 0
	v_pk_mul_f32 v[84:85], v[84:85], v[80:81]
	v_mul_f32_e32 v81, 0xbfb8aa3b, v86
	v_exp_f32_e32 v81, v81
	v_mul_f32_e32 v80, 0xbfb8aa3b, v94
	v_exp_f32_e32 v80, v80
	v_add_f32_e32 v81, 1.0, v81
	v_rcp_f32_e32 v92, v81
	v_mul_f32_e32 v81, 0xbfb8aa3b, v95
	v_exp_f32_e32 v81, v81
	v_add_f32_e32 v80, 1.0, v80
	v_rcp_f32_e32 v80, v80
	v_add_f32_e32 v81, 1.0, v81
	v_rcp_f32_e32 v81, v81
	s_nop 0
	v_pk_mul_f32 v[80:81], v[94:95], v[80:81]
	s_nop 0
	v_pk_mul_f32 v[90:91], v[80:81], v[90:91]
	v_mul_f32_e32 v80, 0xbfb8aa3b, v87
	v_exp_f32_e32 v80, v80
	s_nop 0
	v_add_f32_e32 v80, 1.0, v80
	v_rcp_f32_e32 v93, v80
	s_nop 0
	v_pk_mul_f32 v[80:81], v[86:87], v[92:93]
	s_nop 0
	v_pk_mul_f32 v[86:87], v[80:81], v[82:83]
	v_cvt_pk_bf16_f32 v82, v84, v85
	v_or_b32_e32 v84, 32, v142
	v_mad_i64_i32 v[84:85], s[4:5], v84, s18, v[112:113]
	v_cvt_pk_bf16_f32 v80, v88, v89
	v_cvt_pk_bf16_f32 v81, v90, v91
	v_cvt_pk_bf16_f32 v83, v86, v87
	v_lshl_add_u64 v[84:85], v[84:85], 0, v[114:115]
	global_store_dwordx4 v[84:85], v[80:83], off
	s_nop 1
	v_mul_f32_e32 v81, 0xbfb8aa3b, v68
	v_exp_f32_e32 v81, v81
	v_mul_f32_e32 v80, 0xbfb8aa3b, v76
	v_exp_f32_e32 v80, v80
	v_add_f32_e32 v81, 1.0, v81
	v_rcp_f32_e32 v82, v81
	v_mul_f32_e32 v81, 0xbfb8aa3b, v77
	v_exp_f32_e32 v81, v81
	v_add_f32_e32 v80, 1.0, v80
	v_rcp_f32_e32 v80, v80
	v_add_f32_e32 v81, 1.0, v81
	v_rcp_f32_e32 v81, v81
	s_nop 0
	v_pk_mul_f32 v[76:77], v[76:77], v[80:81]
	s_nop 0
	v_pk_mul_f32 v[72:73], v[76:77], v[72:73]
	v_mul_f32_e32 v76, 0xbfb8aa3b, v69
	v_exp_f32_e32 v76, v76
	s_nop 0
	v_add_f32_e32 v76, 1.0, v76
	v_rcp_f32_e32 v83, v76
	s_nop 0
	v_pk_mul_f32 v[68:69], v[68:69], v[82:83]
	s_nop 0
	v_pk_mul_f32 v[68:69], v[68:69], v[64:65]
	v_mul_f32_e32 v65, 0xbfb8aa3b, v70
	v_exp_f32_e32 v65, v65
	v_mul_f32_e32 v64, 0xbfb8aa3b, v78
	v_exp_f32_e32 v64, v64
	v_add_f32_e32 v65, 1.0, v65
	v_rcp_f32_e32 v76, v65
	v_mul_f32_e32 v65, 0xbfb8aa3b, v79
	v_exp_f32_e32 v65, v65
	v_add_f32_e32 v64, 1.0, v64
	v_rcp_f32_e32 v64, v64
	v_add_f32_e32 v65, 1.0, v65
	v_rcp_f32_e32 v65, v65
	s_nop 0
	v_pk_mul_f32 v[64:65], v[78:79], v[64:65]
	s_nop 0
	v_pk_mul_f32 v[74:75], v[64:65], v[74:75]
	v_mul_f32_e32 v64, 0xbfb8aa3b, v71
	v_exp_f32_e32 v64, v64
	s_nop 0
	v_add_f32_e32 v64, 1.0, v64
	v_rcp_f32_e32 v77, v64
	s_nop 0
	v_pk_mul_f32 v[64:65], v[70:71], v[76:77]
	s_nop 0
	v_pk_mul_f32 v[70:71], v[64:65], v[66:67]
	v_cvt_pk_bf16_f32 v66, v68, v69
	v_or_b32_e32 v68, 48, v142
	v_mad_i64_i32 v[68:69], s[4:5], v68, s18, v[112:113]
	v_cvt_pk_bf16_f32 v64, v72, v73
	v_cvt_pk_bf16_f32 v65, v74, v75
	v_cvt_pk_bf16_f32 v67, v70, v71
	v_lshl_add_u64 v[68:69], v[68:69], 0, v[114:115]
	global_store_dwordx4 v[68:69], v[64:67], off
	v_add_u32_e32 v68, 0x80, v142
	s_nop 0
	v_mul_f32_e32 v65, 0xbfb8aa3b, v52
	v_exp_f32_e32 v65, v65
	v_mul_f32_e32 v64, 0xbfb8aa3b, v60
	v_exp_f32_e32 v64, v64
	v_add_f32_e32 v65, 1.0, v65
	v_rcp_f32_e32 v66, v65
	v_mul_f32_e32 v65, 0xbfb8aa3b, v61
	v_exp_f32_e32 v65, v65
	v_add_f32_e32 v64, 1.0, v64
	v_rcp_f32_e32 v64, v64
	v_add_f32_e32 v65, 1.0, v65
	v_rcp_f32_e32 v65, v65
	s_nop 0
	v_pk_mul_f32 v[60:61], v[60:61], v[64:65]
	s_nop 0
	v_pk_mul_f32 v[56:57], v[60:61], v[56:57]
	v_mul_f32_e32 v60, 0xbfb8aa3b, v53
	v_exp_f32_e32 v60, v60
	s_nop 0
	v_add_f32_e32 v60, 1.0, v60
	v_rcp_f32_e32 v67, v60
	s_nop 0
	v_pk_mul_f32 v[52:53], v[52:53], v[66:67]
	s_nop 0
	v_pk_mul_f32 v[52:53], v[52:53], v[48:49]
	v_mul_f32_e32 v49, 0xbfb8aa3b, v54
	v_exp_f32_e32 v49, v49
	v_mul_f32_e32 v48, 0xbfb8aa3b, v62
	v_exp_f32_e32 v48, v48
	v_add_f32_e32 v49, 1.0, v49
	v_rcp_f32_e32 v60, v49
	v_mul_f32_e32 v49, 0xbfb8aa3b, v63
	v_exp_f32_e32 v49, v49
	v_add_f32_e32 v48, 1.0, v48
	v_rcp_f32_e32 v48, v48
	v_add_f32_e32 v49, 1.0, v49
	v_rcp_f32_e32 v49, v49
	s_nop 0
	v_pk_mul_f32 v[48:49], v[62:63], v[48:49]
	s_nop 0
	v_pk_mul_f32 v[58:59], v[48:49], v[58:59]
; DI float siluf_(float x) { return x * sigmoidf_(x); }
; #define PG8_WAIT_V(n) asm volatile("s_waitcnt vmcnt(" #n ")" ::: "memory")
; #define PG8_BAR __builtin_amdgcn_s_barrier()
; DI u32x4 pack8v(const f32x4& a, const f32x4& b) { u32x4 w; w.x = pk2(a[0], a[1]); w.y = pk2(a[2], a[3]); w.z = pk2(b[0], b[1]); w.w = pk2(b[2], b[3]); return w; }
; #define PG8_WAIT_V(n) asm volatile("s_waitcnt vmcnt(" #n ")" ::: "memory")
; #define PG8_BAR __builtin_amdgcn_s_barrier()
; template <class Epi>
; DI void gemm_phase(char* smem, const bf16_t* A, int lda, const bf16_t* Bt, int ldb, int K, const Order& S_, const Epi& E) {
;     ...
;     if (!has_next) break;
; #pragma unroll
;     for (int a = 0; a < 2; ++a)
; #pragma unroll
;       for (int b = 0; b < 2; ++b)
; #pragma unroll
;         for (int m = 0; m < 4; ++m)
; #pragma unroll
;           for (int n = 0; n < 2; ++n) acc[a][b][m][n] = (f32x4){0.f, 0.f, 0.f, 0.f};
;     cur = nxt; cA = nA; cB = nB; ++ui;
;   }
;   PG8_WAIT_V(0);
;   if (wr == 0) PG8_BAR;
;   PG8_BAR;
;   DI void operator()(const acc_t& acc, const Unit& u, int wr, int wc, int fr, int fq) const {
;     ...
;     for (int ai = 0; ai < 2; ++ai)
; #pragma unroll
;       for (int m = 0; m < 4; ++m) {
;         f32x4 r0, r1;
; #pragma unroll
;         for (int e = 0; e < 4; ++e) { r0[e] = siluf_(acc[ai][0][m][0][e]) * acc[ai][1][m][0][e]; r1[e] = siluf_(acc[ai][0][m][1][e]) * acc[ai][1][m][1][e]; }
;         *(u32x4*)(G + (size_t)(row0 + ai * HALF + m * 16) * DFF + col0) = pack8v(r0, r1); }
	v_mul_f32_e32 v48, 0xbfb8aa3b, v55
	v_exp_f32_e32 v48, v48
	s_nop 0
	v_add_f32_e32 v48, 1.0, v48
	v_rcp_f32_e32 v61, v48
	s_nop 0
	v_pk_mul_f32 v[48:49], v[54:55], v[60:61]
	s_nop 0
	v_pk_mul_f32 v[54:55], v[48:49], v[50:51]
	v_cvt_pk_bf16_f32 v50, v52, v53
	v_mad_i64_i32 v[52:53], s[4:5], v68, s18, v[112:113]
	v_cvt_pk_bf16_f32 v48, v56, v57
	v_cvt_pk_bf16_f32 v49, v58, v59
	v_cvt_pk_bf16_f32 v51, v54, v55
	v_lshl_add_u64 v[52:53], v[52:53], 0, v[114:115]
	global_store_dwordx4 v[52:53], v[48:51], off
	s_nop 1
	v_mul_f32_e32 v49, 0xbfb8aa3b, v36
	v_exp_f32_e32 v49, v49
	v_mul_f32_e32 v48, 0xbfb8aa3b, v44
	v_exp_f32_e32 v48, v48
	v_add_f32_e32 v49, 1.0, v49
	v_rcp_f32_e32 v50, v49
	v_mul_f32_e32 v49, 0xbfb8aa3b, v45
	v_exp_f32_e32 v49, v49
	v_add_f32_e32 v48, 1.0, v48
	v_rcp_f32_e32 v48, v48
	v_add_f32_e32 v49, 1.0, v49
	v_rcp_f32_e32 v49, v49
	s_nop 0
	v_pk_mul_f32 v[44:45], v[44:45], v[48:49]
	s_nop 0
	v_pk_mul_f32 v[40:41], v[44:45], v[40:41]
	v_mul_f32_e32 v44, 0xbfb8aa3b, v37
	v_exp_f32_e32 v44, v44
	s_nop 0
	v_add_f32_e32 v44, 1.0, v44
	v_rcp_f32_e32 v51, v44
	s_nop 0
	v_pk_mul_f32 v[36:37], v[36:37], v[50:51]
	s_nop 0
	v_pk_mul_f32 v[36:37], v[36:37], v[32:33]
	v_mul_f32_e32 v33, 0xbfb8aa3b, v38
	v_exp_f32_e32 v33, v33
	v_mul_f32_e32 v32, 0xbfb8aa3b, v46
	v_exp_f32_e32 v32, v32
	v_add_f32_e32 v33, 1.0, v33
	v_rcp_f32_e32 v44, v33
	v_mul_f32_e32 v33, 0xbfb8aa3b, v47
	v_exp_f32_e32 v33, v33
	v_add_f32_e32 v32, 1.0, v32
	v_rcp_f32_e32 v32, v32
	v_add_f32_e32 v33, 1.0, v33
	v_rcp_f32_e32 v33, v33
	s_nop 0
	v_pk_mul_f32 v[32:33], v[46:47], v[32:33]
	s_nop 0
	v_pk_mul_f32 v[42:43], v[32:33], v[42:43]
	v_mul_f32_e32 v32, 0xbfb8aa3b, v39
	v_exp_f32_e32 v32, v32
	s_nop 0
	v_add_f32_e32 v32, 1.0, v32
	v_rcp_f32_e32 v45, v32
	s_nop 0
	v_pk_mul_f32 v[32:33], v[38:39], v[44:45]
	s_nop 0
	v_pk_mul_f32 v[38:39], v[32:33], v[34:35]
	v_cvt_pk_bf16_f32 v34, v36, v37
	v_add_u32_e32 v36, 0x90, v142
	v_mad_i64_i32 v[36:37], s[4:5], v36, s18, v[112:113]
	v_cvt_pk_bf16_f32 v32, v40, v41
	v_cvt_pk_bf16_f32 v33, v42, v43
	v_cvt_pk_bf16_f32 v35, v38, v39
	v_lshl_add_u64 v[36:37], v[36:37], 0, v[114:115]
	global_store_dwordx4 v[36:37], v[32:35], off
	s_nop 1
	v_mul_f32_e32 v33, 0xbfb8aa3b, v20
	v_exp_f32_e32 v33, v33
	v_mul_f32_e32 v32, 0xbfb8aa3b, v28
	v_exp_f32_e32 v32, v32
	v_add_f32_e32 v33, 1.0, v33
	v_rcp_f32_e32 v34, v33
	v_mul_f32_e32 v33, 0xbfb8aa3b, v29
	v_exp_f32_e32 v33, v33
	v_add_f32_e32 v32, 1.0, v32
	v_rcp_f32_e32 v32, v32
	v_add_f32_e32 v33, 1.0, v33
	v_rcp_f32_e32 v33, v33
	s_nop 0
	v_pk_mul_f32 v[28:29], v[28:29], v[32:33]
	s_nop 0
	v_pk_mul_f32 v[24:25], v[28:29], v[24:25]
	v_mul_f32_e32 v28, 0xbfb8aa3b, v21
	v_exp_f32_e32 v28, v28
	s_nop 0
	v_add_f32_e32 v28, 1.0, v28
	v_rcp_f32_e32 v35, v28
	s_nop 0
	v_pk_mul_f32 v[20:21], v[20:21], v[34:35]
	s_nop 0
	v_pk_mul_f32 v[20:21], v[20:21], v[16:17]
	v_mul_f32_e32 v17, 0xbfb8aa3b, v22
	v_exp_f32_e32 v17, v17
	v_mul_f32_e32 v16, 0xbfb8aa3b, v30
	v_exp_f32_e32 v16, v16
	v_add_f32_e32 v17, 1.0, v17
	v_rcp_f32_e32 v28, v17
	v_mul_f32_e32 v17, 0xbfb8aa3b, v31
	v_exp_f32_e32 v17, v17
	v_add_f32_e32 v16, 1.0, v16
	v_rcp_f32_e32 v16, v16
	v_add_f32_e32 v17, 1.0, v17
	v_rcp_f32_e32 v17, v17
	s_nop 0
	v_pk_mul_f32 v[16:17], v[30:31], v[16:17]
	s_nop 0
	v_pk_mul_f32 v[26:27], v[16:17], v[26:27]
	v_mul_f32_e32 v16, 0xbfb8aa3b, v23
	v_exp_f32_e32 v16, v16
	s_nop 0
	v_add_f32_e32 v16, 1.0, v16
	v_rcp_f32_e32 v29, v16
	s_nop 0
	v_pk_mul_f32 v[16:17], v[22:23], v[28:29]
	s_nop 0
	v_pk_mul_f32 v[22:23], v[16:17], v[18:19]
	v_cvt_pk_bf16_f32 v18, v20, v21
	v_add_u32_e32 v20, 0xa0, v142
	v_mad_i64_i32 v[20:21], s[4:5], v20, s18, v[112:113]
	v_cvt_pk_bf16_f32 v16, v24, v25
	v_cvt_pk_bf16_f32 v17, v26, v27
	v_cvt_pk_bf16_f32 v19, v22, v23
	v_lshl_add_u64 v[20:21], v[20:21], 0, v[114:115]
	global_store_dwordx4 v[20:21], v[16:19], off
	s_nop 1
	v_mul_f32_e32 v17, 0xbfb8aa3b, v4
	v_exp_f32_e32 v17, v17
	v_mul_f32_e32 v16, 0xbfb8aa3b, v12
	v_exp_f32_e32 v16, v16
	v_add_f32_e32 v17, 1.0, v17
	v_rcp_f32_e32 v18, v17
	v_mul_f32_e32 v17, 0xbfb8aa3b, v13
	v_exp_f32_e32 v17, v17
	v_add_f32_e32 v16, 1.0, v16
	v_rcp_f32_e32 v16, v16
	v_add_f32_e32 v17, 1.0, v17
	v_rcp_f32_e32 v17, v17
	s_nop 0
	v_pk_mul_f32 v[12:13], v[12:13], v[16:17]
	s_nop 0
	v_pk_mul_f32 v[8:9], v[12:13], v[8:9]
	v_mul_f32_e32 v12, 0xbfb8aa3b, v5
	v_exp_f32_e32 v12, v12
	s_nop 0
	v_add_f32_e32 v12, 1.0, v12
	v_rcp_f32_e32 v19, v12
	s_nop 0
	v_pk_mul_f32 v[4:5], v[4:5], v[18:19]
	s_nop 0
	v_pk_mul_f32 v[4:5], v[4:5], v[0:1]
	v_mul_f32_e32 v1, 0xbfb8aa3b, v6
	v_exp_f32_e32 v1, v1
	v_mul_f32_e32 v0, 0xbfb8aa3b, v14
	v_exp_f32_e32 v0, v0
	v_add_f32_e32 v1, 1.0, v1
	v_rcp_f32_e32 v12, v1
	v_mul_f32_e32 v1, 0xbfb8aa3b, v15
	v_exp_f32_e32 v1, v1
	v_add_f32_e32 v0, 1.0, v0
	v_rcp_f32_e32 v0, v0
	v_add_f32_e32 v1, 1.0, v1
	v_rcp_f32_e32 v1, v1
	s_nop 0
	v_pk_mul_f32 v[0:1], v[14:15], v[0:1]
	s_nop 0
	v_pk_mul_f32 v[10:11], v[0:1], v[10:11]
	v_mul_f32_e32 v0, 0xbfb8aa3b, v7
	v_exp_f32_e32 v0, v0
	s_nop 0
	v_add_f32_e32 v0, 1.0, v0
	v_rcp_f32_e32 v13, v0
	s_nop 0
	v_pk_mul_f32 v[0:1], v[6:7], v[12:13]
	s_nop 0
	v_pk_mul_f32 v[6:7], v[0:1], v[2:3]
	v_cvt_pk_bf16_f32 v2, v4, v5
	v_add_u32_e32 v4, 0xb0, v142
	v_mad_i64_i32 v[4:5], s[4:5], v4, s18, v[112:113]
	v_cvt_pk_bf16_f32 v0, v8, v9
	v_cvt_pk_bf16_f32 v1, v10, v11
	v_cvt_pk_bf16_f32 v3, v6, v7
	v_lshl_add_u64 v[4:5], v[4:5], 0, v[114:115]
	global_store_dwordx4 v[4:5], v[0:3], off
	s_cbranch_vccz .LBB0_1854
	s_waitcnt vmcnt(0)
	s_cmpk_gt_u32 s3, 0xff
	s_cbranch_scc1 .LBB0_1862
	s_barrier

; #define PG8_STAGE(bufoff, gbase, voff) do { _Pragma("unroll") for (int _i = 0; _i < 2; ++_i) \
;     __builtin_amdgcn_global_load_lds((const unsigned*)((const char*)(gbase) + (voff)[_i]), (LAS unsigned*)(lds + (bufoff) + ldsw + _i * 8192), 16, 0, 0); } while (0)
; #define PG8_LDA(dst, b, h) do { _Pragma("unroll") for (int m = 0; m < 4; ++m) _Pragma("unroll") for (int k = 0; k < 2; ++k) dst[m][k] = *(const LAS bf16x8*)(lds + PG8_SA(b, h) + aoff + m * 2048 + k * 1024); } while (0)
; #define PG8_LDB(dst, b, h) do { _Pragma("unroll") for (int n = 0; n < 2; ++n) _Pragma("unroll") for (int k = 0; k < 2; ++k) dst[n][k] = *(const LAS bf16x8*)(lds + PG8_SB(b, h) + boff + n * 2048 + k * 1024); } while (0)
; #define PG8_MMA(ai, bj, At, Bt_) do { __builtin_amdgcn_s_setprio(1); _Pragma("unroll") for (int m = 0; m < 4; ++m) _Pragma("unroll") for (int n = 0; n < 2; ++n) _Pragma("unroll") for (int k = 0; k < 2; ++k) \
;     acc[ai][bj][m][n] = __builtin_amdgcn_mfma_f32_16x16x32_bf16(Bt_[n][k], At[m][k], acc[ai][bj][m][n], 0, 0, 0); __builtin_amdgcn_s_setprio(0); } while (0)
; #define PG8_WAIT_L(n) asm volatile("s_waitcnt lgkmcnt(" #n ")" ::: "memory")
; #define PG8_BAR __builtin_amdgcn_s_barrier()
; #define PG8_SCHED __builtin_amdgcn_sched_barrier(0)
; #define PG8_WAIT_L(n) asm volatile("s_waitcnt lgkmcnt(" #n ")" ::: "memory")
; #define PG8_BAR __builtin_amdgcn_s_barrier()
; #define PG8_SCHED __builtin_amdgcn_sched_barrier(0)
; template <class Epi>
; DI void gemm_phase(char* smem, const bf16_t* A, int lda, const bf16_t* Bt, int ldb, int K, const Order& S_, const Epi& E) {
;     ...
;     for (int t = 0; t < nt; t += 2) {
;       const bool last = (t == nt - 2);
;       const char* a1 = cA + (size_t)(t + 1) * kstep;
;       const char* a2 = last ? nA : cA + (size_t)(t + 2) * kstep; const char* b2 = last ? nB : cB + (size_t)(t + 2) * kstep;
;       const char* a3 = a2 + kstep; const char* b3 = b2 + kstep;
;       PG8_LDB(B0, 0, 0); PG8_SCHED; PG8_LDA(At, 0, 0); PG8_STAGE(PG8_SA(1, 1), a1 + hstepA, voffA);
;       PG8_WAIT_L(8); PG8_BAR; PG8_WAIT_L(0); PG8_MMA(0, 0, At, B0); PG8_BAR; PG8_SCHED;
;       PG8_LDB(B1, 0, 1); PG8_STAGE(PG8_SB(0, 0), b2, voffB);
;       PG8_BAR; PG8_WAIT_L(0); PG8_MMA(0, 1, At, B1); PG8_BAR;
;       PG8_LDA(At, 0, 1); PG8_STAGE(PG8_SA(0, 0), a2, voffA);
;       PG8_BAR; PG8_WAIT_L(0); PG8_MMA(1, 0, At, B0); PG8_BAR; PG8_SCHED;
.LBB0_1929:
	s_add_u32 s44, s42, 0x100
	s_addc_u32 s45, s43, 0
	s_add_i32 s57, 0, 0x10000
	v_add_u32_e32 v140, s57, v153
	ds_read_b128 v[128:131], v140
	ds_read_b128 v[132:135], v140 offset:1024
	ds_read_b128 v[136:139], v140 offset:2048
	ds_read_b128 v[140:143], v140 offset:3072
	s_cmp_eq_u32 s56, 40
	s_cselect_b32 s51, s1, s45
	s_cselect_b32 s50, s0, s44
	s_cselect_b32 s47, s41, s53
	s_cselect_b32 s46, s40, s52
	v_lshl_add_u64 v[150:151], s[42:43], 0, v[146:147]
	s_add_i32 m0, s27, 0xc000
	ds_read_b128 v[156:159], v155
	ds_read_b128 v[160:163], v155 offset:1024
	ds_read_b128 v[164:167], v155 offset:2048
	ds_read_b128 v[168:171], v155 offset:3072
	ds_read_b128 v[172:175], v155 offset:4096
	ds_read_b128 v[176:179], v155 offset:5120
	ds_read_b128 v[180:183], v155 offset:6144
	ds_read_b128 v[184:187], v155 offset:7168
	global_load_lds_dwordx4 v[150:151], off
	v_lshl_add_u64 v[150:151], s[42:43], 0, v[148:149]
	s_add_i32 m0, s27, 0xe000
	s_nop 0
	global_load_lds_dwordx4 v[150:151], off
	s_waitcnt lgkmcnt(8)
	s_barrier
	s_waitcnt lgkmcnt(0)
	s_waitcnt lgkmcnt(0)
	v_mfma_f32_16x16x32_bf16 v[124:127], v[128:131], v[156:159], v[124:127]
	v_mfma_f32_16x16x32_bf16 v[120:123], v[136:139], v[156:159], v[120:123]
	v_mfma_f32_16x16x32_bf16 v[116:119], v[128:131], v[164:167], v[116:119]
	v_mfma_f32_16x16x32_bf16 v[108:111], v[136:139], v[164:167], v[108:111]
	v_mfma_f32_16x16x32_bf16 v[92:95], v[128:131], v[172:175], v[92:95]
	v_mfma_f32_16x16x32_bf16 v[88:91], v[136:139], v[172:175], v[88:91]
	v_mfma_f32_16x16x32_bf16 v[84:87], v[128:131], v[180:183], v[84:87]
	v_mfma_f32_16x16x32_bf16 v[80:83], v[136:139], v[180:183], v[80:83]
	v_mfma_f32_16x16x32_bf16 v[124:127], v[132:135], v[160:163], v[124:127]
	v_mfma_f32_16x16x32_bf16 v[120:123], v[140:143], v[160:163], v[120:123]
	v_mfma_f32_16x16x32_bf16 v[116:119], v[132:135], v[168:171], v[116:119]
	v_mfma_f32_16x16x32_bf16 v[108:111], v[140:143], v[168:171], v[108:111]
	v_mfma_f32_16x16x32_bf16 v[92:95], v[132:135], v[176:179], v[92:95]
	v_mfma_f32_16x16x32_bf16 v[88:91], v[140:143], v[176:179], v[88:91]
	v_mfma_f32_16x16x32_bf16 v[84:87], v[132:135], v[184:187], v[84:87]
	v_mfma_f32_16x16x32_bf16 v[80:83], v[140:143], v[184:187], v[80:83]
	s_barrier
	s_add_i32 s60, 0, 0x14000
	v_add_u32_e32 v150, s60, v153
	s_add_i32 s42, s57, s15
	ds_read_b128 v[188:191], v150
	ds_read_b128 v[210:213], v150 offset:1024
	ds_read_b128 v[214:217], v150 offset:2048
	ds_read_b128 v[234:237], v150 offset:3072
	v_lshl_add_u64 v[150:151], s[46:47], 0, v[220:221]
	s_mov_b32 m0, s42
	v_lshl_add_u64 v[194:195], s[46:47], 0, v[144:145]
	global_load_lds_dwordx4 v[150:151], off
	s_add_i32 m0, s42, 0x2000
	s_nop 0
	global_load_lds_dwordx4 v[194:195], off
	s_barrier
	s_waitcnt lgkmcnt(0)
	s_waitcnt lgkmcnt(0)
	v_mfma_f32_16x16x32_bf16 v[112:115], v[188:191], v[156:159], v[112:115]
	v_mfma_f32_16x16x32_bf16 v[104:107], v[214:217], v[156:159], v[104:107]
	v_mfma_f32_16x16x32_bf16 v[100:103], v[188:191], v[164:167], v[100:103]
	v_mfma_f32_16x16x32_bf16 v[96:99], v[214:217], v[164:167], v[96:99]
	v_mfma_f32_16x16x32_bf16 v[76:79], v[188:191], v[172:175], v[76:79]
	v_mfma_f32_16x16x32_bf16 v[72:75], v[214:217], v[172:175], v[72:75]
	v_mfma_f32_16x16x32_bf16 v[68:71], v[188:191], v[180:183], v[68:71]
	v_mfma_f32_16x16x32_bf16 v[64:67], v[214:217], v[180:183], v[64:67]
	v_mfma_f32_16x16x32_bf16 v[112:115], v[210:213], v[160:163], v[112:115]
	v_mfma_f32_16x16x32_bf16 v[104:107], v[234:237], v[160:163], v[104:107]
	v_mfma_f32_16x16x32_bf16 v[100:103], v[210:213], v[168:171], v[100:103]
	v_mfma_f32_16x16x32_bf16 v[96:99], v[234:237], v[168:171], v[96:99]
	v_mfma_f32_16x16x32_bf16 v[76:79], v[210:213], v[176:179], v[76:79]
	v_mfma_f32_16x16x32_bf16 v[72:75], v[234:237], v[176:179], v[72:75]
	v_mfma_f32_16x16x32_bf16 v[68:71], v[210:213], v[184:187], v[68:71]
	v_mfma_f32_16x16x32_bf16 v[64:67], v[234:237], v[184:187], v[64:67]
	s_mov_b32 m0, s27
	v_lshl_add_u64 v[200:201], s[50:51], 0, v[220:221]
	s_barrier
	ds_read_b128 v[156:159], v155 offset:16384
	ds_read_b128 v[160:163], v155 offset:17408
	ds_read_b128 v[164:167], v155 offset:18432
	ds_read_b128 v[168:171], v155 offset:19456
	ds_read_b128 v[172:175], v155 offset:20480
	ds_read_b128 v[176:179], v155 offset:21504
	ds_read_b128 v[180:183], v155 offset:22528
	ds_read_b128 v[184:187], v155 offset:23552
	global_load_lds_dwordx4 v[200:201], off
	v_lshl_add_u64 v[202:203], s[50:51], 0, v[144:145]
	s_mov_b32 m0, s29
	s_nop 0
	global_load_lds_dwordx4 v[202:203], off
	s_barrier
	s_waitcnt lgkmcnt(0)
	s_waitcnt lgkmcnt(0)
	v_mfma_f32_16x16x32_bf16 v[60:63], v[128:131], v[156:159], v[60:63]
	v_mfma_f32_16x16x32_bf16 v[56:59], v[136:139], v[156:159], v[56:59]
	v_mfma_f32_16x16x32_bf16 v[52:55], v[128:131], v[164:167], v[52:55]
	v_mfma_f32_16x16x32_bf16 v[48:51], v[136:139], v[164:167], v[48:51]
	v_mfma_f32_16x16x32_bf16 v[28:31], v[128:131], v[172:175], v[28:31]
	v_mfma_f32_16x16x32_bf16 v[24:27], v[136:139], v[172:175], v[24:27]
	v_mfma_f32_16x16x32_bf16 v[20:23], v[128:131], v[180:183], v[20:23]
	v_mfma_f32_16x16x32_bf16 v[16:19], v[136:139], v[180:183], v[16:19]
	v_mfma_f32_16x16x32_bf16 v[60:63], v[132:135], v[160:163], v[60:63]
	v_mfma_f32_16x16x32_bf16 v[56:59], v[140:143], v[160:163], v[56:59]
	v_mfma_f32_16x16x32_bf16 v[52:55], v[132:135], v[168:171], v[52:55]
	v_mfma_f32_16x16x32_bf16 v[48:51], v[140:143], v[168:171], v[48:51]
	v_mfma_f32_16x16x32_bf16 v[28:31], v[132:135], v[176:179], v[28:31]
	v_mfma_f32_16x16x32_bf16 v[24:27], v[140:143], v[176:179], v[24:27]
	v_mfma_f32_16x16x32_bf16 v[20:23], v[132:135], v[184:187], v[20:23]
	v_mfma_f32_16x16x32_bf16 v[16:19], v[140:143], v[184:187], v[16:19]
	s_barrier
; #define PG8_STAGE(bufoff, gbase, voff) do { _Pragma("unroll") for (int _i = 0; _i < 2; ++_i) \
;     __builtin_amdgcn_global_load_lds((const unsigned*)((const char*)(gbase) + (voff)[_i]), (LAS unsigned*)(lds + (bufoff) + ldsw + _i * 8192), 16, 0, 0); } while (0)
; #define PG8_LDA(dst, b, h) do { _Pragma("unroll") for (int m = 0; m < 4; ++m) _Pragma("unroll") for (int k = 0; k < 2; ++k) dst[m][k] = *(const LAS bf16x8*)(lds + PG8_SA(b, h) + aoff + m * 2048 + k * 1024); } while (0)
; #define PG8_LDB(dst, b, h) do { _Pragma("unroll") for (int n = 0; n < 2; ++n) _Pragma("unroll") for (int k = 0; k < 2; ++k) dst[n][k] = *(const LAS bf16x8*)(lds + PG8_SB(b, h) + boff + n * 2048 + k * 1024); } while (0)
; #define PG8_MMA(ai, bj, At, Bt_) do { __builtin_amdgcn_s_setprio(1); _Pragma("unroll") for (int m = 0; m < 4; ++m) _Pragma("unroll") for (int n = 0; n < 2; ++n) _Pragma("unroll") for (int k = 0; k < 2; ++k) \
;     acc[ai][bj][m][n] = __builtin_amdgcn_mfma_f32_16x16x32_bf16(Bt_[n][k], At[m][k], acc[ai][bj][m][n], 0, 0, 0); __builtin_amdgcn_s_setprio(0); } while (0)
; #define PG8_WAIT_V(n) asm volatile("s_waitcnt vmcnt(" #n ")" ::: "memory")
; #define PG8_WAIT_L(n) asm volatile("s_waitcnt lgkmcnt(" #n ")" ::: "memory")
; #define PG8_BAR __builtin_amdgcn_s_barrier()
; #define PG8_SCHED __builtin_amdgcn_sched_barrier(0)
; #define PG8_LDA(dst, b, h) do { _Pragma("unroll") for (int m = 0; m < 4; ++m) _Pragma("unroll") for (int k = 0; k < 2; ++k) dst[m][k] = *(const LAS bf16x8*)(lds + PG8_SA(b, h) + aoff + m * 2048 + k * 1024); } while (0)
; #define PG8_WAIT_V(n) asm volatile("s_waitcnt vmcnt(" #n ")" ::: "memory")
; template <class Epi>
; DI void gemm_phase(char* smem, const bf16_t* A, int lda, const bf16_t* Bt, int ldb, int K, const Order& S_, const Epi& E) {
;     ...
;       PG8_STAGE(PG8_SB(0, 1), b2 + hstepB, voffB);
;       PG8_WAIT_V(6); PG8_BAR; PG8_MMA(1, 1, At, B1); PG8_BAR;
;       PG8_LDB(B0, 1, 0); PG8_SCHED; PG8_LDA(At, 1, 0); PG8_STAGE(PG8_SA(0, 1), a2 + hstepA, voffA);
;       PG8_WAIT_L(8); PG8_BAR; PG8_WAIT_L(0); PG8_MMA(0, 0, At, B0); PG8_BAR; PG8_SCHED;
;       PG8_LDB(B1, 1, 1); PG8_STAGE(PG8_SB(1, 0), b3, voffB);
;       PG8_BAR; PG8_WAIT_L(0); PG8_MMA(0, 1, At, B1); PG8_BAR;
;       PG8_LDA(At, 1, 1); PG8_STAGE(PG8_SA(1, 0), a3, voffA);
;       PG8_BAR; PG8_WAIT_L(0); PG8_MMA(1, 0, At, B0); PG8_BAR; PG8_SCHED;
	s_add_u32 s42, s46, 0xb0000
	s_addc_u32 s43, s47, 0
	s_add_i32 s57, s60, s15
	v_lshl_add_u64 v[128:129], s[42:43], 0, v[220:221]
	s_mov_b32 m0, s57
	s_nop 0
	global_load_lds_dwordx4 v[128:129], off
	v_lshl_add_u64 v[128:129], s[42:43], 0, v[144:145]
	s_add_i32 m0, s57, 0x2000
	s_nop 0
	global_load_lds_dwordx4 v[128:129], off
	s_waitcnt vmcnt(6)
	s_barrier
	v_mfma_f32_16x16x32_bf16 v[44:47], v[188:191], v[156:159], v[44:47]
	v_mfma_f32_16x16x32_bf16 v[40:43], v[214:217], v[156:159], v[40:43]
	v_mfma_f32_16x16x32_bf16 v[36:39], v[188:191], v[164:167], v[36:39]
	v_mfma_f32_16x16x32_bf16 v[32:35], v[214:217], v[164:167], v[32:35]
	v_mfma_f32_16x16x32_bf16 v[12:15], v[188:191], v[172:175], v[12:15]
	v_mfma_f32_16x16x32_bf16 v[8:11], v[214:217], v[172:175], v[8:11]
	v_mfma_f32_16x16x32_bf16 v[4:7], v[188:191], v[180:183], v[4:7]
	v_mfma_f32_16x16x32_bf16 v[0:3], v[214:217], v[180:183], v[0:3]
	v_mfma_f32_16x16x32_bf16 v[44:47], v[210:213], v[160:163], v[44:47]
	v_mfma_f32_16x16x32_bf16 v[40:43], v[234:237], v[160:163], v[40:43]
	v_mfma_f32_16x16x32_bf16 v[36:39], v[210:213], v[168:171], v[36:39]
	v_mfma_f32_16x16x32_bf16 v[32:35], v[234:237], v[168:171], v[32:35]
	v_mfma_f32_16x16x32_bf16 v[12:15], v[210:213], v[176:179], v[12:15]
	v_mfma_f32_16x16x32_bf16 v[8:11], v[234:237], v[176:179], v[8:11]
	v_mfma_f32_16x16x32_bf16 v[4:7], v[210:213], v[184:187], v[4:7]
	v_mfma_f32_16x16x32_bf16 v[0:3], v[234:237], v[184:187], v[0:3]
	s_add_i32 s57, 0, 0x18000
	v_add_u32_e32 v140, s57, v153
	s_barrier
	ds_read_b128 v[128:131], v140
	ds_read_b128 v[132:135], v140 offset:1024
	ds_read_b128 v[136:139], v140 offset:2048
	ds_read_b128 v[140:143], v140 offset:3072
	s_add_u32 s42, s50, 0xb0000
	s_addc_u32 s43, s51, 0
	s_mov_b32 m0, s33
	v_lshl_add_u64 v[188:189], s[42:43], 0, v[220:221]
	ds_read_b128 v[156:159], v155 offset:32768
	ds_read_b128 v[160:163], v155 offset:33792
	ds_read_b128 v[164:167], v155 offset:34816
	ds_read_b128 v[168:171], v155 offset:35840
	ds_read_b128 v[172:175], v155 offset:36864
	ds_read_b128 v[176:179], v155 offset:37888
	ds_read_b128 v[180:183], v155 offset:38912
	ds_read_b128 v[184:187], v155 offset:39936
	global_load_lds_dwordx4 v[188:189], off
	v_lshl_add_u64 v[188:189], s[42:43], 0, v[144:145]
	s_mov_b32 m0, s34
	s_nop 0
	global_load_lds_dwordx4 v[188:189], off
	s_waitcnt lgkmcnt(8)
	s_barrier
	s_waitcnt lgkmcnt(0)
	s_waitcnt lgkmcnt(0)
	v_mfma_f32_16x16x32_bf16 v[124:127], v[128:131], v[156:159], v[124:127]
	v_mfma_f32_16x16x32_bf16 v[120:123], v[136:139], v[156:159], v[120:123]
	v_mfma_f32_16x16x32_bf16 v[116:119], v[128:131], v[164:167], v[116:119]
	v_mfma_f32_16x16x32_bf16 v[108:111], v[136:139], v[164:167], v[108:111]
	v_mfma_f32_16x16x32_bf16 v[92:95], v[128:131], v[172:175], v[92:95]
	v_mfma_f32_16x16x32_bf16 v[88:91], v[136:139], v[172:175], v[88:91]
	v_mfma_f32_16x16x32_bf16 v[84:87], v[128:131], v[180:183], v[84:87]
	v_mfma_f32_16x16x32_bf16 v[80:83], v[136:139], v[180:183], v[80:83]
	v_mfma_f32_16x16x32_bf16 v[124:127], v[132:135], v[160:163], v[124:127]
	v_mfma_f32_16x16x32_bf16 v[120:123], v[140:143], v[160:163], v[120:123]
	v_mfma_f32_16x16x32_bf16 v[116:119], v[132:135], v[168:171], v[116:119]
	v_mfma_f32_16x16x32_bf16 v[108:111], v[140:143], v[168:171], v[108:111]
	v_mfma_f32_16x16x32_bf16 v[92:95], v[132:135], v[176:179], v[92:95]
	v_mfma_f32_16x16x32_bf16 v[88:91], v[140:143], v[176:179], v[88:91]
	v_mfma_f32_16x16x32_bf16 v[84:87], v[132:135], v[184:187], v[84:87]
	v_mfma_f32_16x16x32_bf16 v[80:83], v[140:143], v[184:187], v[80:83]
	s_barrier
	s_add_i32 s50, 0, 0x1c000
	s_add_i32 s42, s57, s15
	v_add_u32_e32 v204, s50, v153
	v_lshl_add_u64 v[150:151], v[150:151], 0, s[58:59]
	s_mov_b32 m0, s42
	ds_read_b128 v[188:191], v204
	ds_read_b128 v[210:213], v204 offset:1024
	ds_read_b128 v[214:217], v204 offset:2048
	ds_read_b128 v[234:237], v204 offset:3072
	global_load_lds_dwordx4 v[150:151], off
	v_lshl_add_u64 v[150:151], v[194:195], 0, s[58:59]
	s_add_i32 m0, s42, 0x2000
	s_nop 0
	global_load_lds_dwordx4 v[150:151], off
	s_barrier
	s_waitcnt lgkmcnt(0)
	s_waitcnt lgkmcnt(0)
	v_mfma_f32_16x16x32_bf16 v[112:115], v[188:191], v[156:159], v[112:115]
	v_mfma_f32_16x16x32_bf16 v[104:107], v[214:217], v[156:159], v[104:107]
	v_mfma_f32_16x16x32_bf16 v[100:103], v[188:191], v[164:167], v[100:103]
	v_mfma_f32_16x16x32_bf16 v[96:99], v[214:217], v[164:167], v[96:99]
	v_mfma_f32_16x16x32_bf16 v[76:79], v[188:191], v[172:175], v[76:79]
	v_mfma_f32_16x16x32_bf16 v[72:75], v[214:217], v[172:175], v[72:75]
	v_mfma_f32_16x16x32_bf16 v[68:71], v[188:191], v[180:183], v[68:71]
	v_mfma_f32_16x16x32_bf16 v[64:67], v[214:217], v[180:183], v[64:67]
	v_mfma_f32_16x16x32_bf16 v[112:115], v[210:213], v[160:163], v[112:115]
	v_mfma_f32_16x16x32_bf16 v[104:107], v[234:237], v[160:163], v[104:107]
	v_mfma_f32_16x16x32_bf16 v[100:103], v[210:213], v[168:171], v[100:103]
	v_mfma_f32_16x16x32_bf16 v[96:99], v[234:237], v[168:171], v[96:99]
	v_mfma_f32_16x16x32_bf16 v[76:79], v[210:213], v[176:179], v[76:79]
	v_mfma_f32_16x16x32_bf16 v[72:75], v[234:237], v[176:179], v[72:75]
	v_mfma_f32_16x16x32_bf16 v[68:71], v[210:213], v[184:187], v[68:71]
	v_mfma_f32_16x16x32_bf16 v[64:67], v[234:237], v[184:187], v[64:67]
	s_mov_b32 m0, s38
	v_lshl_add_u64 v[150:151], v[200:201], 0, s[58:59]
	s_barrier
	ds_read_b128 v[156:159], v155 offset:49152
	ds_read_b128 v[160:163], v155 offset:50176
	ds_read_b128 v[164:167], v155 offset:51200
	ds_read_b128 v[168:171], v155 offset:52224
	ds_read_b128 v[172:175], v155 offset:53248
	ds_read_b128 v[176:179], v155 offset:54272
	ds_read_b128 v[180:183], v155 offset:55296
	ds_read_b128 v[184:187], v155 offset:56320
	global_load_lds_dwordx4 v[150:151], off
	v_lshl_add_u64 v[150:151], v[202:203], 0, s[58:59]
	s_mov_b32 m0, s20
	s_nop 0
	global_load_lds_dwordx4 v[150:151], off
	s_barrier
; #define MEMBAR() asm volatile("" ::: "memory")
; DI float* modp(const Params& p, int layer, int g, int chunk) { return (float*)(p.ws + OFF_MOD) + ((size_t)(layer * 9 + g) * 6 + chunk) * 1024; }
; #define PG8_STAGE(bufoff, gbase, voff) do { _Pragma("unroll") for (int _i = 0; _i < 2; ++_i) \
;     __builtin_amdgcn_global_load_lds((const unsigned*)((const char*)(gbase) + (voff)[_i]), (LAS unsigned*)(lds + (bufoff) + ldsw + _i * 8192), 16, 0, 0); } while (0)
; #define PG8_MMA(ai, bj, At, Bt_) do { __builtin_amdgcn_s_setprio(1); _Pragma("unroll") for (int m = 0; m < 4; ++m) _Pragma("unroll") for (int n = 0; n < 2; ++n) _Pragma("unroll") for (int k = 0; k < 2; ++k) \
;     acc[ai][bj][m][n] = __builtin_amdgcn_mfma_f32_16x16x32_bf16(Bt_[n][k], At[m][k], acc[ai][bj][m][n], 0, 0, 0); __builtin_amdgcn_s_setprio(0); } while (0)
; #define PG8_WAIT_V(n) asm volatile("s_waitcnt vmcnt(" #n ")" ::: "memory")
; #define PG8_WAIT_L(n) asm volatile("s_waitcnt lgkmcnt(" #n ")" ::: "memory")
; #define PG8_BAR __builtin_amdgcn_s_barrier()
; template <class Epi>
; DI void gemm_phase(char* smem, const bf16_t* A, int lda, const bf16_t* Bt, int ldb, int K, const Order& S_, const Epi& E) {
;     ...
;       PG8_BAR; PG8_WAIT_L(0); PG8_MMA(1, 0, At, B0); PG8_BAR; PG8_SCHED;
;       PG8_STAGE(PG8_SB(1, 1), b3 + hstepB, voffB);
;       PG8_WAIT_V(6); PG8_BAR; PG8_MMA(1, 1, At, B1); PG8_BAR;
;   DI void operator()(const acc_t& acc, const Unit& u, int wr, int wc, int fr, int fq) const {
;     const int row0 = u.pm * BM + wr * 64 + fr, col0 = u.pn * BM + wc * 32 + 4 * fq;
;     const int b = u.pm / 17, g = (u.pm - b * 17) == 0 ? 8 : b;
;     const float* gate = modp(p, layer, g, chunk);
;     f32x4 gv[2][2];
; #pragma unroll
;     for (int bj = 0; bj < 2; ++bj)
; #pragma unroll
;       for (int n = 0; n < 2; ++n) gv[bj][n] = *(const f32x4*)(gate + col0 + bj * HALF + n * 16);
; #pragma unroll
;     for (int q = 0; q < 4; ++q) {
;       const int ai = q >> 1, mh = q & 1;
;       MEMBAR();
;       f32x4 xv[2][2][2];
; #pragma unroll
;       for (int mm = 0; mm < 2; ++mm) { const int t = row0 + ai * HALF + (2 * mh + mm) * 16;
;         const float* xi = from_input ? xrow_in(p, t) : xrow_ws(p, t);
; #pragma unroll
;         for (int bj = 0; bj < 2; ++bj)
; #pragma unroll
;           for (int n = 0; n < 2; ++n) xv[mm][bj][n] = *(const f32x4*)(xi + col0 + bj * HALF + n * 16); }
	s_waitcnt lgkmcnt(0)
	s_waitcnt lgkmcnt(0)
	v_mfma_f32_16x16x32_bf16 v[60:63], v[128:131], v[156:159], v[60:63]
	v_mfma_f32_16x16x32_bf16 v[56:59], v[136:139], v[156:159], v[56:59]
	v_mfma_f32_16x16x32_bf16 v[52:55], v[128:131], v[164:167], v[52:55]
	v_mfma_f32_16x16x32_bf16 v[48:51], v[136:139], v[164:167], v[48:51]
	v_mfma_f32_16x16x32_bf16 v[28:31], v[128:131], v[172:175], v[28:31]
	v_mfma_f32_16x16x32_bf16 v[24:27], v[136:139], v[172:175], v[24:27]
	v_mfma_f32_16x16x32_bf16 v[20:23], v[128:131], v[180:183], v[20:23]
	v_mfma_f32_16x16x32_bf16 v[16:19], v[136:139], v[180:183], v[16:19]
	v_mfma_f32_16x16x32_bf16 v[60:63], v[132:135], v[160:163], v[60:63]
	v_mfma_f32_16x16x32_bf16 v[56:59], v[140:143], v[160:163], v[56:59]
	v_mfma_f32_16x16x32_bf16 v[52:55], v[132:135], v[168:171], v[52:55]
	v_mfma_f32_16x16x32_bf16 v[48:51], v[140:143], v[168:171], v[48:51]
	v_mfma_f32_16x16x32_bf16 v[28:31], v[132:135], v[176:179], v[28:31]
	v_mfma_f32_16x16x32_bf16 v[24:27], v[140:143], v[176:179], v[24:27]
	v_mfma_f32_16x16x32_bf16 v[20:23], v[132:135], v[184:187], v[20:23]
	v_mfma_f32_16x16x32_bf16 v[16:19], v[140:143], v[184:187], v[16:19]
	s_barrier
	s_add_u32 s42, s46, 0xb0080
	s_addc_u32 s43, s47, 0
	s_add_i32 s46, s50, s15
	v_lshl_add_u64 v[128:129], s[42:43], 0, v[220:221]
	s_mov_b32 m0, s46
	s_nop 0
	global_load_lds_dwordx4 v[128:129], off
	v_lshl_add_u64 v[128:129], s[42:43], 0, v[144:145]
	s_add_i32 m0, s46, 0x2000
	s_nop 0
	global_load_lds_dwordx4 v[128:129], off
	s_waitcnt vmcnt(6)
	s_barrier
	v_mfma_f32_16x16x32_bf16 v[44:47], v[188:191], v[156:159], v[44:47]
	v_mfma_f32_16x16x32_bf16 v[40:43], v[214:217], v[156:159], v[40:43]
	v_mfma_f32_16x16x32_bf16 v[36:39], v[188:191], v[164:167], v[36:39]
	v_mfma_f32_16x16x32_bf16 v[32:35], v[214:217], v[164:167], v[32:35]
	v_mfma_f32_16x16x32_bf16 v[12:15], v[188:191], v[172:175], v[12:15]
	v_mfma_f32_16x16x32_bf16 v[8:11], v[214:217], v[172:175], v[8:11]
	v_mfma_f32_16x16x32_bf16 v[4:7], v[188:191], v[180:183], v[4:7]
	v_mfma_f32_16x16x32_bf16 v[0:3], v[214:217], v[180:183], v[0:3]
	v_mfma_f32_16x16x32_bf16 v[44:47], v[210:213], v[160:163], v[44:47]
	v_mfma_f32_16x16x32_bf16 v[40:43], v[234:237], v[160:163], v[40:43]
	v_mfma_f32_16x16x32_bf16 v[36:39], v[210:213], v[168:171], v[36:39]
	v_mfma_f32_16x16x32_bf16 v[32:35], v[234:237], v[168:171], v[32:35]
	v_mfma_f32_16x16x32_bf16 v[12:15], v[210:213], v[176:179], v[12:15]
	v_mfma_f32_16x16x32_bf16 v[8:11], v[234:237], v[176:179], v[8:11]
	v_mfma_f32_16x16x32_bf16 v[4:7], v[210:213], v[184:187], v[4:7]
	v_mfma_f32_16x16x32_bf16 v[0:3], v[234:237], v[184:187], v[0:3]
	s_add_i32 s56, s56, 2
	s_add_u32 s52, s52, 0x100
	s_addc_u32 s53, s53, 0
	s_cmp_gt_u32 s56, 41
	s_mov_b64 s[42:43], s[44:45]
	s_barrier
	s_cbranch_scc0 .LBB0_1929
	v_lshl_add_u32 v157, s39, 8, v152
	s_mov_b32 s51, 0x78787879
	v_mul_hi_i32 v156, v157, s51
	v_lshrrev_b32_e32 v158, 31, v156
	v_ashrrev_i32_e32 v156, 11, v156
	v_add_u32_e32 v162, v156, v158
	s_mul_hi_i32 s42, s39, 0x78787879
	v_mad_i32_i24 v161, v162, s80, v157
	s_movk_i32 s50, 0x100
	s_lshr_b32 s43, s42, 31
	s_ashr_i32 s42, s42, 3
	v_ashrrev_i32_e32 v166, 31, v161
	v_add_u32_e32 v168, 0xffffff00, v161
	v_cmp_gt_i32_e32 vcc, s50, v161
	s_add_i32 s42, s42, s43
	v_ashrrev_i32_e32 v163, 31, v162
	v_cndmask_b32_e32 v167, 0, v166, vcc
	v_cndmask_b32_e32 v166, v168, v161, vcc
	v_cndmask_b32_e64 v161, 24, 20, vcc
	s_mul_i32 s43, s42, 0xffffffef
	s_sub_i32 s44, 0, s39
	v_lshlrev_b64 v[162:163], v161, v[162:163]
	v_or_b32_e32 v161, 16, v157
	s_cmp_lg_u32 s43, s44
	v_mul_hi_i32 v178, v161, s51
	s_cselect_b32 s42, s42, 8
	v_readlane_b32 s43, v254, 59
	v_lshrrev_b32_e32 v179, 31, v178
	v_ashrrev_i32_e32 v178, 11, v178
	s_add_i32 s42, s42, s43
	v_readlane_b32 s39, v254, 42
	v_add_u32_e32 v178, v178, v179
	s_mul_i32 s42, s42, 6
	v_mov_b32_e32 v156, s93
	v_mov_b32_e32 v158, s83
	v_mov_b32_e32 v159, s92
	v_mov_b32_e32 v160, s39
	v_mad_i32_i24 v161, v178, s80, v161
	s_ashr_i32 s43, s42, 31
	v_cndmask_b32_e32 v165, v156, v158, vcc
	v_cndmask_b32_e32 v164, v159, v160, vcc
	v_cmp_gt_i32_e32 vcc, s50, v161
	v_lshl_or_b32 v128, s49, 8, v154
	s_lshl_b64 s[42:43], s[42:43], 12
	v_readlane_b32 s44, v253, 29
	v_ashrrev_i32_e32 v179, 31, v178
	v_cndmask_b32_e64 v180, 24, 20, vcc
	v_ashrrev_i32_e32 v182, 31, v161
	v_add_u32_e32 v184, 0xffffff00, v161
	s_add_u32 s42, s44, s42
	v_readlane_b32 s44, v253, 30
	v_ashrrev_i32_e32 v129, 31, v128
	v_lshlrev_b64 v[178:179], v180, v[178:179]
	v_cndmask_b32_e32 v181, v156, v158, vcc
	v_cndmask_b32_e32 v180, v159, v160, vcc
	v_cndmask_b32_e32 v183, 0, v182, vcc
	v_cndmask_b32_e32 v182, v184, v161, vcc
	s_addc_u32 s43, s44, s43
	v_lshlrev_b64 v[150:151], 2, v[128:129]
	v_lshl_add_u64 v[162:163], v[164:165], 0, v[162:163]
	v_lshlrev_b64 v[164:165], 12, v[166:167]
	v_lshl_add_u64 v[178:179], v[180:181], 0, v[178:179]
	v_lshlrev_b64 v[180:181], 12, v[182:183]
	v_lshl_add_u64 v[128:129], s[42:43], 0, v[150:151]
	v_lshl_add_u64 v[162:163], v[162:163], 0, v[164:165]
	v_lshl_add_u64 v[178:179], v[178:179], 0, v[180:181]
	global_load_dwordx4 v[140:143], v[128:129], off
	global_load_dwordx4 v[136:139], v[128:129], off offset:64
	global_load_dwordx4 v[132:135], v[128:129], off offset:512
	s_nop 0
	global_load_dwordx4 v[128:131], v[128:129], off offset:576
	v_lshl_add_u64 v[190:191], v[162:163], 0, v[150:151]
	v_lshl_add_u64 v[194:195], v[178:179], 0, v[150:151]
	global_load_dwordx4 v[162:165], v[190:191], off
	global_load_dwordx4 v[166:169], v[190:191], off offset:64
	global_load_dwordx4 v[170:173], v[190:191], off offset:512
	global_load_dwordx4 v[174:177], v[190:191], off offset:576
	global_load_dwordx4 v[178:181], v[194:195], off
	global_load_dwordx4 v[182:185], v[194:195], off offset:64
	global_load_dwordx4 v[186:189], v[194:195], off offset:512
	global_load_dwordx4 v[210:213], v[194:195], off offset:576
	v_add_u32_e32 v161, 0x80, v157
	v_readlane_b32 s46, v254, 46
	s_mov_b32 s49, s4
	s_mov_b32 s39, s5
	s_mov_b64 s[44:45], s[40:41]
	s_mov_b64 s[42:43], s[0:1]
	v_readlane_b32 s47, v254, 47
	s_waitcnt vmcnt(0)
; #define MEMBAR() asm volatile("" ::: "memory")
;   DI void operator()(const acc_t& acc, const Unit& u, int wr, int wc, int fr, int fq) const {
;     ...
;     for (int q = 0; q < 4; ++q) {
;       const int ai = q >> 1, mh = q & 1;
;       MEMBAR();
;       f32x4 xv[2][2][2];
; #pragma unroll
;       for (int mm = 0; mm < 2; ++mm) { const int t = row0 + ai * HALF + (2 * mh + mm) * 16;
;         const float* xi = from_input ? xrow_in(p, t) : xrow_ws(p, t);
; #pragma unroll
;         for (int bj = 0; bj < 2; ++bj)
; #pragma unroll
;           for (int n = 0; n < 2; ++n) xv[mm][bj][n] = *(const f32x4*)(xi + col0 + bj * HALF + n * 16); }
;       MEMBAR();
; #pragma unroll
;       for (int mm = 0; mm < 2; ++mm) { const int t = row0 + ai * HALF + (2 * mh + mm) * 16;
;         float* xo = xrow_ws(p, t);
; #pragma unroll
;         for (int bj = 0; bj < 2; ++bj)
; #pragma unroll
;           for (int n = 0; n < 2; ++n) *(f32x4*)(xo + col0 + bj * HALF + n * 16) = xv[mm][bj][n] + gv[bj][n] * acc[ai][bj][2 * mh + mm][n]; }
	v_pk_fma_f32 v[126:127], v[126:127], v[142:143], v[164:165]
	v_pk_fma_f32 v[124:125], v[124:125], v[140:141], v[162:163]
	v_pk_fma_f32 v[122:123], v[122:123], v[138:139], v[168:169]
	v_pk_fma_f32 v[120:121], v[120:121], v[136:137], v[166:167]
	v_pk_fma_f32 v[98:99], v[98:99], v[130:131], v[212:213]
	v_pk_fma_f32 v[96:97], v[96:97], v[128:129], v[210:211]
	v_pk_fma_f32 v[114:115], v[114:115], v[134:135], v[172:173]
	v_pk_fma_f32 v[112:113], v[112:113], v[132:133], v[170:171]
	v_pk_fma_f32 v[106:107], v[106:107], v[130:131], v[176:177]
	v_pk_fma_f32 v[104:105], v[104:105], v[128:129], v[174:175]
	v_pk_fma_f32 v[118:119], v[118:119], v[142:143], v[180:181]
	v_pk_fma_f32 v[116:117], v[116:117], v[140:141], v[178:179]
	v_pk_fma_f32 v[110:111], v[110:111], v[138:139], v[184:185]
	v_pk_fma_f32 v[108:109], v[108:109], v[136:137], v[182:183]
	v_pk_fma_f32 v[102:103], v[102:103], v[134:135], v[188:189]
	v_pk_fma_f32 v[100:101], v[100:101], v[132:133], v[186:187]
	global_store_dwordx4 v[190:191], v[124:127], off
	global_store_dwordx4 v[190:191], v[120:123], off offset:64
	global_store_dwordx4 v[190:191], v[112:115], off offset:512
	global_store_dwordx4 v[190:191], v[104:107], off offset:576
	global_store_dwordx4 v[194:195], v[116:119], off
	global_store_dwordx4 v[194:195], v[108:111], off offset:64
	global_store_dwordx4 v[194:195], v[100:103], off offset:512
	global_store_dwordx4 v[194:195], v[96:99], off offset:576
	v_or_b32_e32 v113, 48, v157
	v_mul_hi_i32 v112, v113, s51
	v_or_b32_e32 v97, 32, v157
	v_mul_hi_i32 v96, v97, s51
	v_lshrrev_b32_e32 v98, 31, v96
	v_ashrrev_i32_e32 v96, 11, v96
	v_add_u32_e32 v96, v96, v98
	v_lshrrev_b32_e32 v114, 31, v112
	v_ashrrev_i32_e32 v112, 11, v112
	v_mad_i32_i24 v100, v96, s80, v97
	v_add_u32_e32 v112, v112, v114
	v_ashrrev_i32_e32 v101, 31, v100
	v_add_u32_e32 v102, 0xffffff00, v100
	v_cmp_gt_i32_e32 vcc, s50, v100
	v_mad_i32_i24 v116, v112, s80, v113
	v_ashrrev_i32_e32 v97, 31, v96
	v_cndmask_b32_e32 v99, v156, v158, vcc
	v_cndmask_b32_e32 v98, v159, v160, vcc
	v_cndmask_b32_e32 v101, 0, v101, vcc
	v_cndmask_b32_e32 v100, v102, v100, vcc
	v_cndmask_b32_e64 v102, 24, 20, vcc
	v_cmp_gt_i32_e32 vcc, s50, v116
	v_ashrrev_i32_e32 v113, 31, v112
	v_ashrrev_i32_e32 v117, 31, v116
	v_cndmask_b32_e64 v114, 24, 20, vcc
	v_add_u32_e32 v118, 0xffffff00, v116
	v_lshlrev_b64 v[96:97], v102, v[96:97]
	v_lshlrev_b64 v[112:113], v114, v[112:113]
	v_cndmask_b32_e32 v115, v156, v158, vcc
	v_cndmask_b32_e32 v114, v159, v160, vcc
	v_cndmask_b32_e32 v117, 0, v117, vcc
	v_cndmask_b32_e32 v116, v118, v116, vcc
	v_lshl_add_u64 v[96:97], v[98:99], 0, v[96:97]
	v_lshlrev_b64 v[98:99], 12, v[100:101]
	v_lshl_add_u64 v[112:113], v[114:115], 0, v[112:113]
	v_lshlrev_b64 v[114:115], 12, v[116:117]
	v_lshl_add_u64 v[96:97], v[96:97], 0, v[98:99]
	v_lshl_add_u64 v[112:113], v[112:113], 0, v[114:115]
	v_lshl_add_u64 v[162:163], v[96:97], 0, v[150:151]
	v_lshl_add_u64 v[164:165], v[112:113], 0, v[150:151]
	global_load_dwordx4 v[96:99], v[162:163], off
	global_load_dwordx4 v[100:103], v[162:163], off offset:64
	global_load_dwordx4 v[104:107], v[162:163], off offset:512
	global_load_dwordx4 v[108:111], v[162:163], off offset:576
	global_load_dwordx4 v[112:115], v[164:165], off
	global_load_dwordx4 v[116:119], v[164:165], off offset:64
	global_load_dwordx4 v[120:123], v[164:165], off offset:512
	global_load_dwordx4 v[124:127], v[164:165], off offset:576
	v_mul_hi_i32 v166, v161, s51
	v_lshrrev_b32_e32 v167, 31, v166
	v_ashrrev_i32_e32 v166, 11, v166
	v_add_u32_e32 v166, v166, v167
	v_ashrrev_i32_e32 v167, 31, v166
	s_waitcnt vmcnt(0)
	v_pk_fma_f32 v[94:95], v[94:95], v[142:143], v[98:99]
	v_pk_fma_f32 v[92:93], v[92:93], v[140:141], v[96:97]
	v_pk_fma_f32 v[80:81], v[80:81], v[136:137], v[116:117]
	v_pk_fma_f32 v[90:91], v[90:91], v[138:139], v[102:103]
	v_pk_fma_f32 v[88:89], v[88:89], v[136:137], v[100:101]
	v_pk_fma_f32 v[78:79], v[78:79], v[134:135], v[106:107]
	v_pk_fma_f32 v[76:77], v[76:77], v[132:133], v[104:105]
	v_pk_fma_f32 v[74:75], v[74:75], v[130:131], v[110:111]
	v_pk_fma_f32 v[72:73], v[72:73], v[128:129], v[108:109]
	v_pk_fma_f32 v[86:87], v[86:87], v[142:143], v[114:115]
	v_pk_fma_f32 v[84:85], v[84:85], v[140:141], v[112:113]
	v_pk_fma_f32 v[82:83], v[82:83], v[138:139], v[118:119]
	v_pk_fma_f32 v[70:71], v[70:71], v[134:135], v[122:123]
	v_pk_fma_f32 v[68:69], v[68:69], v[132:133], v[120:121]
	v_pk_fma_f32 v[66:67], v[66:67], v[130:131], v[126:127]
	v_pk_fma_f32 v[64:65], v[64:65], v[128:129], v[124:125]
	global_store_dwordx4 v[162:163], v[92:95], off
	global_store_dwordx4 v[162:163], v[88:91], off offset:64
	global_store_dwordx4 v[162:163], v[76:79], off offset:512
	global_store_dwordx4 v[162:163], v[72:75], off offset:576
	global_store_dwordx4 v[164:165], v[84:87], off
	global_store_dwordx4 v[164:165], v[80:83], off offset:64
	global_store_dwordx4 v[164:165], v[68:71], off offset:512
	global_store_dwordx4 v[164:165], v[64:67], off offset:576
	v_add_u32_e32 v81, 0x90, v157
	v_mul_hi_i32 v80, v81, s51
	v_lshrrev_b32_e32 v82, 31, v80
	v_ashrrev_i32_e32 v80, 11, v80
	v_mad_i32_i24 v66, v166, s80, v161
	v_add_u32_e32 v80, v80, v82
	v_ashrrev_i32_e32 v67, 31, v66
	v_add_u32_e32 v68, 0xffffff00, v66
	v_cmp_gt_i32_e32 vcc, s50, v66
	v_mad_i32_i24 v84, v80, s80, v81
	v_ashrrev_i32_e32 v81, 31, v80
	v_cndmask_b32_e32 v65, v156, v158, vcc
	v_cndmask_b32_e32 v64, v159, v160, vcc
	v_cndmask_b32_e32 v67, 0, v67, vcc
	v_cndmask_b32_e32 v66, v68, v66, vcc
	v_cndmask_b32_e64 v68, 24, 20, vcc
	v_cmp_gt_i32_e32 vcc, s50, v84
	v_ashrrev_i32_e32 v85, 31, v84
	v_add_u32_e32 v86, 0xffffff00, v84
	v_cndmask_b32_e64 v82, 24, 20, vcc
	v_lshlrev_b64 v[68:69], v68, v[166:167]
	v_lshlrev_b64 v[80:81], v82, v[80:81]
	v_cndmask_b32_e32 v83, v156, v158, vcc
	v_cndmask_b32_e32 v82, v159, v160, vcc
	v_cndmask_b32_e32 v85, 0, v85, vcc
	v_cndmask_b32_e32 v84, v86, v84, vcc
	v_lshl_add_u64 v[64:65], v[64:65], 0, v[68:69]
	v_lshlrev_b64 v[66:67], 12, v[66:67]
	v_lshl_add_u64 v[80:81], v[82:83], 0, v[80:81]
	v_lshlrev_b64 v[82:83], 12, v[84:85]
	v_lshl_add_u64 v[64:65], v[64:65], 0, v[66:67]
	v_lshl_add_u64 v[80:81], v[80:81], 0, v[82:83]
	v_lshl_add_u64 v[96:97], v[64:65], 0, v[150:151]
	v_lshl_add_u64 v[98:99], v[80:81], 0, v[150:151]
	global_load_dwordx4 v[64:67], v[96:97], off
	global_load_dwordx4 v[68:71], v[96:97], off offset:64
	global_load_dwordx4 v[72:75], v[96:97], off offset:512
	global_load_dwordx4 v[76:79], v[96:97], off offset:576
	global_load_dwordx4 v[80:83], v[98:99], off
	global_load_dwordx4 v[84:87], v[98:99], off offset:64
	global_load_dwordx4 v[88:91], v[98:99], off offset:512
	global_load_dwordx4 v[92:95], v[98:99], off offset:576
	v_add_u32_e32 v101, 0xa0, v157
	v_mul_hi_i32 v100, v101, s51
	v_lshrrev_b32_e32 v102, 31, v100
	v_ashrrev_i32_e32 v100, 11, v100
	v_add_u32_e32 v100, v100, v102
	v_mad_i32_i24 v104, v100, s80, v101
	v_ashrrev_i32_e32 v105, 31, v104
	v_add_u32_e32 v106, 0xffffff00, v104
	v_cmp_gt_i32_e32 vcc, s50, v104
	v_ashrrev_i32_e32 v101, 31, v100
	s_waitcnt vmcnt(0)
; #define MEMBAR() asm volatile("" ::: "memory")
;   DI void operator()(const acc_t& acc, const Unit& u, int wr, int wc, int fr, int fq) const {
;     ...
;     for (int q = 0; q < 4; ++q) {
;       const int ai = q >> 1, mh = q & 1;
;       MEMBAR();
;       f32x4 xv[2][2][2];
; #pragma unroll
;       for (int mm = 0; mm < 2; ++mm) { const int t = row0 + ai * HALF + (2 * mh + mm) * 16;
;         const float* xi = from_input ? xrow_in(p, t) : xrow_ws(p, t);
; #pragma unroll
;         for (int bj = 0; bj < 2; ++bj)
; #pragma unroll
;           for (int n = 0; n < 2; ++n) xv[mm][bj][n] = *(const f32x4*)(xi + col0 + bj * HALF + n * 16); }
;       MEMBAR();
; #pragma unroll
;       for (int mm = 0; mm < 2; ++mm) { const int t = row0 + ai * HALF + (2 * mh + mm) * 16;
;         float* xo = xrow_ws(p, t);
; #pragma unroll
;         for (int bj = 0; bj < 2; ++bj)
; #pragma unroll
;           for (int n = 0; n < 2; ++n) *(f32x4*)(xo + col0 + bj * HALF + n * 16) = xv[mm][bj][n] + gv[bj][n] * acc[ai][bj][2 * mh + mm][n]; }
	v_pk_fma_f32 v[62:63], v[62:63], v[142:143], v[66:67]
	v_pk_fma_f32 v[60:61], v[60:61], v[140:141], v[64:65]
	v_pk_fma_f32 v[48:49], v[48:49], v[136:137], v[84:85]
	v_pk_fma_f32 v[58:59], v[58:59], v[138:139], v[70:71]
	v_pk_fma_f32 v[56:57], v[56:57], v[136:137], v[68:69]
	v_pk_fma_f32 v[46:47], v[46:47], v[134:135], v[74:75]
	v_pk_fma_f32 v[44:45], v[44:45], v[132:133], v[72:73]
	v_pk_fma_f32 v[42:43], v[42:43], v[130:131], v[78:79]
	v_pk_fma_f32 v[40:41], v[40:41], v[128:129], v[76:77]
	v_pk_fma_f32 v[54:55], v[54:55], v[142:143], v[82:83]
	v_pk_fma_f32 v[52:53], v[52:53], v[140:141], v[80:81]
	v_pk_fma_f32 v[50:51], v[50:51], v[138:139], v[86:87]
	v_pk_fma_f32 v[38:39], v[38:39], v[134:135], v[90:91]
	v_pk_fma_f32 v[36:37], v[36:37], v[132:133], v[88:89]
	v_pk_fma_f32 v[34:35], v[34:35], v[130:131], v[94:95]
	v_pk_fma_f32 v[32:33], v[32:33], v[128:129], v[92:93]
	global_store_dwordx4 v[96:97], v[60:63], off
	global_store_dwordx4 v[96:97], v[56:59], off offset:64
	global_store_dwordx4 v[96:97], v[44:47], off offset:512
	global_store_dwordx4 v[96:97], v[40:43], off offset:576
	global_store_dwordx4 v[98:99], v[52:55], off
	global_store_dwordx4 v[98:99], v[48:51], off offset:64
	global_store_dwordx4 v[98:99], v[36:39], off offset:512
	global_store_dwordx4 v[98:99], v[32:35], off offset:576
	v_add_u32_e32 v49, 0xb0, v157
	v_mul_hi_i32 v48, v49, s51
	v_lshrrev_b32_e32 v50, 31, v48
	v_ashrrev_i32_e32 v48, 11, v48
	v_add_u32_e32 v48, v48, v50
	v_mad_i32_i24 v52, v48, s80, v49
	v_cndmask_b32_e32 v103, v156, v158, vcc
	v_cndmask_b32_e32 v102, v159, v160, vcc
	v_cndmask_b32_e32 v105, 0, v105, vcc
	v_cndmask_b32_e32 v104, v106, v104, vcc
	v_cndmask_b32_e64 v32, 24, 20, vcc
	v_cmp_gt_i32_e32 vcc, s50, v52
	v_ashrrev_i32_e32 v49, 31, v48
	v_ashrrev_i32_e32 v53, 31, v52
	v_cndmask_b32_e64 v50, 24, 20, vcc
	v_add_u32_e32 v54, 0xffffff00, v52
	v_lshlrev_b64 v[32:33], v32, v[100:101]
	v_lshlrev_b64 v[48:49], v50, v[48:49]
	v_cndmask_b32_e32 v51, v156, v158, vcc
	v_cndmask_b32_e32 v50, v159, v160, vcc
	v_cndmask_b32_e32 v53, 0, v53, vcc
	v_cndmask_b32_e32 v52, v54, v52, vcc
	v_lshl_add_u64 v[32:33], v[102:103], 0, v[32:33]
	v_lshlrev_b64 v[34:35], 12, v[104:105]
	v_lshl_add_u64 v[48:49], v[50:51], 0, v[48:49]
	v_lshlrev_b64 v[50:51], 12, v[52:53]
	v_lshl_add_u64 v[32:33], v[32:33], 0, v[34:35]
	v_lshl_add_u64 v[48:49], v[48:49], 0, v[50:51]
	v_lshl_add_u64 v[64:65], v[32:33], 0, v[150:151]
	v_lshl_add_u64 v[66:67], v[48:49], 0, v[150:151]
	global_load_dwordx4 v[32:35], v[64:65], off
	global_load_dwordx4 v[36:39], v[64:65], off offset:64
	global_load_dwordx4 v[40:43], v[64:65], off offset:512
	global_load_dwordx4 v[44:47], v[64:65], off offset:576
	global_load_dwordx4 v[48:51], v[66:67], off
	global_load_dwordx4 v[52:55], v[66:67], off offset:64
	global_load_dwordx4 v[56:59], v[66:67], off offset:512
	global_load_dwordx4 v[60:63], v[66:67], off offset:576
	s_and_b64 vcc, exec, s[36:37]
	s_waitcnt vmcnt(0)
	v_pk_fma_f32 v[30:31], v[30:31], v[142:143], v[34:35]
	v_pk_fma_f32 v[28:29], v[28:29], v[140:141], v[32:33]
	v_pk_fma_f32 v[26:27], v[26:27], v[138:139], v[38:39]
	v_pk_fma_f32 v[24:25], v[24:25], v[136:137], v[36:37]
	v_pk_fma_f32 v[14:15], v[14:15], v[134:135], v[42:43]
	v_pk_fma_f32 v[12:13], v[12:13], v[132:133], v[40:41]
	v_pk_fma_f32 v[10:11], v[10:11], v[130:131], v[46:47]
	v_pk_fma_f32 v[8:9], v[8:9], v[128:129], v[44:45]
	v_pk_fma_f32 v[22:23], v[22:23], v[142:143], v[50:51]
	v_pk_fma_f32 v[20:21], v[20:21], v[140:141], v[48:49]
	v_pk_fma_f32 v[18:19], v[18:19], v[138:139], v[54:55]
	v_pk_fma_f32 v[16:17], v[16:17], v[136:137], v[52:53]
	v_pk_fma_f32 v[6:7], v[6:7], v[134:135], v[58:59]
	v_pk_fma_f32 v[4:5], v[4:5], v[132:133], v[56:57]
	v_pk_fma_f32 v[2:3], v[2:3], v[130:131], v[62:63]
	v_pk_fma_f32 v[0:1], v[0:1], v[128:129], v[60:61]
	global_store_dwordx4 v[64:65], v[28:31], off
	global_store_dwordx4 v[64:65], v[24:27], off offset:64
	global_store_dwordx4 v[64:65], v[12:15], off offset:512
	global_store_dwordx4 v[64:65], v[8:11], off offset:576
	global_store_dwordx4 v[66:67], v[20:23], off
	global_store_dwordx4 v[66:67], v[16:19], off offset:64
	global_store_dwordx4 v[66:67], v[4:7], off offset:512
	global_store_dwordx4 v[66:67], v[0:3], off offset:576
	s_cbranch_vccz .LBB0_1921
	s_waitcnt vmcnt(0)
	s_cmpk_gt_u32 s3, 0xff
	s_cbranch_scc1 .LBB0_1933
	s_barrier
